# L-build loop of gdn_prep hand-rewritten (prefetched LDS reads, select instead of exec-masked branches); L1 invalidate moved to barrier arrival; FFT radix-2 reads hoisted past non-aliasing writes
# speedup vs baseline: 1.0324x; 1.0074x over previous
.LBB0_65:
	s_mov_b64 s[6:7], exec
	v_readlane_b32 s2, v239, 2
	s_lshl_b32 s2, s2, 8
	v_mbcnt_lo_u32_b32 v1, s6, 0
	s_add_u32 s4, s96, s2
	v_mbcnt_hi_u32_b32 v1, s7, v1
	s_addc_u32 s5, s97, 0
	v_cmp_eq_u32_e32 vcc, 0, v1
	s_and_saveexec_b64 s[8:9], vcc
	s_cbranch_execz .LBB0_67
	s_bcnt1_i32_b64 s2, s[6:7]
	v_mov_b32_e32 v3, 0x1000
	v_mov_b32_e32 v4, s2
	buffer_inv sc1
	global_atomic_add v3, v3, v4, s[4:5] offset:1024 sc0

.LBB0_80:
	s_or_b64 exec, exec, s[8:9]
	s_waitcnt vmcnt(0)
	s_waitcnt vmcnt(0)

.LBB0_98:
	s_or_b64 exec, exec, s[6:7]
	s_mov_b64 s[6:7], exec
	v_mbcnt_lo_u32_b32 v0, s6, 0
	v_mbcnt_hi_u32_b32 v0, s7, v0
	v_cmp_eq_u32_e32 vcc, 0, v0
	s_waitcnt vmcnt(0)
	s_and_saveexec_b64 s[8:9], vcc
	s_cbranch_execz .LBB0_100
	s_bcnt1_i32_b64 s2, s[6:7]
	v_mov_b32_e32 v0, 0x2000
	v_mov_b32_e32 v1, s2
	global_atomic_add v0, v1, s[4:5] offset:1024

.LBB0_313:
	s_mov_b64 s[8:9], exec
	v_readlane_b32 s1, v239, 2
	s_lshl_b32 s1, s1, 8
	v_mbcnt_lo_u32_b32 v1, s8, 0
	s_add_u32 s6, s96, s1
	v_mbcnt_hi_u32_b32 v1, s9, v1
	s_addc_u32 s7, s97, 0
	v_cmp_eq_u32_e32 vcc, 0, v1
	s_and_saveexec_b64 s[10:11], vcc
	s_cbranch_execz .LBB0_315
	s_bcnt1_i32_b64 s1, s[8:9]
	v_mov_b32_e32 v3, 0x1000
	v_mov_b32_e32 v4, s1
	buffer_inv sc1
	global_atomic_add v3, v3, v4, s[6:7] offset:1024 sc0

.LBB0_328:
	s_or_b64 exec, exec, s[10:11]
	s_waitcnt vmcnt(0)
	s_waitcnt vmcnt(0)

.LBB0_346:
	s_or_b64 exec, exec, s[8:9]
	s_mov_b64 s[8:9], exec
	v_mbcnt_lo_u32_b32 v0, s8, 0
	v_mbcnt_hi_u32_b32 v0, s9, v0
	v_cmp_eq_u32_e32 vcc, 0, v0
	s_waitcnt vmcnt(0)
	s_and_saveexec_b64 s[10:11], vcc
	s_cbranch_execz .LBB0_348
	s_bcnt1_i32_b64 s1, s[8:9]
	v_mov_b32_e32 v0, 0x2000
	v_mov_b32_e32 v1, s1
	global_atomic_add v0, v1, s[6:7] offset:1024

.LBB0_563:
	s_mov_b64 s[10:11], exec
	v_readlane_b32 s1, v239, 2
	s_lshl_b32 s1, s1, 8
	v_mbcnt_lo_u32_b32 v1, s10, 0
	s_add_u32 s8, s96, s1
	v_mbcnt_hi_u32_b32 v1, s11, v1
	s_addc_u32 s9, s97, 0
	v_cmp_eq_u32_e32 vcc, 0, v1
	s_and_saveexec_b64 s[12:13], vcc
	s_cbranch_execz .LBB0_565
	s_bcnt1_i32_b64 s1, s[10:11]
	v_mov_b32_e32 v3, 0x1000
	v_mov_b32_e32 v4, s1
	buffer_inv sc1
	global_atomic_add v3, v3, v4, s[8:9] offset:1024 sc0

.LBB0_578:
	s_or_b64 exec, exec, s[12:13]
	s_waitcnt vmcnt(0)
	s_waitcnt vmcnt(0)

.LBB0_596:
	s_or_b64 exec, exec, s[10:11]
	s_mov_b64 s[10:11], exec
	v_mbcnt_lo_u32_b32 v0, s10, 0
	v_mbcnt_hi_u32_b32 v0, s11, v0
	v_cmp_eq_u32_e32 vcc, 0, v0
	s_waitcnt vmcnt(0)
	s_and_saveexec_b64 s[12:13], vcc
	s_cbranch_execz .LBB0_598
	s_bcnt1_i32_b64 s1, s[10:11]
	v_mov_b32_e32 v0, 0x2000
	v_mov_b32_e32 v1, s1
	global_atomic_add v0, v1, s[8:9] offset:1024

.LBB0_1560:
	v_and_b32_e32 v1, 0x7fffffff, v1
	v_and_b32_e32 v2, 0x7fffffff, v31
	v_and_b32_e32 v3, 0x7fffffff, v3
	v_add_f32_e32 v1, v1, v2
	v_and_b32_e32 v4, 0x7fffffff, v19
	v_add_f32_e32 v1, v3, v1
	v_and_b32_e32 v5, 0x7fffffff, v5
	v_add_f32_e32 v1, v4, v1
	v_and_b32_e32 v6, 0x7fffffff, v17
	v_add_f32_e32 v1, v5, v1
	v_and_b32_e32 v7, 0x7fffffff, v7
	v_add_f32_e32 v1, v6, v1
	v_and_b32_e32 v8, 0x7fffffff, v21
	v_add_f32_e32 v1, v7, v1
	v_and_b32_e32 v9, 0x7fffffff, v9
	v_add_f32_e32 v1, v8, v1
	v_and_b32_e32 v10, 0x7fffffff, v23
	v_add_f32_e32 v1, v9, v1
	v_and_b32_e32 v11, 0x7fffffff, v11
	v_add_f32_e32 v1, v10, v1
	v_and_b32_e32 v12, 0x7fffffff, v25
	v_add_f32_e32 v1, v11, v1
	v_and_b32_e32 v13, 0x7fffffff, v13
	v_add_f32_e32 v1, v12, v1
	v_and_b32_e32 v14, 0x7fffffff, v29
	v_add_f32_e32 v1, v13, v1
	v_mbcnt_lo_u32_b32 v2, -1, 0
	v_mbcnt_hi_u32_b32 v2, -1, v2
	v_and_b32_e32 v15, 0x7fffffff, v15
	v_add_f32_e32 v1, v14, v1
	v_and_b32_e32 v16, 0x7fffffff, v27
	v_add_f32_e32 v1, v15, v1
	v_lshlrev_b32_e32 v2, 2, v2
	v_add_f32_e32 v1, v16, v1
	v_xor_b32_e32 v3, 0x80, v2
	ds_bpermute_b32 v3, v3, v1
	v_xor_b32_e32 v4, 32, v2
	s_ashr_i32 s41, s40, 31
	s_waitcnt lgkmcnt(0)
	s_barrier
	v_add_f32_e32 v1, v1, v3
	v_xor_b32_e32 v3, 64, v2
	ds_bpermute_b32 v3, v3, v1
	s_waitcnt lgkmcnt(0)
	v_add_f32_e32 v1, v1, v3
	ds_bpermute_b32 v173, v4, v1
	v_xor_b32_e32 v4, 16, v2
	s_waitcnt lgkmcnt(0)
	v_add_f32_e32 v1, v1, v173
	ds_bpermute_b32 v172, v4, v1
	v_xor_b32_e32 v4, 8, v2
	v_xor_b32_e32 v2, 4, v2
	s_waitcnt lgkmcnt(0)
	v_add_f32_e32 v1, v1, v172
	ds_bpermute_b32 v3, v4, v1
	s_waitcnt lgkmcnt(0)
	v_add_f32_e32 v1, v1, v3
	ds_bpermute_b32 v2, v2, v1
	s_and_saveexec_b64 s[8:9], vcc
	s_cbranch_execz .LBB0_1562
	s_waitcnt lgkmcnt(0)
	v_add_f32_e32 v1, v1, v2
	ds_write_b32 v0, v1

.LBB0_1575:
	s_or_b64 exec, exec, s[8:9]
	s_waitcnt lgkmcnt(0)
	s_barrier
	s_and_saveexec_b64 s[8:9], vcc
	s_cbranch_execz .LBB0_1577
	ds_read_b64 v[202:203], v23 offset:61440
	ds_read_b64 v[174:175], v63 offset:57344
	ds_read_b64 v[176:177], v102 offset:53248
	ds_read_b64 v[178:179], v105 offset:49152
	ds_read_b64 v[180:181], v108 offset:45056
	ds_read_b64 v[182:183], v111 offset:40960
	ds_read_b64 v[184:185], v117
	ds_read_b64 v[186:187], v109 offset:4096
	ds_read_b64 v[188:189], v106 offset:8192
	ds_read_b64 v[190:191], v103 offset:12288
	ds_read_b64 v[192:193], v65 offset:16384
	ds_read_b64 v[194:195], v27 offset:20480
	ds_read_b64 v[196:197], v15 offset:24576
	ds_read_b64 v[198:199], v11 offset:28672
	ds_read_b64 v[200:201], v116 offset:32768
	s_waitcnt lgkmcnt(14)
	ds_read_b64 v[172:173], v113 offset:36864
	v_and_b32_e32 v68, 15, v114
	v_cvt_f32_ubyte0_e32 v68, v68
	v_mul_f32_e32 v68, 0x3b800000, v68
	v_cos_f32_e32 v84, v68
	v_sin_f32_e32 v92, v68
	s_mov_b32 s29, s26
	v_mov_b32_e32 v93, v84
	v_xor_b32_e32 v85, 0x80000000, v92
	v_pk_mul_f32 v[68:69], v[92:93], v[92:93] op_sel_hi:[1,0] neg_lo:[0,1] neg_hi:[0,1]
	s_mov_b32 s10, s26
	v_pk_fma_f32 v[90:91], v[84:85], v[84:85], v[68:69] op_sel_hi:[1,0,1]
	s_mov_b32 s11, s28
	v_pk_mul_f32 v[68:69], v[92:93], v[90:91] op_sel:[0,1]
	s_mov_b32 s37, s20
	v_pk_fma_f32 v[86:87], v[84:85], v[90:91], v[68:69] op_sel_hi:[1,0,1]
	s_mov_b32 s12, s27
	v_pk_mul_f32 v[68:69], v[92:93], v[86:87] op_sel:[0,1]
	s_mov_b32 s13, s34
	v_pk_fma_f32 v[82:83], v[84:85], v[86:87], v[68:69] op_sel_hi:[1,0,1]
	s_mov_b32 s35, s28
	v_pk_mul_f32 v[68:69], v[92:93], v[82:83] op_sel:[0,1]
	s_nop 0
	v_pk_fma_f32 v[80:81], v[84:85], v[82:83], v[68:69] op_sel_hi:[1,0,1]
	s_nop 0
	v_pk_mul_f32 v[68:69], v[92:93], v[80:81] op_sel:[0,1]
	s_nop 0
	v_pk_fma_f32 v[78:79], v[84:85], v[80:81], v[68:69] op_sel_hi:[1,0,1]
	s_nop 0
	v_pk_mul_f32 v[68:69], v[92:93], v[78:79] op_sel:[0,1]
	s_nop 0
	v_pk_fma_f32 v[76:77], v[84:85], v[78:79], v[68:69] op_sel_hi:[1,0,1]
	s_nop 0
	v_pk_mul_f32 v[68:69], v[92:93], v[76:77] op_sel:[0,1]
	s_nop 0
	v_pk_fma_f32 v[70:71], v[84:85], v[76:77], v[68:69] op_sel_hi:[1,0,1]
	s_nop 0
	v_pk_mul_f32 v[68:69], v[92:93], v[70:71] op_sel:[0,1]
	s_nop 0
	v_pk_fma_f32 v[68:69], v[84:85], v[70:71], v[68:69] op_sel_hi:[1,0,1]
	s_nop 0
	v_pk_mul_f32 v[72:73], v[92:93], v[68:69] op_sel:[0,1]
	s_nop 0
	v_pk_fma_f32 v[96:97], v[84:85], v[68:69], v[72:73] op_sel_hi:[1,0,1]
	s_nop 0
	v_pk_mul_f32 v[72:73], v[92:93], v[96:97] op_sel:[0,1]
	s_nop 0
	v_pk_fma_f32 v[94:95], v[84:85], v[96:97], v[72:73] op_sel_hi:[1,0,1]
	s_nop 0
	v_pk_mul_f32 v[72:73], v[92:93], v[94:95] op_sel:[0,1]
	s_nop 0
	v_pk_fma_f32 v[98:99], v[84:85], v[94:95], v[72:73] op_sel_hi:[1,0,1]
	s_nop 0
	v_pk_mul_f32 v[72:73], v[92:93], v[98:99] op_sel:[0,1]
	s_nop 0
	v_pk_fma_f32 v[88:89], v[84:85], v[98:99], v[72:73] op_sel_hi:[1,0,1]
	s_nop 0
	v_pk_mul_f32 v[72:73], v[92:93], v[88:89] op_sel:[0,1]
	s_nop 0
	v_pk_fma_f32 v[74:75], v[84:85], v[88:89], v[72:73] op_sel_hi:[1,0,1]
	s_nop 0
	v_pk_mul_f32 v[72:73], v[92:93], v[74:75] op_sel:[0,1]
	s_nop 0
	v_pk_fma_f32 v[72:73], v[84:85], v[74:75], v[72:73] op_sel_hi:[1,0,1]
	s_nop 0
	v_xor_b32_e32 v122, 0x80000000, v73
	v_mov_b32_e32 v123, v72
	s_waitcnt lgkmcnt(15)
	s_nop 0
	v_pk_mul_f32 v[122:123], v[122:123], v[202:203] op_sel:[0,1]
	s_nop 0
	v_pk_fma_f32 v[72:73], v[72:73], v[202:203], v[122:123] op_sel_hi:[1,0,1]
	v_xor_b32_e32 v122, 0x80000000, v75
	v_mov_b32_e32 v123, v74
	s_waitcnt lgkmcnt(14)
	v_pk_mul_f32 v[122:123], v[122:123], v[174:175] op_sel:[0,1]
	s_nop 0
	v_pk_fma_f32 v[74:75], v[74:75], v[174:175], v[122:123] op_sel_hi:[1,0,1]
	v_xor_b32_e32 v122, 0x80000000, v89
	v_mov_b32_e32 v123, v88
	s_waitcnt lgkmcnt(13)
	v_pk_mul_f32 v[122:123], v[122:123], v[176:177] op_sel:[0,1]
	s_nop 0
	v_pk_fma_f32 v[88:89], v[88:89], v[176:177], v[122:123] op_sel_hi:[1,0,1]
	v_xor_b32_e32 v122, 0x80000000, v99
	v_mov_b32_e32 v123, v98
	s_waitcnt lgkmcnt(12)
	v_pk_mul_f32 v[122:123], v[122:123], v[178:179] op_sel:[0,1]
	s_nop 0
	v_pk_fma_f32 v[98:99], v[98:99], v[178:179], v[122:123] op_sel_hi:[1,0,1]
	v_xor_b32_e32 v122, 0x80000000, v95
	v_mov_b32_e32 v123, v94
	s_waitcnt lgkmcnt(11)
	v_pk_mul_f32 v[122:123], v[122:123], v[180:181] op_sel:[0,1]
	s_nop 0
	v_pk_fma_f32 v[94:95], v[94:95], v[180:181], v[122:123] op_sel_hi:[1,0,1]
	v_xor_b32_e32 v122, 0x80000000, v97
	v_mov_b32_e32 v123, v96
	s_waitcnt lgkmcnt(10)
	v_pk_mul_f32 v[122:123], v[122:123], v[182:183] op_sel:[0,1]
	s_nop 0
	v_pk_fma_f32 v[96:97], v[96:97], v[182:183], v[122:123] op_sel_hi:[1,0,1]
	s_waitcnt lgkmcnt(8)
	v_pk_mul_f32 v[92:93], v[92:93], v[186:187] op_sel:[0,1]
	s_nop 0
	v_pk_fma_f32 v[92:93], v[84:85], v[186:187], v[92:93] op_sel_hi:[1,0,1]
	v_xor_b32_e32 v122, 0x80000000, v91
	v_mov_b32_e32 v123, v90
	s_waitcnt lgkmcnt(7)
	v_pk_mul_f32 v[122:123], v[122:123], v[188:189] op_sel:[0,1]
	s_nop 0
	v_pk_fma_f32 v[90:91], v[90:91], v[188:189], v[122:123] op_sel_hi:[1,0,1]
	v_xor_b32_e32 v122, 0x80000000, v87
	v_mov_b32_e32 v123, v86
	s_waitcnt lgkmcnt(6)
	v_pk_mul_f32 v[122:123], v[122:123], v[190:191] op_sel:[0,1]
	s_nop 0
	v_pk_fma_f32 v[84:85], v[86:87], v[190:191], v[122:123] op_sel_hi:[1,0,1]
	v_xor_b32_e32 v122, 0x80000000, v83
	v_mov_b32_e32 v123, v82
	s_waitcnt lgkmcnt(5)
	v_pk_mul_f32 v[122:123], v[122:123], v[192:193] op_sel:[0,1]
	s_nop 0
	v_pk_fma_f32 v[82:83], v[82:83], v[192:193], v[122:123] op_sel_hi:[1,0,1]
	v_xor_b32_e32 v122, 0x80000000, v81
	v_mov_b32_e32 v123, v80
	s_waitcnt lgkmcnt(4)
	v_pk_mul_f32 v[122:123], v[122:123], v[194:195] op_sel:[0,1]
	s_nop 0
	v_pk_fma_f32 v[80:81], v[80:81], v[194:195], v[122:123] op_sel_hi:[1,0,1]
	v_xor_b32_e32 v122, 0x80000000, v79
	v_mov_b32_e32 v123, v78
	s_waitcnt lgkmcnt(3)
	v_pk_mul_f32 v[122:123], v[122:123], v[196:197] op_sel:[0,1]
	s_nop 0
	v_pk_fma_f32 v[78:79], v[78:79], v[196:197], v[122:123] op_sel_hi:[1,0,1]
	v_xor_b32_e32 v122, 0x80000000, v77
	v_mov_b32_e32 v123, v76
	s_waitcnt lgkmcnt(2)
	v_pk_mul_f32 v[122:123], v[122:123], v[198:199] op_sel:[0,1]
	s_nop 0
	v_pk_fma_f32 v[76:77], v[76:77], v[198:199], v[122:123] op_sel_hi:[1,0,1]
	v_xor_b32_e32 v122, 0x80000000, v71
	v_mov_b32_e32 v123, v70
	s_waitcnt lgkmcnt(1)
	v_pk_mul_f32 v[122:123], v[122:123], v[200:201] op_sel:[0,1]
	s_nop 0
	v_pk_fma_f32 v[70:71], v[70:71], v[200:201], v[122:123] op_sel_hi:[1,0,1]
	v_xor_b32_e32 v122, 0x80000000, v69
	v_mov_b32_e32 v123, v68
	s_waitcnt lgkmcnt(0)
	v_pk_mul_f32 v[122:123], v[122:123], v[172:173] op_sel:[0,1]
	s_nop 0
	v_pk_fma_f32 v[68:69], v[68:69], v[172:173], v[122:123] op_sel_hi:[1,0,1]
	v_pk_add_f32 v[86:87], v[184:185], v[70:71]
	v_pk_add_f32 v[100:101], v[184:185], v[70:71] neg_lo:[0,1] neg_hi:[0,1]
	v_pk_add_f32 v[70:71], v[98:99], v[82:83]
	v_pk_add_f32 v[82:83], v[82:83], v[98:99] neg_lo:[0,1] neg_hi:[0,1]
	v_pk_add_f32 v[98:99], v[70:71], v[86:87]
	v_pk_add_f32 v[86:87], v[86:87], v[70:71] neg_lo:[0,1] neg_hi:[0,1]
	v_pk_add_f32 v[70:71], v[92:93], v[68:69]
	v_pk_add_f32 v[92:93], v[92:93], v[68:69] neg_lo:[0,1] neg_hi:[0,1]
	v_pk_add_f32 v[68:69], v[88:89], v[80:81]
	v_pk_add_f32 v[80:81], v[80:81], v[88:89] neg_lo:[0,1] neg_hi:[0,1]
	v_pk_add_f32 v[88:89], v[68:69], v[70:71]
	v_pk_add_f32 v[124:125], v[70:71], v[68:69] neg_lo:[0,1] neg_hi:[0,1]
	v_pk_add_f32 v[68:69], v[96:97], v[90:91]
	v_pk_add_f32 v[70:71], v[74:75], v[78:79]
	v_pk_add_f32 v[96:97], v[90:91], v[96:97] neg_lo:[0,1] neg_hi:[0,1]
	v_pk_add_f32 v[74:75], v[78:79], v[74:75] neg_lo:[0,1] neg_hi:[0,1]
	v_pk_add_f32 v[78:79], v[68:69], v[70:71]
	v_pk_add_f32 v[90:91], v[68:69], v[70:71] neg_lo:[0,1] neg_hi:[0,1]
	v_pk_add_f32 v[68:69], v[94:95], v[84:85]
	v_pk_add_f32 v[70:71], v[72:73], v[76:77]
	v_xor_b32_e32 v129, 0x80000000, v74
	v_mov_b32_e32 v128, v75
	v_pk_add_f32 v[72:73], v[76:77], v[72:73] neg_lo:[0,1] neg_hi:[0,1]
	v_pk_add_f32 v[74:75], v[68:69], v[70:71]
	v_xor_b32_e32 v127, 0x80000000, v80
	v_mov_b32_e32 v126, v81
	v_pk_add_f32 v[94:95], v[84:85], v[94:95] neg_lo:[0,1] neg_hi:[0,1]
	v_pk_add_f32 v[84:85], v[68:69], v[70:71] neg_lo:[0,1] neg_hi:[0,1]
	v_xor_b32_e32 v133, 0x80000000, v72
	v_mov_b32_e32 v132, v73
	v_pk_add_f32 v[68:69], v[78:79], v[98:99]
	v_pk_add_f32 v[70:71], v[74:75], v[88:89]
	v_pk_add_f32 v[72:73], v[88:89], v[74:75] neg_lo:[0,1] neg_hi:[0,1]
	v_pk_add_f32 v[80:81], v[126:127], v[92:93]
	v_pk_add_f32 v[78:79], v[98:99], v[78:79] neg_lo:[0,1] neg_hi:[0,1]
	v_pk_add_f32 v[74:75], v[68:69], v[70:71]
	v_pk_add_f32 v[70:71], v[68:69], v[70:71] neg_lo:[0,1] neg_hi:[0,1]
	v_xor_b32_e32 v69, 0x80000000, v72
	v_mov_b32_e32 v68, v73
	v_pk_add_f32 v[130:131], v[96:97], v[128:129]
	v_pk_add_f32 v[76:77], v[94:95], v[132:133]
	v_pk_add_f32 v[72:73], v[78:79], v[68:69]
	v_pk_add_f32 v[68:69], v[78:79], v[68:69] neg_lo:[0,1] neg_hi:[0,1]
	v_pk_mul_f32 v[78:79], v[80:81], s[28:29] op_sel:[1,0]
	v_xor_b32_e32 v123, 0x80000000, v82
	v_mov_b32_e32 v122, v83
	v_pk_fma_f32 v[78:79], v[80:81], s[26:27], v[78:79] op_sel_hi:[0,1,1]
	v_mul_f32_e32 v80, 0x3f3504f3, v131
	s_mov_b32 s29, s34
	v_pk_mul_f32 v[88:89], v[76:77], s[10:11] op_sel:[1,0]
	v_pk_add_f32 v[82:83], v[122:123], v[100:101]
	v_pk_fma_f32 v[80:81], v[130:131], s[30:31], v[80:81] op_sel_hi:[0,1,0]
	v_pk_fma_f32 v[76:77], v[76:77], s[28:29], v[88:89] op_sel_hi:[0,1,1]
	v_pk_add_f32 v[88:89], v[82:83], v[80:81]
	v_pk_add_f32 v[98:99], v[82:83], v[80:81] neg_lo:[0,1] neg_hi:[0,1]
	v_pk_add_f32 v[80:81], v[78:79], v[76:77]
	v_pk_add_f32 v[76:77], v[78:79], v[76:77] neg_lo:[0,1] neg_hi:[0,1]
	v_pk_add_f32 v[82:83], v[88:89], v[80:81]
	v_pk_add_f32 v[78:79], v[88:89], v[80:81] neg_lo:[0,1] neg_hi:[0,1]
	v_xor_b32_e32 v89, 0x80000000, v76
	v_mov_b32_e32 v88, v77
	v_pk_add_f32 v[80:81], v[98:99], v[88:89]
	v_pk_add_f32 v[76:77], v[98:99], v[88:89] neg_lo:[0,1] neg_hi:[0,1]
	v_pk_mul_f32 v[98:99], v[90:91], s[36:37] op_sel:[1,0]
	v_mul_f32_e32 v88, 0x3f3504f3, v125
	v_pk_fma_f32 v[90:91], v[90:91], s[20:21], v[98:99] op_sel_hi:[0,1,1]
	v_mul_f32_e32 v98, 0xbf3504f3, v84
	v_pk_fma_f32 v[88:89], v[124:125], s[30:31], v[88:89] op_sel_hi:[0,1,0]
	v_pk_fma_f32 v[84:85], v[84:85], s[30:31], v[98:99] op_sel:[1,0,0] op_sel_hi:[1,1,0]
	v_pk_add_f32 v[98:99], v[86:87], v[90:91]
	v_pk_add_f32 v[124:125], v[86:87], v[90:91] neg_lo:[0,1] neg_hi:[0,1]
	v_pk_add_f32 v[86:87], v[84:85], v[88:89]
	v_pk_add_f32 v[84:85], v[88:89], v[84:85] neg_lo:[0,1] neg_hi:[0,1]
	v_pk_add_f32 v[90:91], v[98:99], v[86:87]
	v_pk_add_f32 v[86:87], v[98:99], v[86:87] neg_lo:[0,1] neg_hi:[0,1]
	v_xor_b32_e32 v99, 0x80000000, v84
	v_mov_b32_e32 v98, v85
	v_pk_add_f32 v[94:95], v[94:95], v[132:133] neg_lo:[0,1] neg_hi:[0,1]
	v_pk_add_f32 v[88:89], v[124:125], v[98:99]
	v_pk_add_f32 v[84:85], v[124:125], v[98:99] neg_lo:[0,1] neg_hi:[0,1]
	v_pk_mul_f32 v[98:99], v[94:95], s[12:13] op_sel:[1,0]
	v_pk_add_f32 v[92:93], v[92:93], v[126:127] neg_lo:[0,1] neg_hi:[0,1]
	v_pk_fma_f32 v[94:95], v[94:95], s[34:35], v[98:99] op_sel_hi:[0,1,1]
	v_pk_add_f32 v[98:99], v[100:101], v[122:123] neg_lo:[0,1] neg_hi:[0,1]
	v_pk_mul_f32 v[100:101], v[92:93], s[10:11] op_sel:[1,0]
	v_pk_add_f32 v[96:97], v[96:97], v[128:129] neg_lo:[0,1] neg_hi:[0,1]
	v_pk_fma_f32 v[92:93], v[92:93], s[28:29], v[100:101] op_sel_hi:[0,1,1]
	v_mul_f32_e32 v100, 0xbf3504f3, v96
	v_pk_fma_f32 v[96:97], v[96:97], s[30:31], v[100:101] op_sel:[1,0,0] op_sel_hi:[1,1,0]
	v_pk_add_f32 v[122:123], v[92:93], v[94:95]
	v_pk_add_f32 v[100:101], v[98:99], v[96:97]
	v_pk_add_f32 v[94:95], v[92:93], v[94:95] neg_lo:[0,1] neg_hi:[0,1]
	v_pk_add_f32 v[98:99], v[98:99], v[96:97] neg_lo:[0,1] neg_hi:[0,1]
	v_pk_add_f32 v[96:97], v[100:101], v[122:123]
	v_pk_add_f32 v[92:93], v[100:101], v[122:123] neg_lo:[0,1] neg_hi:[0,1]
	v_xor_b32_e32 v101, 0x80000000, v94
	v_mov_b32_e32 v100, v95
	v_pk_add_f32 v[94:95], v[98:99], v[100:101]
	v_pk_add_f32 v[98:99], v[98:99], v[100:101] neg_lo:[0,1] neg_hi:[0,1]

.LBB0_1579:
	s_or_b64 exec, exec, s[8:9]
	s_waitcnt lgkmcnt(0)
	s_barrier
	s_and_saveexec_b64 s[8:9], vcc
	s_cbranch_execz .LBB0_1581
	ds_read_b64 v[202:203], v23 offset:61440
	ds_read_b64 v[174:175], v63 offset:57344
	ds_read_b64 v[176:177], v102 offset:53248
	ds_read_b64 v[178:179], v105 offset:49152
	ds_read_b64 v[180:181], v108 offset:45056
	ds_read_b64 v[182:183], v111 offset:40960
	ds_read_b64 v[184:185], v117
	ds_read_b64 v[186:187], v109 offset:4096
	ds_read_b64 v[188:189], v106 offset:8192
	ds_read_b64 v[190:191], v103 offset:12288
	ds_read_b64 v[192:193], v65 offset:16384
	ds_read_b64 v[194:195], v27 offset:20480
	ds_read_b64 v[196:197], v15 offset:24576
	ds_read_b64 v[198:199], v11 offset:28672
	ds_read_b64 v[200:201], v116 offset:32768
	s_waitcnt lgkmcnt(14)
	ds_read_b64 v[172:173], v113 offset:36864
	v_cvt_f32_ubyte0_e32 v68, v114
	v_mul_f32_e32 v68, 0x39800000, v68
	v_cos_f32_e32 v84, v68
	v_sin_f32_e32 v92, v68
	s_mov_b32 s29, s26
	v_mov_b32_e32 v93, v84
	v_xor_b32_e32 v85, 0x80000000, v92
	v_pk_mul_f32 v[68:69], v[92:93], v[92:93] op_sel_hi:[1,0] neg_lo:[0,1] neg_hi:[0,1]
	s_mov_b32 s10, s26
	v_pk_fma_f32 v[90:91], v[84:85], v[84:85], v[68:69] op_sel_hi:[1,0,1]
	s_mov_b32 s11, s28
	v_pk_mul_f32 v[68:69], v[92:93], v[90:91] op_sel:[0,1]
	s_mov_b32 s37, s20
	v_pk_fma_f32 v[86:87], v[84:85], v[90:91], v[68:69] op_sel_hi:[1,0,1]
	s_mov_b32 s12, s27
	v_pk_mul_f32 v[68:69], v[92:93], v[86:87] op_sel:[0,1]
	s_mov_b32 s13, s34
	v_pk_fma_f32 v[82:83], v[84:85], v[86:87], v[68:69] op_sel_hi:[1,0,1]
	s_mov_b32 s35, s28
	v_pk_mul_f32 v[68:69], v[92:93], v[82:83] op_sel:[0,1]
	s_nop 0
	v_pk_fma_f32 v[80:81], v[84:85], v[82:83], v[68:69] op_sel_hi:[1,0,1]
	s_nop 0
	v_pk_mul_f32 v[68:69], v[92:93], v[80:81] op_sel:[0,1]
	s_nop 0
	v_pk_fma_f32 v[78:79], v[84:85], v[80:81], v[68:69] op_sel_hi:[1,0,1]
	s_nop 0
	v_pk_mul_f32 v[68:69], v[92:93], v[78:79] op_sel:[0,1]
	s_nop 0
	v_pk_fma_f32 v[76:77], v[84:85], v[78:79], v[68:69] op_sel_hi:[1,0,1]
	s_nop 0
	v_pk_mul_f32 v[68:69], v[92:93], v[76:77] op_sel:[0,1]
	s_nop 0
	v_pk_fma_f32 v[70:71], v[84:85], v[76:77], v[68:69] op_sel_hi:[1,0,1]
	s_nop 0
	v_pk_mul_f32 v[68:69], v[92:93], v[70:71] op_sel:[0,1]
	s_nop 0
	v_pk_fma_f32 v[68:69], v[84:85], v[70:71], v[68:69] op_sel_hi:[1,0,1]
	s_nop 0
	v_pk_mul_f32 v[72:73], v[92:93], v[68:69] op_sel:[0,1]
	s_nop 0
	v_pk_fma_f32 v[96:97], v[84:85], v[68:69], v[72:73] op_sel_hi:[1,0,1]
	s_nop 0
	v_pk_mul_f32 v[72:73], v[92:93], v[96:97] op_sel:[0,1]
	s_nop 0
	v_pk_fma_f32 v[94:95], v[84:85], v[96:97], v[72:73] op_sel_hi:[1,0,1]
	s_nop 0
	v_pk_mul_f32 v[72:73], v[92:93], v[94:95] op_sel:[0,1]
	s_nop 0
	v_pk_fma_f32 v[98:99], v[84:85], v[94:95], v[72:73] op_sel_hi:[1,0,1]
	s_nop 0
	v_pk_mul_f32 v[72:73], v[92:93], v[98:99] op_sel:[0,1]
	s_nop 0
	v_pk_fma_f32 v[88:89], v[84:85], v[98:99], v[72:73] op_sel_hi:[1,0,1]
	s_nop 0
	v_pk_mul_f32 v[72:73], v[92:93], v[88:89] op_sel:[0,1]
	s_nop 0
	v_pk_fma_f32 v[74:75], v[84:85], v[88:89], v[72:73] op_sel_hi:[1,0,1]
	s_nop 0
	v_pk_mul_f32 v[72:73], v[92:93], v[74:75] op_sel:[0,1]
	s_nop 0
	v_pk_fma_f32 v[72:73], v[84:85], v[74:75], v[72:73] op_sel_hi:[1,0,1]
	s_nop 0
	v_xor_b32_e32 v124, 0x80000000, v73
	v_mov_b32_e32 v125, v72
	s_waitcnt lgkmcnt(15)
	s_nop 0
	v_pk_mul_f32 v[124:125], v[124:125], v[202:203] op_sel:[0,1]
	s_nop 0
	v_pk_fma_f32 v[72:73], v[72:73], v[202:203], v[124:125] op_sel_hi:[1,0,1]
	v_xor_b32_e32 v124, 0x80000000, v75
	v_mov_b32_e32 v125, v74
	s_waitcnt lgkmcnt(14)
	v_pk_mul_f32 v[124:125], v[124:125], v[174:175] op_sel:[0,1]
	s_nop 0
	v_pk_fma_f32 v[74:75], v[74:75], v[174:175], v[124:125] op_sel_hi:[1,0,1]
	v_xor_b32_e32 v124, 0x80000000, v89
	v_mov_b32_e32 v125, v88
	s_waitcnt lgkmcnt(13)
	v_pk_mul_f32 v[124:125], v[124:125], v[176:177] op_sel:[0,1]
	s_nop 0
	v_pk_fma_f32 v[88:89], v[88:89], v[176:177], v[124:125] op_sel_hi:[1,0,1]
	v_xor_b32_e32 v124, 0x80000000, v99
	v_mov_b32_e32 v125, v98
	s_waitcnt lgkmcnt(12)
	v_pk_mul_f32 v[124:125], v[124:125], v[178:179] op_sel:[0,1]
	s_nop 0
	v_pk_fma_f32 v[98:99], v[98:99], v[178:179], v[124:125] op_sel_hi:[1,0,1]
	v_xor_b32_e32 v124, 0x80000000, v95
	v_mov_b32_e32 v125, v94
	s_waitcnt lgkmcnt(11)
	v_pk_mul_f32 v[124:125], v[124:125], v[180:181] op_sel:[0,1]
	s_nop 0
	v_pk_fma_f32 v[94:95], v[94:95], v[180:181], v[124:125] op_sel_hi:[1,0,1]
	v_xor_b32_e32 v124, 0x80000000, v97
	v_mov_b32_e32 v125, v96
	s_waitcnt lgkmcnt(10)
	v_pk_mul_f32 v[124:125], v[124:125], v[182:183] op_sel:[0,1]
	s_nop 0
	v_pk_fma_f32 v[96:97], v[96:97], v[182:183], v[124:125] op_sel_hi:[1,0,1]
	s_waitcnt lgkmcnt(8)
	v_pk_mul_f32 v[92:93], v[92:93], v[186:187] op_sel:[0,1]
	s_nop 0
	v_pk_fma_f32 v[92:93], v[84:85], v[186:187], v[92:93] op_sel_hi:[1,0,1]
	v_xor_b32_e32 v124, 0x80000000, v91
	v_mov_b32_e32 v125, v90
	s_waitcnt lgkmcnt(7)
	v_pk_mul_f32 v[124:125], v[124:125], v[188:189] op_sel:[0,1]
	s_nop 0
	v_pk_fma_f32 v[90:91], v[90:91], v[188:189], v[124:125] op_sel_hi:[1,0,1]
	v_xor_b32_e32 v124, 0x80000000, v87
	v_mov_b32_e32 v125, v86
	s_waitcnt lgkmcnt(6)
	v_pk_mul_f32 v[124:125], v[124:125], v[190:191] op_sel:[0,1]
	s_nop 0
	v_pk_fma_f32 v[84:85], v[86:87], v[190:191], v[124:125] op_sel_hi:[1,0,1]
	v_xor_b32_e32 v124, 0x80000000, v83
	v_mov_b32_e32 v125, v82
	s_waitcnt lgkmcnt(5)
	v_pk_mul_f32 v[124:125], v[124:125], v[192:193] op_sel:[0,1]
	s_nop 0
	v_pk_fma_f32 v[82:83], v[82:83], v[192:193], v[124:125] op_sel_hi:[1,0,1]
	v_xor_b32_e32 v124, 0x80000000, v81
	v_mov_b32_e32 v125, v80
	s_waitcnt lgkmcnt(4)
	v_pk_mul_f32 v[124:125], v[124:125], v[194:195] op_sel:[0,1]
	s_nop 0
	v_pk_fma_f32 v[80:81], v[80:81], v[194:195], v[124:125] op_sel_hi:[1,0,1]
	v_xor_b32_e32 v124, 0x80000000, v79
	v_mov_b32_e32 v125, v78
	s_waitcnt lgkmcnt(3)
	v_pk_mul_f32 v[124:125], v[124:125], v[196:197] op_sel:[0,1]
	s_nop 0
	v_pk_fma_f32 v[78:79], v[78:79], v[196:197], v[124:125] op_sel_hi:[1,0,1]
	v_xor_b32_e32 v124, 0x80000000, v77
	v_mov_b32_e32 v125, v76
	s_waitcnt lgkmcnt(2)
	v_pk_mul_f32 v[124:125], v[124:125], v[198:199] op_sel:[0,1]
	s_nop 0
	v_pk_fma_f32 v[76:77], v[76:77], v[198:199], v[124:125] op_sel_hi:[1,0,1]
	v_xor_b32_e32 v124, 0x80000000, v71
	v_mov_b32_e32 v125, v70
	s_waitcnt lgkmcnt(1)
	v_pk_mul_f32 v[124:125], v[124:125], v[200:201] op_sel:[0,1]
	s_nop 0
	v_pk_fma_f32 v[70:71], v[70:71], v[200:201], v[124:125] op_sel_hi:[1,0,1]
	v_xor_b32_e32 v124, 0x80000000, v69
	v_mov_b32_e32 v125, v68
	s_waitcnt lgkmcnt(0)
	v_pk_mul_f32 v[124:125], v[124:125], v[172:173] op_sel:[0,1]
	s_nop 0
	v_pk_fma_f32 v[68:69], v[68:69], v[172:173], v[124:125] op_sel_hi:[1,0,1]
	v_pk_add_f32 v[86:87], v[184:185], v[70:71]
	v_pk_add_f32 v[100:101], v[184:185], v[70:71] neg_lo:[0,1] neg_hi:[0,1]
	v_pk_add_f32 v[70:71], v[98:99], v[82:83]
	v_pk_add_f32 v[82:83], v[82:83], v[98:99] neg_lo:[0,1] neg_hi:[0,1]
	v_pk_add_f32 v[98:99], v[70:71], v[86:87]
	v_pk_add_f32 v[86:87], v[86:87], v[70:71] neg_lo:[0,1] neg_hi:[0,1]
	v_pk_add_f32 v[70:71], v[92:93], v[68:69]
	v_pk_add_f32 v[92:93], v[92:93], v[68:69] neg_lo:[0,1] neg_hi:[0,1]
	v_pk_add_f32 v[68:69], v[88:89], v[80:81]
	v_pk_add_f32 v[80:81], v[80:81], v[88:89] neg_lo:[0,1] neg_hi:[0,1]
	v_pk_add_f32 v[88:89], v[68:69], v[70:71]
	v_pk_add_f32 v[126:127], v[70:71], v[68:69] neg_lo:[0,1] neg_hi:[0,1]
	v_pk_add_f32 v[68:69], v[96:97], v[90:91]
	v_pk_add_f32 v[70:71], v[74:75], v[78:79]
	v_pk_add_f32 v[96:97], v[90:91], v[96:97] neg_lo:[0,1] neg_hi:[0,1]
	v_pk_add_f32 v[74:75], v[78:79], v[74:75] neg_lo:[0,1] neg_hi:[0,1]
	v_pk_add_f32 v[78:79], v[68:69], v[70:71]
	v_pk_add_f32 v[90:91], v[68:69], v[70:71] neg_lo:[0,1] neg_hi:[0,1]
	v_pk_add_f32 v[68:69], v[94:95], v[84:85]
	v_pk_add_f32 v[70:71], v[72:73], v[76:77]
	v_xor_b32_e32 v131, 0x80000000, v74
	v_mov_b32_e32 v130, v75
	v_pk_add_f32 v[72:73], v[76:77], v[72:73] neg_lo:[0,1] neg_hi:[0,1]
	v_pk_add_f32 v[74:75], v[68:69], v[70:71]
	v_xor_b32_e32 v129, 0x80000000, v80
	v_mov_b32_e32 v128, v81
	v_pk_add_f32 v[94:95], v[84:85], v[94:95] neg_lo:[0,1] neg_hi:[0,1]
	v_pk_add_f32 v[84:85], v[68:69], v[70:71] neg_lo:[0,1] neg_hi:[0,1]
	v_xor_b32_e32 v135, 0x80000000, v72
	v_mov_b32_e32 v134, v73
	v_pk_add_f32 v[68:69], v[78:79], v[98:99]
	v_pk_add_f32 v[70:71], v[74:75], v[88:89]
	v_pk_add_f32 v[72:73], v[88:89], v[74:75] neg_lo:[0,1] neg_hi:[0,1]
	v_pk_add_f32 v[80:81], v[128:129], v[92:93]
	v_pk_add_f32 v[78:79], v[98:99], v[78:79] neg_lo:[0,1] neg_hi:[0,1]
	v_pk_add_f32 v[74:75], v[68:69], v[70:71]
	v_pk_add_f32 v[70:71], v[68:69], v[70:71] neg_lo:[0,1] neg_hi:[0,1]
	v_xor_b32_e32 v69, 0x80000000, v72
	v_mov_b32_e32 v68, v73
	v_pk_add_f32 v[132:133], v[96:97], v[130:131]
	v_pk_add_f32 v[76:77], v[94:95], v[134:135]
	v_pk_add_f32 v[72:73], v[78:79], v[68:69]
	v_pk_add_f32 v[68:69], v[78:79], v[68:69] neg_lo:[0,1] neg_hi:[0,1]
	v_pk_mul_f32 v[78:79], v[80:81], s[28:29] op_sel:[1,0]
	v_xor_b32_e32 v125, 0x80000000, v82
	v_mov_b32_e32 v124, v83
	v_pk_fma_f32 v[78:79], v[80:81], s[26:27], v[78:79] op_sel_hi:[0,1,1]
	v_mul_f32_e32 v80, 0x3f3504f3, v133
	s_mov_b32 s29, s34
	v_pk_mul_f32 v[88:89], v[76:77], s[10:11] op_sel:[1,0]
	v_pk_add_f32 v[82:83], v[124:125], v[100:101]
	v_pk_fma_f32 v[80:81], v[132:133], s[30:31], v[80:81] op_sel_hi:[0,1,0]
	v_pk_fma_f32 v[76:77], v[76:77], s[28:29], v[88:89] op_sel_hi:[0,1,1]
	v_pk_add_f32 v[88:89], v[82:83], v[80:81]
	v_pk_add_f32 v[98:99], v[82:83], v[80:81] neg_lo:[0,1] neg_hi:[0,1]
	v_pk_add_f32 v[80:81], v[78:79], v[76:77]
	v_pk_add_f32 v[76:77], v[78:79], v[76:77] neg_lo:[0,1] neg_hi:[0,1]
	v_pk_add_f32 v[82:83], v[88:89], v[80:81]
	v_pk_add_f32 v[78:79], v[88:89], v[80:81] neg_lo:[0,1] neg_hi:[0,1]
	v_xor_b32_e32 v89, 0x80000000, v76
	v_mov_b32_e32 v88, v77
	v_pk_add_f32 v[80:81], v[98:99], v[88:89]
	v_pk_add_f32 v[76:77], v[98:99], v[88:89] neg_lo:[0,1] neg_hi:[0,1]
	v_pk_mul_f32 v[98:99], v[90:91], s[36:37] op_sel:[1,0]
	v_mul_f32_e32 v88, 0x3f3504f3, v127
	v_pk_fma_f32 v[90:91], v[90:91], s[20:21], v[98:99] op_sel_hi:[0,1,1]
	v_mul_f32_e32 v98, 0xbf3504f3, v84
	v_pk_fma_f32 v[88:89], v[126:127], s[30:31], v[88:89] op_sel_hi:[0,1,0]
	v_pk_fma_f32 v[84:85], v[84:85], s[30:31], v[98:99] op_sel:[1,0,0] op_sel_hi:[1,1,0]
	v_pk_add_f32 v[98:99], v[86:87], v[90:91]
	v_pk_add_f32 v[126:127], v[86:87], v[90:91] neg_lo:[0,1] neg_hi:[0,1]
	v_pk_add_f32 v[86:87], v[84:85], v[88:89]
	v_pk_add_f32 v[84:85], v[88:89], v[84:85] neg_lo:[0,1] neg_hi:[0,1]
	v_pk_add_f32 v[90:91], v[98:99], v[86:87]
	v_pk_add_f32 v[86:87], v[98:99], v[86:87] neg_lo:[0,1] neg_hi:[0,1]
	v_xor_b32_e32 v99, 0x80000000, v84
	v_mov_b32_e32 v98, v85
	v_pk_add_f32 v[94:95], v[94:95], v[134:135] neg_lo:[0,1] neg_hi:[0,1]
	v_pk_add_f32 v[88:89], v[126:127], v[98:99]
	v_pk_add_f32 v[84:85], v[126:127], v[98:99] neg_lo:[0,1] neg_hi:[0,1]
	v_pk_mul_f32 v[98:99], v[94:95], s[12:13] op_sel:[1,0]
	v_pk_add_f32 v[92:93], v[92:93], v[128:129] neg_lo:[0,1] neg_hi:[0,1]
	v_pk_fma_f32 v[94:95], v[94:95], s[34:35], v[98:99] op_sel_hi:[0,1,1]
	v_pk_add_f32 v[98:99], v[100:101], v[124:125] neg_lo:[0,1] neg_hi:[0,1]
	v_pk_mul_f32 v[100:101], v[92:93], s[10:11] op_sel:[1,0]
	v_pk_add_f32 v[96:97], v[96:97], v[130:131] neg_lo:[0,1] neg_hi:[0,1]
	v_pk_fma_f32 v[92:93], v[92:93], s[28:29], v[100:101] op_sel_hi:[0,1,1]
	v_mul_f32_e32 v100, 0xbf3504f3, v96
	v_pk_fma_f32 v[96:97], v[96:97], s[30:31], v[100:101] op_sel:[1,0,0] op_sel_hi:[1,1,0]
	v_pk_add_f32 v[124:125], v[92:93], v[94:95]
	v_pk_add_f32 v[100:101], v[98:99], v[96:97]
	v_pk_add_f32 v[94:95], v[92:93], v[94:95] neg_lo:[0,1] neg_hi:[0,1]
	v_pk_add_f32 v[98:99], v[98:99], v[96:97] neg_lo:[0,1] neg_hi:[0,1]
	v_pk_add_f32 v[96:97], v[100:101], v[124:125]
	v_pk_add_f32 v[92:93], v[100:101], v[124:125] neg_lo:[0,1] neg_hi:[0,1]
	v_xor_b32_e32 v101, 0x80000000, v94
	v_mov_b32_e32 v100, v95
	v_pk_add_f32 v[94:95], v[98:99], v[100:101]
	v_pk_add_f32 v[98:99], v[98:99], v[100:101] neg_lo:[0,1] neg_hi:[0,1]

.LBB0_1583:
	s_or_b64 exec, exec, s[8:9]
	s_waitcnt lgkmcnt(0)
	s_barrier
	s_and_saveexec_b64 s[8:9], vcc
	s_cbranch_execz .LBB0_1585
	ds_read_b64 v[176:177], v116 offset:32768
	v_cvt_f32_i32_e32 v70, v114
	v_lshlrev_b32_e32 v71, 3, v115
	v_lshlrev_b32_e32 v73, 3, v114
	v_mul_f32_e32 v72, 0x39000000, v70
	v_sin_f32_e32 v70, v72
	v_cos_f32_e32 v72, v72
	v_add3_u32 v76, s3, v71, v73
	ds_read_b64 v[178:179], v76
	ds_read_b64 v[180:181], v113 offset:36864
	ds_read_b64 v[182:183], v109 offset:4096
	ds_read_b64 v[184:185], v111 offset:40960
	ds_read_b64 v[186:187], v106 offset:8192
	ds_read_b64 v[188:189], v108 offset:45056
	ds_read_b64 v[190:191], v103 offset:12288
	ds_read_b64 v[192:193], v105 offset:49152
	ds_read_b64 v[194:195], v65 offset:16384
	ds_read_b64 v[196:197], v102 offset:53248
	ds_read_b64 v[198:199], v27 offset:20480
	ds_read_b64 v[172:173], v63 offset:57344
	ds_read_b64 v[174:175], v15 offset:24576
	v_xor_b32_e32 v73, 0x80000000, v70
	v_mov_b32_e32 v71, v72
	s_waitcnt lgkmcnt(14)
	s_waitcnt lgkmcnt(13)
	v_pk_mul_f32 v[70:71], v[70:71], v[176:177] op_sel:[0,1]
	v_cvt_f32_i32_e32 v67, v67
	v_pk_fma_f32 v[68:69], v[72:73], v[176:177], v[70:71] op_sel_hi:[1,0,1]
	v_cvt_f32_i32_e32 v72, v112
	s_waitcnt lgkmcnt(12)
	v_pk_add_f32 v[70:71], v[178:179], v[68:69]
	v_pk_add_f32 v[68:69], v[178:179], v[68:69] neg_lo:[0,1] neg_hi:[0,1]
	ds_write_b64 v76, v[70:71]
	ds_write_b64 v116, v[68:69] offset:32768
	v_mul_f32_e32 v69, 0x39000000, v72
	v_cos_f32_e32 v68, v69
	v_sin_f32_e32 v70, v69
	v_cvt_f32_i32_e32 v31, v31
	v_mov_b32_e32 v71, v68
	v_xor_b32_e32 v69, 0x80000000, v70
	s_waitcnt lgkmcnt(13)
	v_pk_mul_f32 v[70:71], v[70:71], v[180:181] op_sel:[0,1]
	v_cvt_f32_i32_e32 v19, v19
	v_pk_fma_f32 v[68:69], v[68:69], v[180:181], v[70:71] op_sel_hi:[1,0,1]
	v_cvt_f32_i32_e32 v72, v110
	s_waitcnt lgkmcnt(12)
	v_pk_add_f32 v[70:71], v[182:183], v[68:69]
	v_pk_add_f32 v[68:69], v[182:183], v[68:69] neg_lo:[0,1] neg_hi:[0,1]
	ds_write_b64 v109, v[70:71] offset:4096
	ds_write_b64 v113, v[68:69] offset:36864
	v_mul_f32_e32 v69, 0x39000000, v72
	v_cos_f32_e32 v68, v69
	v_sin_f32_e32 v70, v69
	s_nop 0
	v_mov_b32_e32 v71, v68
	v_xor_b32_e32 v69, 0x80000000, v70
	s_waitcnt lgkmcnt(13)
	v_pk_mul_f32 v[70:71], v[70:71], v[184:185] op_sel:[0,1]
	s_nop 0
	v_pk_fma_f32 v[68:69], v[68:69], v[184:185], v[70:71] op_sel_hi:[1,0,1]
	v_cvt_f32_i32_e32 v72, v107
	s_waitcnt lgkmcnt(12)
	v_pk_add_f32 v[70:71], v[186:187], v[68:69]
	v_pk_add_f32 v[68:69], v[186:187], v[68:69] neg_lo:[0,1] neg_hi:[0,1]
	ds_write_b64 v106, v[70:71] offset:8192
	ds_write_b64 v111, v[68:69] offset:40960
	v_mul_f32_e32 v69, 0x39000000, v72
	v_cos_f32_e32 v68, v69
	v_sin_f32_e32 v70, v69
	s_nop 0
	v_mov_b32_e32 v71, v68
	v_xor_b32_e32 v69, 0x80000000, v70
	s_waitcnt lgkmcnt(13)
	v_pk_mul_f32 v[70:71], v[70:71], v[188:189] op_sel:[0,1]
	s_nop 0
	v_pk_fma_f32 v[68:69], v[68:69], v[188:189], v[70:71] op_sel_hi:[1,0,1]
	v_cvt_f32_i32_e32 v72, v104
	s_waitcnt lgkmcnt(12)
	v_pk_add_f32 v[70:71], v[190:191], v[68:69]
	v_pk_add_f32 v[68:69], v[190:191], v[68:69] neg_lo:[0,1] neg_hi:[0,1]
	ds_write_b64 v103, v[70:71] offset:12288
	ds_write_b64 v108, v[68:69] offset:45056
	v_mul_f32_e32 v69, 0x39000000, v72
	ds_read_b64 v[72:73], v23 offset:61440
	s_waitcnt lgkmcnt(14)
	ds_read_b64 v[74:75], v11 offset:28672
	v_cos_f32_e32 v68, v69
	v_sin_f32_e32 v70, v69
	s_nop 0
	v_mov_b32_e32 v71, v68
	v_xor_b32_e32 v69, 0x80000000, v70
	s_nop 0
	v_pk_mul_f32 v[70:71], v[70:71], v[192:193] op_sel:[0,1]
	s_nop 0
	v_pk_fma_f32 v[68:69], v[68:69], v[192:193], v[70:71] op_sel_hi:[1,0,1]
	s_waitcnt lgkmcnt(14)
	v_pk_add_f32 v[70:71], v[194:195], v[68:69]
	ds_write_b64 v65, v[70:71] offset:16384
	v_pk_add_f32 v[68:69], v[194:195], v[68:69] neg_lo:[0,1] neg_hi:[0,1]
	v_mul_f32_e32 v65, 0x39000000, v67
	s_waitcnt lgkmcnt(14)
	ds_write_b64 v105, v[68:69] offset:49152
	v_cos_f32_e32 v68, v65
	v_sin_f32_e32 v70, v65
	s_nop 0
	v_mov_b32_e32 v71, v68
	v_xor_b32_e32 v69, 0x80000000, v70
	s_nop 0
	v_pk_mul_f32 v[70:71], v[70:71], v[196:197] op_sel:[0,1]
	s_nop 0
	v_pk_fma_f32 v[68:69], v[68:69], v[196:197], v[70:71] op_sel_hi:[1,0,1]
	s_waitcnt lgkmcnt(14)
	v_pk_add_f32 v[70:71], v[198:199], v[68:69]
	ds_write_b64 v27, v[70:71] offset:20480
	v_pk_add_f32 v[68:69], v[198:199], v[68:69] neg_lo:[0,1] neg_hi:[0,1]
	v_mul_f32_e32 v27, 0x39000000, v31
	s_waitcnt lgkmcnt(14)
	ds_write_b64 v102, v[68:69] offset:53248
	v_cos_f32_e32 v68, v27
	v_sin_f32_e32 v70, v27
	s_nop 0
	v_mov_b32_e32 v71, v68
	v_xor_b32_e32 v69, 0x80000000, v70
	s_nop 0
	v_pk_mul_f32 v[70:71], v[70:71], v[172:173] op_sel:[0,1]
	s_nop 0
	v_pk_fma_f32 v[68:69], v[68:69], v[172:173], v[70:71] op_sel_hi:[1,0,1]
	s_waitcnt lgkmcnt(14)
	v_pk_add_f32 v[70:71], v[174:175], v[68:69]
	ds_write_b64 v15, v[70:71] offset:24576
	v_pk_add_f32 v[68:69], v[174:175], v[68:69] neg_lo:[0,1] neg_hi:[0,1]
	v_mul_f32_e32 v15, 0x39000000, v19
	s_waitcnt lgkmcnt(14)
	ds_write_b64 v63, v[68:69] offset:57344
	v_cos_f32_e32 v68, v15
	v_sin_f32_e32 v70, v15
	s_nop 0
	v_mov_b32_e32 v71, v68
	v_xor_b32_e32 v69, 0x80000000, v70
	s_waitcnt lgkmcnt(7)
	v_pk_mul_f32 v[70:71], v[70:71], v[72:73] op_sel:[0,1]
	s_nop 0
	v_pk_fma_f32 v[68:69], v[68:69], v[72:73], v[70:71] op_sel_hi:[1,0,1]
	s_waitcnt lgkmcnt(6)
	v_pk_add_f32 v[70:71], v[74:75], v[68:69]
	v_pk_add_f32 v[68:69], v[74:75], v[68:69] neg_lo:[0,1] neg_hi:[0,1]
	ds_write_b64 v11, v[70:71] offset:28672
	ds_write_b64 v23, v[68:69] offset:61440

.LBB0_1605:
	s_or_b64 exec, exec, s[6:7]
	v_add_u32_e32 v116, 0x1000, v128
	v_ashrrev_i32_e32 v116, 4, v116
	v_lshlrev_b32_e32 v116, 3, v116
	v_lshlrev_b32_e32 v135, 3, v128
	v_add3_u32 v134, 0, v116, v135
	v_add_u32_e32 v116, 0x1200, v128
	v_ashrrev_i32_e32 v116, 4, v116
	v_lshlrev_b32_e32 v116, 3, v116
	v_add3_u32 v133, 0, v116, v135
	v_add_u32_e32 v116, 0x1400, v128
	v_ashrrev_i32_e32 v116, 4, v116
	v_lshlrev_b32_e32 v116, 3, v116
	v_add3_u32 v132, 0, v116, v135
	v_add_u32_e32 v116, 0x1600, v128
	v_ashrrev_i32_e32 v116, 4, v116
	v_lshlrev_b32_e32 v116, 3, v116
	v_add3_u32 v131, 0, v116, v135
	v_add_u32_e32 v116, 0x1800, v128
	v_ashrrev_i32_e32 v116, 4, v116
	v_lshlrev_b32_e32 v116, 3, v116
	v_add3_u32 v130, 0, v116, v135
	v_add_u32_e32 v116, 0x1a00, v128
	v_ashrrev_i32_e32 v116, 4, v116
	v_lshlrev_b32_e32 v116, 3, v116
	v_add3_u32 v129, 0, v116, v135
	v_add_u32_e32 v116, 0x1c00, v128
	v_ashrrev_i32_e32 v116, 4, v116
	v_lshlrev_b32_e32 v116, 3, v116
	v_add3_u32 v117, 0, v116, v135
	v_add_u32_e32 v116, 0x1e00, v128
	v_ashrrev_i32_e32 v116, 4, v116
	s_waitcnt lgkmcnt(0)
	s_barrier
	v_lshlrev_b32_e32 v116, 3, v116
	v_add3_u32 v116, 0, v116, v135
	s_and_saveexec_b64 s[6:7], vcc
	s_cbranch_execz .LBB0_1607
	ds_read_b64 v[172:173], v136
	ds_read_b64 v[174:175], v124 offset:4096
	ds_read_b64 v[176:177], v122 offset:8192
	ds_read_b64 v[178:179], v65 offset:12288
	ds_read_b64 v[180:181], v31 offset:16384
	ds_read_b64 v[182:183], v23 offset:20480
	ds_read_b64 v[184:185], v15 offset:24576
	ds_read_b64 v[186:187], v11 offset:28672
	ds_read_b64 v[188:189], v134 offset:32768
	ds_read_b64 v[190:191], v133 offset:36864
	ds_read_b64 v[192:193], v132 offset:40960
	ds_read_b64 v[194:195], v131 offset:45056
	ds_read_b64 v[196:197], v130 offset:49152
	ds_read_b64 v[198:199], v129 offset:53248
	ds_read_b64 v[200:201], v117 offset:57344
	s_waitcnt lgkmcnt(14)
	ds_read_b64 v[202:203], v116 offset:61440
	v_and_b32_e32 v108, 15, v128
	v_cvt_f32_ubyte0_e32 v108, v108
	v_mul_f32_e32 v109, 0x3b800000, v108
	v_cos_f32_e32 v108, v109
	v_sin_f32_e32 v110, v109
	s_waitcnt lgkmcnt(15)
	v_mov_b32_e32 v111, v108
	v_xor_b32_e32 v109, 0x80000000, v110
	v_pk_mul_f32 v[142:143], v[110:111], v[110:111] op_sel_hi:[1,0] neg_lo:[0,1] neg_hi:[0,1]
	s_mov_b32 s29, s26
	v_pk_fma_f32 v[142:143], v[108:109], v[108:109], v[142:143] op_sel_hi:[1,0,1]
	s_mov_b32 s8, s26
	v_pk_mul_f32 v[144:145], v[110:111], v[142:143] op_sel:[0,1]
	s_mov_b32 s9, s28
	v_pk_fma_f32 v[144:145], v[108:109], v[142:143], v[144:145] op_sel_hi:[1,0,1]
	s_mov_b32 s37, s20
	v_pk_mul_f32 v[146:147], v[110:111], v[144:145] op_sel:[0,1]
	s_mov_b32 s10, s27
	v_pk_fma_f32 v[146:147], v[108:109], v[144:145], v[146:147] op_sel_hi:[1,0,1]
	s_mov_b32 s11, s34
	v_pk_mul_f32 v[148:149], v[110:111], v[146:147] op_sel:[0,1]
	s_mov_b32 s35, s28
	v_pk_fma_f32 v[148:149], v[108:109], v[146:147], v[148:149] op_sel_hi:[1,0,1]
	s_nop 0
	v_pk_mul_f32 v[150:151], v[110:111], v[148:149] op_sel:[0,1]
	s_nop 0
	v_pk_fma_f32 v[150:151], v[108:109], v[148:149], v[150:151] op_sel_hi:[1,0,1]
	s_nop 0
	v_pk_mul_f32 v[152:153], v[110:111], v[150:151] op_sel:[0,1]
	s_nop 0
	v_pk_fma_f32 v[152:153], v[108:109], v[150:151], v[152:153] op_sel_hi:[1,0,1]
	s_nop 0
	v_pk_mul_f32 v[154:155], v[110:111], v[152:153] op_sel:[0,1]
	s_nop 0
	v_pk_fma_f32 v[154:155], v[108:109], v[152:153], v[154:155] op_sel_hi:[1,0,1]
	s_nop 0
	v_pk_mul_f32 v[156:157], v[110:111], v[154:155] op_sel:[0,1]
	s_nop 0
	v_pk_fma_f32 v[156:157], v[108:109], v[154:155], v[156:157] op_sel_hi:[1,0,1]
	s_nop 0
	v_pk_mul_f32 v[158:159], v[110:111], v[156:157] op_sel:[0,1]
	s_nop 0
	v_pk_fma_f32 v[158:159], v[108:109], v[156:157], v[158:159] op_sel_hi:[1,0,1]
	s_nop 0
	v_pk_mul_f32 v[160:161], v[110:111], v[158:159] op_sel:[0,1]
	s_nop 0
	v_pk_fma_f32 v[160:161], v[108:109], v[158:159], v[160:161] op_sel_hi:[1,0,1]
	s_nop 0
	v_pk_mul_f32 v[162:163], v[110:111], v[160:161] op_sel:[0,1]
	s_nop 0
	v_pk_fma_f32 v[162:163], v[108:109], v[160:161], v[162:163] op_sel_hi:[1,0,1]
	s_nop 0
	v_pk_mul_f32 v[164:165], v[110:111], v[162:163] op_sel:[0,1]
	s_nop 0
	v_pk_fma_f32 v[164:165], v[108:109], v[162:163], v[164:165] op_sel_hi:[1,0,1]
	s_nop 0
	v_pk_mul_f32 v[166:167], v[110:111], v[164:165] op_sel:[0,1]
	s_nop 0
	v_pk_fma_f32 v[166:167], v[108:109], v[164:165], v[166:167] op_sel_hi:[1,0,1]
	s_nop 0
	v_pk_mul_f32 v[168:169], v[110:111], v[166:167] op_sel:[0,1]
	s_waitcnt lgkmcnt(14)
	v_pk_mul_f32 v[110:111], v[110:111], v[174:175] op_sel:[0,1]
	v_pk_fma_f32 v[168:169], v[108:109], v[166:167], v[168:169] op_sel_hi:[1,0,1]
	v_pk_fma_f32 v[86:87], v[108:109], v[174:175], v[110:111] op_sel_hi:[1,0,1]
	v_xor_b32_e32 v170, 0x80000000, v169
	v_mov_b32_e32 v171, v168
	s_waitcnt lgkmcnt(0)
	v_pk_mul_f32 v[170:171], v[170:171], v[202:203] op_sel:[0,1]
	s_nop 0
	v_pk_fma_f32 v[140:141], v[168:169], v[202:203], v[170:171] op_sel_hi:[1,0,1]
	v_xor_b32_e32 v168, 0x80000000, v167
	v_mov_b32_e32 v169, v166
	v_pk_mul_f32 v[168:169], v[168:169], v[200:201] op_sel:[0,1]
	s_nop 0
	v_pk_fma_f32 v[138:139], v[166:167], v[200:201], v[168:169] op_sel_hi:[1,0,1]
	v_xor_b32_e32 v166, 0x80000000, v165
	v_mov_b32_e32 v167, v164
	v_pk_mul_f32 v[166:167], v[166:167], v[198:199] op_sel:[0,1]
	s_nop 0
	v_pk_fma_f32 v[114:115], v[164:165], v[198:199], v[166:167] op_sel_hi:[1,0,1]
	v_xor_b32_e32 v164, 0x80000000, v163
	v_mov_b32_e32 v165, v162
	v_pk_mul_f32 v[164:165], v[164:165], v[196:197] op_sel:[0,1]
	s_nop 0
	v_pk_fma_f32 v[112:113], v[162:163], v[196:197], v[164:165] op_sel_hi:[1,0,1]
	v_xor_b32_e32 v162, 0x80000000, v161
	v_mov_b32_e32 v163, v160
	v_pk_mul_f32 v[162:163], v[162:163], v[194:195] op_sel:[0,1]
	s_nop 0
	v_pk_fma_f32 v[106:107], v[160:161], v[194:195], v[162:163] op_sel_hi:[1,0,1]
	v_xor_b32_e32 v160, 0x80000000, v159
	v_mov_b32_e32 v161, v158
	v_pk_mul_f32 v[160:161], v[160:161], v[192:193] op_sel:[0,1]
	s_nop 0
	v_pk_fma_f32 v[104:105], v[158:159], v[192:193], v[160:161] op_sel_hi:[1,0,1]
	v_xor_b32_e32 v158, 0x80000000, v157
	v_mov_b32_e32 v159, v156
	v_pk_mul_f32 v[158:159], v[158:159], v[190:191] op_sel:[0,1]
	s_nop 0
	v_pk_fma_f32 v[102:103], v[156:157], v[190:191], v[158:159] op_sel_hi:[1,0,1]
	v_xor_b32_e32 v156, 0x80000000, v155
	v_mov_b32_e32 v157, v154
	v_pk_mul_f32 v[156:157], v[156:157], v[188:189] op_sel:[0,1]
	s_nop 0
	v_pk_fma_f32 v[100:101], v[154:155], v[188:189], v[156:157] op_sel_hi:[1,0,1]
	v_xor_b32_e32 v154, 0x80000000, v153
	v_mov_b32_e32 v155, v152
	v_pk_mul_f32 v[154:155], v[154:155], v[186:187] op_sel:[0,1]
	v_pk_add_f32 v[108:109], v[172:173], v[100:101]
	v_pk_fma_f32 v[98:99], v[152:153], v[186:187], v[154:155] op_sel_hi:[1,0,1]
	v_xor_b32_e32 v152, 0x80000000, v151
	v_mov_b32_e32 v153, v150
	v_pk_mul_f32 v[152:153], v[152:153], v[184:185] op_sel:[0,1]
	v_pk_add_f32 v[110:111], v[172:173], v[100:101] neg_lo:[0,1] neg_hi:[0,1]
	v_pk_fma_f32 v[96:97], v[150:151], v[184:185], v[152:153] op_sel_hi:[1,0,1]
	v_xor_b32_e32 v150, 0x80000000, v149
	v_mov_b32_e32 v151, v148
	v_pk_mul_f32 v[150:151], v[150:151], v[182:183] op_sel:[0,1]
	s_nop 0
	v_pk_fma_f32 v[94:95], v[148:149], v[182:183], v[150:151] op_sel_hi:[1,0,1]
	v_xor_b32_e32 v148, 0x80000000, v147
	v_mov_b32_e32 v149, v146
	v_pk_mul_f32 v[148:149], v[148:149], v[180:181] op_sel:[0,1]
	s_nop 0
	v_pk_fma_f32 v[92:93], v[146:147], v[180:181], v[148:149] op_sel_hi:[1,0,1]
	v_xor_b32_e32 v146, 0x80000000, v145
	v_mov_b32_e32 v147, v144
	v_pk_mul_f32 v[146:147], v[146:147], v[178:179] op_sel:[0,1]
	v_pk_add_f32 v[84:85], v[92:93], v[112:113]
	v_pk_fma_f32 v[90:91], v[144:145], v[178:179], v[146:147] op_sel_hi:[1,0,1]
	v_xor_b32_e32 v144, 0x80000000, v143
	v_mov_b32_e32 v145, v142
	v_pk_mul_f32 v[144:145], v[144:145], v[176:177] op_sel:[0,1]
	v_pk_add_f32 v[100:101], v[108:109], v[84:85]
	v_pk_fma_f32 v[88:89], v[142:143], v[176:177], v[144:145] op_sel_hi:[1,0,1]
	v_pk_add_f32 v[108:109], v[108:109], v[84:85] neg_lo:[0,1] neg_hi:[0,1]
	v_pk_add_f32 v[84:85], v[86:87], v[102:103]
	v_pk_add_f32 v[142:143], v[86:87], v[102:103] neg_lo:[0,1] neg_hi:[0,1]
	v_pk_add_f32 v[86:87], v[94:95], v[114:115]
	v_pk_add_f32 v[94:95], v[94:95], v[114:115] neg_lo:[0,1] neg_hi:[0,1]
	v_pk_add_f32 v[102:103], v[84:85], v[86:87]
	v_pk_add_f32 v[114:115], v[84:85], v[86:87] neg_lo:[0,1] neg_hi:[0,1]
	v_pk_add_f32 v[84:85], v[88:89], v[104:105]
	v_pk_add_f32 v[86:87], v[96:97], v[138:139]
	v_pk_add_f32 v[146:147], v[88:89], v[104:105] neg_lo:[0,1] neg_hi:[0,1]
	v_pk_add_f32 v[88:89], v[96:97], v[138:139] neg_lo:[0,1] neg_hi:[0,1]
	v_pk_add_f32 v[96:97], v[84:85], v[86:87]
	v_pk_add_f32 v[104:105], v[84:85], v[86:87] neg_lo:[0,1] neg_hi:[0,1]
	v_pk_add_f32 v[84:85], v[90:91], v[106:107]
	v_pk_add_f32 v[86:87], v[98:99], v[140:141]
	v_xor_b32_e32 v139, 0x80000000, v88
	v_mov_b32_e32 v138, v89
	v_pk_add_f32 v[150:151], v[90:91], v[106:107] neg_lo:[0,1] neg_hi:[0,1]
	v_pk_add_f32 v[88:89], v[98:99], v[140:141] neg_lo:[0,1] neg_hi:[0,1]
	v_pk_add_f32 v[90:91], v[84:85], v[86:87]
	v_xor_b32_e32 v145, 0x80000000, v94
	v_mov_b32_e32 v144, v95
	v_pk_add_f32 v[106:107], v[84:85], v[86:87] neg_lo:[0,1] neg_hi:[0,1]
	v_xor_b32_e32 v141, 0x80000000, v88
	v_mov_b32_e32 v140, v89
	v_pk_add_f32 v[84:85], v[100:101], v[96:97]
	v_pk_add_f32 v[86:87], v[102:103], v[90:91]
	v_pk_add_f32 v[88:89], v[102:103], v[90:91] neg_lo:[0,1] neg_hi:[0,1]
	v_pk_add_f32 v[94:95], v[142:143], v[144:145]
	v_pk_add_f32 v[96:97], v[100:101], v[96:97] neg_lo:[0,1] neg_hi:[0,1]
	v_pk_add_f32 v[90:91], v[84:85], v[86:87]
	v_pk_add_f32 v[86:87], v[84:85], v[86:87] neg_lo:[0,1] neg_hi:[0,1]
	v_xor_b32_e32 v85, 0x80000000, v88
	v_mov_b32_e32 v84, v89
	v_pk_add_f32 v[92:93], v[92:93], v[112:113] neg_lo:[0,1] neg_hi:[0,1]
	v_pk_add_f32 v[148:149], v[146:147], v[138:139]
	v_pk_add_f32 v[98:99], v[150:151], v[140:141]
	v_pk_add_f32 v[88:89], v[96:97], v[84:85]
	v_pk_add_f32 v[84:85], v[96:97], v[84:85] neg_lo:[0,1] neg_hi:[0,1]
	v_pk_mul_f32 v[96:97], v[94:95], s[28:29] op_sel:[1,0]
	v_xor_b32_e32 v113, 0x80000000, v92
	v_mov_b32_e32 v112, v93
	v_pk_fma_f32 v[94:95], v[94:95], s[26:27], v[96:97] op_sel_hi:[0,1,1]
	v_mul_f32_e32 v96, 0x3f3504f3, v149
	s_mov_b32 s29, s34
	v_pk_mul_f32 v[100:101], v[98:99], s[8:9] op_sel:[1,0]
	v_pk_add_f32 v[92:93], v[110:111], v[112:113]
	v_pk_fma_f32 v[96:97], v[148:149], s[30:31], v[96:97] op_sel_hi:[0,1,0]
	v_pk_fma_f32 v[98:99], v[98:99], s[28:29], v[100:101] op_sel_hi:[0,1,1]
	v_pk_add_f32 v[100:101], v[92:93], v[96:97]
	v_pk_add_f32 v[92:93], v[92:93], v[96:97] neg_lo:[0,1] neg_hi:[0,1]
	v_pk_add_f32 v[96:97], v[94:95], v[98:99]
	v_pk_add_f32 v[102:103], v[94:95], v[98:99] neg_lo:[0,1] neg_hi:[0,1]
	v_pk_add_f32 v[98:99], v[100:101], v[96:97]
	v_pk_add_f32 v[94:95], v[100:101], v[96:97] neg_lo:[0,1] neg_hi:[0,1]
	v_xor_b32_e32 v101, 0x80000000, v102
	v_mov_b32_e32 v100, v103
	v_pk_mul_f32 v[102:103], v[104:105], s[36:37] op_sel:[1,0]
	v_pk_add_f32 v[96:97], v[92:93], v[100:101]
	v_pk_add_f32 v[92:93], v[92:93], v[100:101] neg_lo:[0,1] neg_hi:[0,1]
	v_mul_f32_e32 v100, 0x3f3504f3, v115
	v_pk_fma_f32 v[102:103], v[104:105], s[20:21], v[102:103] op_sel_hi:[0,1,1]
	v_mul_f32_e32 v104, 0xbf3504f3, v106
	v_pk_fma_f32 v[100:101], v[114:115], s[30:31], v[100:101] op_sel_hi:[0,1,0]
	v_pk_fma_f32 v[104:105], v[106:107], s[30:31], v[104:105] op_sel:[1,0,0] op_sel_hi:[1,1,0]
	v_pk_add_f32 v[114:115], v[108:109], v[102:103]
	v_pk_add_f32 v[108:109], v[108:109], v[102:103] neg_lo:[0,1] neg_hi:[0,1]
	v_pk_add_f32 v[102:103], v[100:101], v[104:105]
	v_pk_add_f32 v[100:101], v[100:101], v[104:105] neg_lo:[0,1] neg_hi:[0,1]
	v_pk_add_f32 v[106:107], v[114:115], v[102:103]
	v_pk_add_f32 v[102:103], v[114:115], v[102:103] neg_lo:[0,1] neg_hi:[0,1]
	v_xor_b32_e32 v115, 0x80000000, v100
	v_mov_b32_e32 v114, v101
	v_pk_add_f32 v[104:105], v[108:109], v[114:115]
	v_pk_add_f32 v[100:101], v[108:109], v[114:115] neg_lo:[0,1] neg_hi:[0,1]
	v_pk_add_f32 v[108:109], v[150:151], v[140:141] neg_lo:[0,1] neg_hi:[0,1]
	v_pk_add_f32 v[110:111], v[110:111], v[112:113] neg_lo:[0,1] neg_hi:[0,1]
	v_pk_mul_f32 v[114:115], v[108:109], s[10:11] op_sel:[1,0]
	v_pk_add_f32 v[112:113], v[142:143], v[144:145] neg_lo:[0,1] neg_hi:[0,1]
	v_pk_fma_f32 v[108:109], v[108:109], s[34:35], v[114:115] op_sel_hi:[0,1,1]
	v_pk_mul_f32 v[114:115], v[112:113], s[8:9] op_sel:[1,0]
	s_nop 0
	v_pk_fma_f32 v[112:113], v[112:113], s[28:29], v[114:115] op_sel_hi:[0,1,1]
	v_pk_add_f32 v[114:115], v[146:147], v[138:139] neg_lo:[0,1] neg_hi:[0,1]
	v_pk_add_f32 v[140:141], v[112:113], v[108:109] neg_lo:[0,1] neg_hi:[0,1]
	v_mul_f32_e32 v138, 0xbf3504f3, v114
	v_pk_fma_f32 v[114:115], v[114:115], s[30:31], v[138:139] op_sel:[1,0,0] op_sel_hi:[1,1,0]
	s_nop 0
	v_pk_add_f32 v[138:139], v[110:111], v[114:115]
	v_pk_add_f32 v[114:115], v[110:111], v[114:115] neg_lo:[0,1] neg_hi:[0,1]
	v_pk_add_f32 v[110:111], v[112:113], v[108:109]
	s_nop 0
	v_pk_add_f32 v[112:113], v[138:139], v[110:111]
	v_pk_add_f32 v[108:109], v[138:139], v[110:111] neg_lo:[0,1] neg_hi:[0,1]
	v_xor_b32_e32 v139, 0x80000000, v140
	v_mov_b32_e32 v138, v141
	v_pk_add_f32 v[110:111], v[114:115], v[138:139]
	v_pk_add_f32 v[114:115], v[114:115], v[138:139] neg_lo:[0,1] neg_hi:[0,1]

.LBB0_1609:
	s_or_b64 exec, exec, s[6:7]
	s_waitcnt lgkmcnt(0)
	s_barrier
	s_and_saveexec_b64 s[6:7], vcc
	s_cbranch_execz .LBB0_1611
	ds_read_b64 v[172:173], v136
	ds_read_b64 v[174:175], v124 offset:4096
	ds_read_b64 v[176:177], v122 offset:8192
	ds_read_b64 v[178:179], v65 offset:12288
	ds_read_b64 v[180:181], v31 offset:16384
	ds_read_b64 v[182:183], v23 offset:20480
	ds_read_b64 v[184:185], v15 offset:24576
	ds_read_b64 v[186:187], v11 offset:28672
	ds_read_b64 v[188:189], v134 offset:32768
	ds_read_b64 v[190:191], v133 offset:36864
	ds_read_b64 v[192:193], v132 offset:40960
	ds_read_b64 v[194:195], v131 offset:45056
	ds_read_b64 v[196:197], v130 offset:49152
	ds_read_b64 v[198:199], v129 offset:53248
	ds_read_b64 v[200:201], v117 offset:57344
	s_waitcnt lgkmcnt(14)
	ds_read_b64 v[202:203], v116 offset:61440
	v_cvt_f32_ubyte0_e32 v108, v128
	v_mul_f32_e32 v109, 0x39800000, v108
	v_cos_f32_e32 v108, v109
	v_sin_f32_e32 v110, v109
	s_waitcnt lgkmcnt(15)
	v_mov_b32_e32 v111, v108
	v_xor_b32_e32 v109, 0x80000000, v110
	v_pk_mul_f32 v[142:143], v[110:111], v[110:111] op_sel_hi:[1,0] neg_lo:[0,1] neg_hi:[0,1]
	s_mov_b32 s29, s26
	v_pk_fma_f32 v[142:143], v[108:109], v[108:109], v[142:143] op_sel_hi:[1,0,1]
	s_mov_b32 s8, s26
	v_pk_mul_f32 v[144:145], v[110:111], v[142:143] op_sel:[0,1]
	s_mov_b32 s9, s28
	v_pk_fma_f32 v[144:145], v[108:109], v[142:143], v[144:145] op_sel_hi:[1,0,1]
	s_mov_b32 s37, s20
	v_pk_mul_f32 v[146:147], v[110:111], v[144:145] op_sel:[0,1]
	s_mov_b32 s10, s27
	v_pk_fma_f32 v[146:147], v[108:109], v[144:145], v[146:147] op_sel_hi:[1,0,1]
	s_mov_b32 s11, s34
	v_pk_mul_f32 v[148:149], v[110:111], v[146:147] op_sel:[0,1]
	s_mov_b32 s35, s28
	v_pk_fma_f32 v[148:149], v[108:109], v[146:147], v[148:149] op_sel_hi:[1,0,1]
	s_nop 0
	v_pk_mul_f32 v[150:151], v[110:111], v[148:149] op_sel:[0,1]
	s_nop 0
	v_pk_fma_f32 v[150:151], v[108:109], v[148:149], v[150:151] op_sel_hi:[1,0,1]
	s_nop 0
	v_pk_mul_f32 v[152:153], v[110:111], v[150:151] op_sel:[0,1]
	s_nop 0
	v_pk_fma_f32 v[152:153], v[108:109], v[150:151], v[152:153] op_sel_hi:[1,0,1]
	s_nop 0
	v_pk_mul_f32 v[154:155], v[110:111], v[152:153] op_sel:[0,1]
	s_nop 0
	v_pk_fma_f32 v[154:155], v[108:109], v[152:153], v[154:155] op_sel_hi:[1,0,1]
	s_nop 0
	v_pk_mul_f32 v[156:157], v[110:111], v[154:155] op_sel:[0,1]
	s_nop 0
	v_pk_fma_f32 v[156:157], v[108:109], v[154:155], v[156:157] op_sel_hi:[1,0,1]
	s_nop 0
	v_pk_mul_f32 v[158:159], v[110:111], v[156:157] op_sel:[0,1]
	s_nop 0
	v_pk_fma_f32 v[158:159], v[108:109], v[156:157], v[158:159] op_sel_hi:[1,0,1]
	s_nop 0
	v_pk_mul_f32 v[160:161], v[110:111], v[158:159] op_sel:[0,1]
	s_nop 0
	v_pk_fma_f32 v[160:161], v[108:109], v[158:159], v[160:161] op_sel_hi:[1,0,1]
	s_nop 0
	v_pk_mul_f32 v[162:163], v[110:111], v[160:161] op_sel:[0,1]
	s_nop 0
	v_pk_fma_f32 v[162:163], v[108:109], v[160:161], v[162:163] op_sel_hi:[1,0,1]
	s_nop 0
	v_pk_mul_f32 v[164:165], v[110:111], v[162:163] op_sel:[0,1]
	s_nop 0
	v_pk_fma_f32 v[164:165], v[108:109], v[162:163], v[164:165] op_sel_hi:[1,0,1]
	s_nop 0
	v_pk_mul_f32 v[166:167], v[110:111], v[164:165] op_sel:[0,1]
	s_nop 0
	v_pk_fma_f32 v[166:167], v[108:109], v[164:165], v[166:167] op_sel_hi:[1,0,1]
	s_nop 0
	v_pk_mul_f32 v[168:169], v[110:111], v[166:167] op_sel:[0,1]
	s_waitcnt lgkmcnt(14)
	v_pk_mul_f32 v[110:111], v[110:111], v[174:175] op_sel:[0,1]
	v_pk_fma_f32 v[168:169], v[108:109], v[166:167], v[168:169] op_sel_hi:[1,0,1]
	v_pk_fma_f32 v[86:87], v[108:109], v[174:175], v[110:111] op_sel_hi:[1,0,1]
	v_xor_b32_e32 v170, 0x80000000, v169
	v_mov_b32_e32 v171, v168
	s_waitcnt lgkmcnt(0)
	v_pk_mul_f32 v[170:171], v[170:171], v[202:203] op_sel:[0,1]
	s_nop 0
	v_pk_fma_f32 v[140:141], v[168:169], v[202:203], v[170:171] op_sel_hi:[1,0,1]
	v_xor_b32_e32 v168, 0x80000000, v167
	v_mov_b32_e32 v169, v166
	v_pk_mul_f32 v[168:169], v[168:169], v[200:201] op_sel:[0,1]
	s_nop 0
	v_pk_fma_f32 v[138:139], v[166:167], v[200:201], v[168:169] op_sel_hi:[1,0,1]
	v_xor_b32_e32 v166, 0x80000000, v165
	v_mov_b32_e32 v167, v164
	v_pk_mul_f32 v[166:167], v[166:167], v[198:199] op_sel:[0,1]
	s_nop 0
	v_pk_fma_f32 v[114:115], v[164:165], v[198:199], v[166:167] op_sel_hi:[1,0,1]
	v_xor_b32_e32 v164, 0x80000000, v163
	v_mov_b32_e32 v165, v162
	v_pk_mul_f32 v[164:165], v[164:165], v[196:197] op_sel:[0,1]
	s_nop 0
	v_pk_fma_f32 v[112:113], v[162:163], v[196:197], v[164:165] op_sel_hi:[1,0,1]
	v_xor_b32_e32 v162, 0x80000000, v161
	v_mov_b32_e32 v163, v160
	v_pk_mul_f32 v[162:163], v[162:163], v[194:195] op_sel:[0,1]
	s_nop 0
	v_pk_fma_f32 v[106:107], v[160:161], v[194:195], v[162:163] op_sel_hi:[1,0,1]
	v_xor_b32_e32 v160, 0x80000000, v159
	v_mov_b32_e32 v161, v158
	v_pk_mul_f32 v[160:161], v[160:161], v[192:193] op_sel:[0,1]
	s_nop 0
	v_pk_fma_f32 v[104:105], v[158:159], v[192:193], v[160:161] op_sel_hi:[1,0,1]
	v_xor_b32_e32 v158, 0x80000000, v157
	v_mov_b32_e32 v159, v156
	v_pk_mul_f32 v[158:159], v[158:159], v[190:191] op_sel:[0,1]
	s_nop 0
	v_pk_fma_f32 v[102:103], v[156:157], v[190:191], v[158:159] op_sel_hi:[1,0,1]
	v_xor_b32_e32 v156, 0x80000000, v155
	v_mov_b32_e32 v157, v154
	v_pk_mul_f32 v[156:157], v[156:157], v[188:189] op_sel:[0,1]
	s_nop 0
	v_pk_fma_f32 v[100:101], v[154:155], v[188:189], v[156:157] op_sel_hi:[1,0,1]
	v_xor_b32_e32 v154, 0x80000000, v153
	v_mov_b32_e32 v155, v152
	v_pk_mul_f32 v[154:155], v[154:155], v[186:187] op_sel:[0,1]
	v_pk_add_f32 v[108:109], v[172:173], v[100:101]
	v_pk_fma_f32 v[98:99], v[152:153], v[186:187], v[154:155] op_sel_hi:[1,0,1]
	v_xor_b32_e32 v152, 0x80000000, v151
	v_mov_b32_e32 v153, v150
	v_pk_mul_f32 v[152:153], v[152:153], v[184:185] op_sel:[0,1]
	v_pk_add_f32 v[110:111], v[172:173], v[100:101] neg_lo:[0,1] neg_hi:[0,1]
	v_pk_fma_f32 v[96:97], v[150:151], v[184:185], v[152:153] op_sel_hi:[1,0,1]
	v_xor_b32_e32 v150, 0x80000000, v149
	v_mov_b32_e32 v151, v148
	v_pk_mul_f32 v[150:151], v[150:151], v[182:183] op_sel:[0,1]
	s_nop 0
	v_pk_fma_f32 v[94:95], v[148:149], v[182:183], v[150:151] op_sel_hi:[1,0,1]
	v_xor_b32_e32 v148, 0x80000000, v147
	v_mov_b32_e32 v149, v146
	v_pk_mul_f32 v[148:149], v[148:149], v[180:181] op_sel:[0,1]
	s_nop 0
	v_pk_fma_f32 v[92:93], v[146:147], v[180:181], v[148:149] op_sel_hi:[1,0,1]
	v_xor_b32_e32 v146, 0x80000000, v145
	v_mov_b32_e32 v147, v144
	v_pk_mul_f32 v[146:147], v[146:147], v[178:179] op_sel:[0,1]
	v_pk_add_f32 v[84:85], v[92:93], v[112:113]
	v_pk_fma_f32 v[90:91], v[144:145], v[178:179], v[146:147] op_sel_hi:[1,0,1]
	v_xor_b32_e32 v144, 0x80000000, v143
	v_mov_b32_e32 v145, v142
	v_pk_mul_f32 v[144:145], v[144:145], v[176:177] op_sel:[0,1]
	v_pk_add_f32 v[100:101], v[108:109], v[84:85]
	v_pk_fma_f32 v[88:89], v[142:143], v[176:177], v[144:145] op_sel_hi:[1,0,1]
	v_pk_add_f32 v[108:109], v[108:109], v[84:85] neg_lo:[0,1] neg_hi:[0,1]
	v_pk_add_f32 v[84:85], v[86:87], v[102:103]
	v_pk_add_f32 v[142:143], v[86:87], v[102:103] neg_lo:[0,1] neg_hi:[0,1]
	v_pk_add_f32 v[86:87], v[94:95], v[114:115]
	v_pk_add_f32 v[94:95], v[94:95], v[114:115] neg_lo:[0,1] neg_hi:[0,1]
	v_pk_add_f32 v[102:103], v[84:85], v[86:87]
	v_pk_add_f32 v[114:115], v[84:85], v[86:87] neg_lo:[0,1] neg_hi:[0,1]
	v_pk_add_f32 v[84:85], v[88:89], v[104:105]
	v_pk_add_f32 v[86:87], v[96:97], v[138:139]
	v_pk_add_f32 v[146:147], v[88:89], v[104:105] neg_lo:[0,1] neg_hi:[0,1]
	v_pk_add_f32 v[88:89], v[96:97], v[138:139] neg_lo:[0,1] neg_hi:[0,1]
	v_pk_add_f32 v[96:97], v[84:85], v[86:87]
	v_pk_add_f32 v[104:105], v[84:85], v[86:87] neg_lo:[0,1] neg_hi:[0,1]
	v_pk_add_f32 v[84:85], v[90:91], v[106:107]
	v_pk_add_f32 v[86:87], v[98:99], v[140:141]
	v_xor_b32_e32 v139, 0x80000000, v88
	v_mov_b32_e32 v138, v89
	v_pk_add_f32 v[150:151], v[90:91], v[106:107] neg_lo:[0,1] neg_hi:[0,1]
	v_pk_add_f32 v[88:89], v[98:99], v[140:141] neg_lo:[0,1] neg_hi:[0,1]
	v_pk_add_f32 v[90:91], v[84:85], v[86:87]
	v_xor_b32_e32 v145, 0x80000000, v94
	v_mov_b32_e32 v144, v95
	v_pk_add_f32 v[106:107], v[84:85], v[86:87] neg_lo:[0,1] neg_hi:[0,1]
	v_xor_b32_e32 v141, 0x80000000, v88
	v_mov_b32_e32 v140, v89
	v_pk_add_f32 v[84:85], v[100:101], v[96:97]
	v_pk_add_f32 v[86:87], v[102:103], v[90:91]
	v_pk_add_f32 v[88:89], v[102:103], v[90:91] neg_lo:[0,1] neg_hi:[0,1]
	v_pk_add_f32 v[94:95], v[142:143], v[144:145]
	v_pk_add_f32 v[96:97], v[100:101], v[96:97] neg_lo:[0,1] neg_hi:[0,1]
	v_pk_add_f32 v[90:91], v[84:85], v[86:87]
	v_pk_add_f32 v[86:87], v[84:85], v[86:87] neg_lo:[0,1] neg_hi:[0,1]
	v_xor_b32_e32 v85, 0x80000000, v88
	v_mov_b32_e32 v84, v89
	v_pk_add_f32 v[92:93], v[92:93], v[112:113] neg_lo:[0,1] neg_hi:[0,1]
	v_pk_add_f32 v[148:149], v[146:147], v[138:139]
	v_pk_add_f32 v[98:99], v[150:151], v[140:141]
	v_pk_add_f32 v[88:89], v[96:97], v[84:85]
	v_pk_add_f32 v[84:85], v[96:97], v[84:85] neg_lo:[0,1] neg_hi:[0,1]
	v_pk_mul_f32 v[96:97], v[94:95], s[28:29] op_sel:[1,0]
	v_xor_b32_e32 v113, 0x80000000, v92
	v_mov_b32_e32 v112, v93
	v_pk_fma_f32 v[94:95], v[94:95], s[26:27], v[96:97] op_sel_hi:[0,1,1]
	v_mul_f32_e32 v96, 0x3f3504f3, v149
	s_mov_b32 s29, s34
	v_pk_mul_f32 v[100:101], v[98:99], s[8:9] op_sel:[1,0]
	v_pk_add_f32 v[92:93], v[110:111], v[112:113]
	v_pk_fma_f32 v[96:97], v[148:149], s[30:31], v[96:97] op_sel_hi:[0,1,0]
	v_pk_fma_f32 v[98:99], v[98:99], s[28:29], v[100:101] op_sel_hi:[0,1,1]
	v_pk_add_f32 v[100:101], v[92:93], v[96:97]
	v_pk_add_f32 v[92:93], v[92:93], v[96:97] neg_lo:[0,1] neg_hi:[0,1]
	v_pk_add_f32 v[96:97], v[94:95], v[98:99]
	v_pk_add_f32 v[102:103], v[94:95], v[98:99] neg_lo:[0,1] neg_hi:[0,1]
	v_pk_add_f32 v[98:99], v[100:101], v[96:97]
	v_pk_add_f32 v[94:95], v[100:101], v[96:97] neg_lo:[0,1] neg_hi:[0,1]
	v_xor_b32_e32 v101, 0x80000000, v102
	v_mov_b32_e32 v100, v103
	v_pk_mul_f32 v[102:103], v[104:105], s[36:37] op_sel:[1,0]
	v_pk_add_f32 v[96:97], v[92:93], v[100:101]
	v_pk_add_f32 v[92:93], v[92:93], v[100:101] neg_lo:[0,1] neg_hi:[0,1]
	v_mul_f32_e32 v100, 0x3f3504f3, v115
	v_pk_fma_f32 v[102:103], v[104:105], s[20:21], v[102:103] op_sel_hi:[0,1,1]
	v_mul_f32_e32 v104, 0xbf3504f3, v106
	v_pk_fma_f32 v[100:101], v[114:115], s[30:31], v[100:101] op_sel_hi:[0,1,0]
	v_pk_fma_f32 v[104:105], v[106:107], s[30:31], v[104:105] op_sel:[1,0,0] op_sel_hi:[1,1,0]
	v_pk_add_f32 v[114:115], v[108:109], v[102:103]
	v_pk_add_f32 v[108:109], v[108:109], v[102:103] neg_lo:[0,1] neg_hi:[0,1]
	v_pk_add_f32 v[102:103], v[100:101], v[104:105]
	v_pk_add_f32 v[100:101], v[100:101], v[104:105] neg_lo:[0,1] neg_hi:[0,1]
	v_pk_add_f32 v[106:107], v[114:115], v[102:103]
	v_pk_add_f32 v[102:103], v[114:115], v[102:103] neg_lo:[0,1] neg_hi:[0,1]
	v_xor_b32_e32 v115, 0x80000000, v100
	v_mov_b32_e32 v114, v101
	v_pk_add_f32 v[104:105], v[108:109], v[114:115]
	v_pk_add_f32 v[100:101], v[108:109], v[114:115] neg_lo:[0,1] neg_hi:[0,1]
	v_pk_add_f32 v[108:109], v[150:151], v[140:141] neg_lo:[0,1] neg_hi:[0,1]
	v_pk_add_f32 v[110:111], v[110:111], v[112:113] neg_lo:[0,1] neg_hi:[0,1]
	v_pk_mul_f32 v[114:115], v[108:109], s[10:11] op_sel:[1,0]
	v_pk_add_f32 v[112:113], v[142:143], v[144:145] neg_lo:[0,1] neg_hi:[0,1]
	v_pk_fma_f32 v[108:109], v[108:109], s[34:35], v[114:115] op_sel_hi:[0,1,1]
	v_pk_mul_f32 v[114:115], v[112:113], s[8:9] op_sel:[1,0]
	s_nop 0
	v_pk_fma_f32 v[112:113], v[112:113], s[28:29], v[114:115] op_sel_hi:[0,1,1]
	v_pk_add_f32 v[114:115], v[146:147], v[138:139] neg_lo:[0,1] neg_hi:[0,1]
	v_pk_add_f32 v[140:141], v[112:113], v[108:109] neg_lo:[0,1] neg_hi:[0,1]
	v_mul_f32_e32 v136, 0xbf3504f3, v114
	v_pk_fma_f32 v[114:115], v[114:115], s[30:31], v[136:137] op_sel:[1,0,0] op_sel_hi:[1,1,0]
	s_nop 0
	v_pk_add_f32 v[138:139], v[110:111], v[114:115]
	v_pk_add_f32 v[114:115], v[110:111], v[114:115] neg_lo:[0,1] neg_hi:[0,1]
	v_pk_add_f32 v[110:111], v[112:113], v[108:109]
	s_nop 0
	v_pk_add_f32 v[112:113], v[138:139], v[110:111]
	v_pk_add_f32 v[108:109], v[138:139], v[110:111] neg_lo:[0,1] neg_hi:[0,1]
	v_xor_b32_e32 v139, 0x80000000, v140
	v_mov_b32_e32 v138, v141
	v_pk_add_f32 v[110:111], v[114:115], v[138:139]
	v_pk_add_f32 v[114:115], v[114:115], v[138:139] neg_lo:[0,1] neg_hi:[0,1]

.LBB0_1613:
	s_or_b64 exec, exec, s[6:7]
	s_waitcnt lgkmcnt(0)
	s_barrier
	s_and_saveexec_b64 s[6:7], vcc
	s_cbranch_execz .LBB0_1615
	ds_read_b64 v[176:177], v134 offset:32768
	v_cvt_f32_i32_e32 v86, v128
	v_lshlrev_b32_e32 v87, 3, v127
	v_add3_u32 v92, 0, v87, v135
	ds_read_b64 v[178:179], v92
	ds_read_b64 v[180:181], v133 offset:36864
	ds_read_b64 v[182:183], v124 offset:4096
	ds_read_b64 v[184:185], v132 offset:40960
	ds_read_b64 v[186:187], v122 offset:8192
	ds_read_b64 v[188:189], v131 offset:45056
	ds_read_b64 v[190:191], v65 offset:12288
	ds_read_b64 v[192:193], v130 offset:49152
	ds_read_b64 v[194:195], v31 offset:16384
	ds_read_b64 v[196:197], v129 offset:53248
	ds_read_b64 v[198:199], v23 offset:20480
	ds_read_b64 v[172:173], v117 offset:57344
	ds_read_b64 v[174:175], v15 offset:24576
	v_mul_f32_e32 v88, 0x39000000, v86
	v_sin_f32_e32 v86, v88
	v_cos_f32_e32 v88, v88
	v_cvt_f32_i32_e32 v67, v67
	v_xor_b32_e32 v89, 0x80000000, v86
	v_mov_b32_e32 v87, v88
	s_waitcnt lgkmcnt(14)
	s_waitcnt lgkmcnt(13)
	v_pk_mul_f32 v[86:87], v[86:87], v[176:177] op_sel:[0,1]
	v_cvt_f32_i32_e32 v63, v63
	v_pk_fma_f32 v[84:85], v[88:89], v[176:177], v[86:87] op_sel_hi:[1,0,1]
	v_cvt_f32_i32_e32 v88, v126
	s_waitcnt lgkmcnt(12)
	v_pk_add_f32 v[86:87], v[178:179], v[84:85]
	v_pk_add_f32 v[84:85], v[178:179], v[84:85] neg_lo:[0,1] neg_hi:[0,1]
	ds_write_b64 v92, v[86:87]
	ds_write_b64 v134, v[84:85] offset:32768
	v_mul_f32_e32 v85, 0x39000000, v88
	v_cos_f32_e32 v84, v85
	v_sin_f32_e32 v86, v85
	v_cvt_f32_i32_e32 v27, v27
	v_mov_b32_e32 v87, v84
	v_xor_b32_e32 v85, 0x80000000, v86
	s_waitcnt lgkmcnt(13)
	v_pk_mul_f32 v[86:87], v[86:87], v[180:181] op_sel:[0,1]
	v_cvt_f32_i32_e32 v19, v19
	v_pk_fma_f32 v[84:85], v[84:85], v[180:181], v[86:87] op_sel_hi:[1,0,1]
	v_cvt_f32_i32_e32 v88, v125
	s_waitcnt lgkmcnt(12)
	v_pk_add_f32 v[86:87], v[182:183], v[84:85]
	v_pk_add_f32 v[84:85], v[182:183], v[84:85] neg_lo:[0,1] neg_hi:[0,1]
	ds_write_b64 v124, v[86:87] offset:4096
	ds_write_b64 v133, v[84:85] offset:36864
	v_mul_f32_e32 v85, 0x39000000, v88
	v_cos_f32_e32 v84, v85
	v_sin_f32_e32 v86, v85
	s_nop 0
	v_mov_b32_e32 v87, v84
	v_xor_b32_e32 v85, 0x80000000, v86
	s_waitcnt lgkmcnt(13)
	v_pk_mul_f32 v[86:87], v[86:87], v[184:185] op_sel:[0,1]
	s_nop 0
	v_pk_fma_f32 v[84:85], v[84:85], v[184:185], v[86:87] op_sel_hi:[1,0,1]
	v_cvt_f32_i32_e32 v88, v123
	s_waitcnt lgkmcnt(12)
	v_pk_add_f32 v[86:87], v[186:187], v[84:85]
	v_pk_add_f32 v[84:85], v[186:187], v[84:85] neg_lo:[0,1] neg_hi:[0,1]
	ds_write_b64 v122, v[86:87] offset:8192
	ds_write_b64 v132, v[84:85] offset:40960
	v_mul_f32_e32 v85, 0x39000000, v88
	ds_read_b64 v[88:89], v116 offset:61440
	s_waitcnt lgkmcnt(14)
	ds_read_b64 v[90:91], v11 offset:28672
	v_cos_f32_e32 v84, v85
	v_sin_f32_e32 v86, v85
	s_nop 0
	v_mov_b32_e32 v87, v84
	v_xor_b32_e32 v85, 0x80000000, v86
	s_nop 0
	v_pk_mul_f32 v[86:87], v[86:87], v[188:189] op_sel:[0,1]
	s_nop 0
	v_pk_fma_f32 v[84:85], v[84:85], v[188:189], v[86:87] op_sel_hi:[1,0,1]
	s_waitcnt lgkmcnt(14)
	v_pk_add_f32 v[86:87], v[190:191], v[84:85]
	ds_write_b64 v65, v[86:87] offset:12288
	v_pk_add_f32 v[84:85], v[190:191], v[84:85] neg_lo:[0,1] neg_hi:[0,1]
	v_mul_f32_e32 v65, 0x39000000, v67
	s_waitcnt lgkmcnt(14)
	ds_write_b64 v131, v[84:85] offset:45056
	v_cos_f32_e32 v84, v65
	v_sin_f32_e32 v86, v65
	s_nop 0
	v_mov_b32_e32 v87, v84
	v_xor_b32_e32 v85, 0x80000000, v86
	s_nop 0
	v_pk_mul_f32 v[86:87], v[86:87], v[192:193] op_sel:[0,1]
	s_nop 0
	v_pk_fma_f32 v[84:85], v[84:85], v[192:193], v[86:87] op_sel_hi:[1,0,1]
	s_waitcnt lgkmcnt(14)
	v_pk_add_f32 v[86:87], v[194:195], v[84:85]
	ds_write_b64 v31, v[86:87] offset:16384
	v_pk_add_f32 v[84:85], v[194:195], v[84:85] neg_lo:[0,1] neg_hi:[0,1]
	v_mul_f32_e32 v31, 0x39000000, v63
	s_waitcnt lgkmcnt(14)
	ds_write_b64 v130, v[84:85] offset:49152
	v_cos_f32_e32 v84, v31
	v_sin_f32_e32 v86, v31
	s_nop 0
	v_mov_b32_e32 v87, v84
	v_xor_b32_e32 v85, 0x80000000, v86
	s_nop 0
	v_pk_mul_f32 v[86:87], v[86:87], v[196:197] op_sel:[0,1]
	s_nop 0
	v_pk_fma_f32 v[84:85], v[84:85], v[196:197], v[86:87] op_sel_hi:[1,0,1]
	s_waitcnt lgkmcnt(14)
	v_pk_add_f32 v[86:87], v[198:199], v[84:85]
	ds_write_b64 v23, v[86:87] offset:20480
	v_pk_add_f32 v[84:85], v[198:199], v[84:85] neg_lo:[0,1] neg_hi:[0,1]
	v_mul_f32_e32 v23, 0x39000000, v27
	s_waitcnt lgkmcnt(14)
	ds_write_b64 v129, v[84:85] offset:53248
	v_cos_f32_e32 v84, v23
	v_sin_f32_e32 v86, v23
	s_nop 0
	v_mov_b32_e32 v87, v84
	v_xor_b32_e32 v85, 0x80000000, v86
	s_nop 0
	v_pk_mul_f32 v[86:87], v[86:87], v[172:173] op_sel:[0,1]
	s_nop 0
	v_pk_fma_f32 v[84:85], v[84:85], v[172:173], v[86:87] op_sel_hi:[1,0,1]
	s_waitcnt lgkmcnt(14)
	v_pk_add_f32 v[86:87], v[174:175], v[84:85]
	ds_write_b64 v15, v[86:87] offset:24576
	v_pk_add_f32 v[84:85], v[174:175], v[84:85] neg_lo:[0,1] neg_hi:[0,1]
	v_mul_f32_e32 v15, 0x39000000, v19
	s_waitcnt lgkmcnt(14)
	ds_write_b64 v117, v[84:85] offset:57344
	v_cos_f32_e32 v84, v15
	v_sin_f32_e32 v86, v15
	s_nop 0
	v_mov_b32_e32 v87, v84
	v_xor_b32_e32 v85, 0x80000000, v86
	s_waitcnt lgkmcnt(9)
	v_pk_mul_f32 v[86:87], v[86:87], v[88:89] op_sel:[0,1]
	s_nop 0
	v_pk_fma_f32 v[84:85], v[84:85], v[88:89], v[86:87] op_sel_hi:[1,0,1]
	s_waitcnt lgkmcnt(8)
	v_pk_add_f32 v[86:87], v[90:91], v[84:85]
	v_pk_add_f32 v[84:85], v[90:91], v[84:85] neg_lo:[0,1] neg_hi:[0,1]
	ds_write_b64 v11, v[86:87] offset:28672
	ds_write_b64 v116, v[84:85] offset:61440

.LBB0_1622:
	s_or_b64 exec, exec, s[6:7]
	s_waitcnt lgkmcnt(0)
	s_barrier
	s_and_saveexec_b64 s[6:7], vcc
	s_cbranch_execz .LBB0_1624
	ds_read_b64 v[202:203], v31 offset:61440
	ds_read_b64 v[174:175], v65 offset:57344
	ds_read_b64 v[176:177], v123 offset:53248
	ds_read_b64 v[178:179], v126 offset:49152
	ds_read_b64 v[180:181], v129 offset:45056
	ds_read_b64 v[182:183], v131 offset:40960
	ds_read_b64 v[184:185], v136
	ds_read_b64 v[186:187], v127 offset:4096
	ds_read_b64 v[188:189], v124 offset:8192
	ds_read_b64 v[190:191], v67 offset:12288
	ds_read_b64 v[192:193], v59 offset:16384
	ds_read_b64 v[194:195], v23 offset:20480
	ds_read_b64 v[196:197], v15 offset:24576
	ds_read_b64 v[198:199], v11 offset:28672
	ds_read_b64 v[200:201], v135 offset:32768
	s_waitcnt lgkmcnt(14)
	ds_read_b64 v[172:173], v134 offset:36864
	v_and_b32_e32 v84, 15, v132
	v_cvt_f32_ubyte0_e32 v84, v84
	v_mul_f32_e32 v84, 0x3b800000, v84
	v_cos_f32_e32 v98, v84
	v_sin_f32_e32 v99, v84
	s_mov_b32 s10, s27
	v_mov_b32_e32 v101, v98
	v_xor_b32_e32 v100, 0x80000000, v99
	v_mov_b32_e32 v84, v99
	v_pk_mul_f32 v[84:85], v[100:101], v[84:85] op_sel_hi:[1,0]
	s_mov_b32 s11, s26
	v_pk_fma_f32 v[106:107], v[98:99], v[98:99], v[84:85] op_sel_hi:[1,0,1]
	s_mov_b32 s8, s26
	v_pk_mul_f32 v[84:85], v[100:101], v[106:107] op_sel:[0,1]
	s_mov_b32 s9, s28
	v_pk_fma_f32 v[110:111], v[98:99], v[106:107], v[84:85] op_sel_hi:[1,0,1]
	s_mov_b32 s35, s28
	v_pk_mul_f32 v[84:85], v[100:101], v[110:111] op_sel:[0,1]
	s_mov_b32 s29, s26
	v_pk_fma_f32 v[112:113], v[98:99], v[110:111], v[84:85] op_sel_hi:[1,0,1]
	s_mov_b32 s12, s21
	v_pk_mul_f32 v[84:85], v[100:101], v[112:113] op_sel:[0,1]
	s_mov_b32 s13, s20
	v_pk_fma_f32 v[114:115], v[98:99], v[112:113], v[84:85] op_sel_hi:[1,0,1]
	s_nop 0
	v_pk_mul_f32 v[84:85], v[100:101], v[114:115] op_sel:[0,1]
	s_nop 0
	v_pk_fma_f32 v[116:117], v[98:99], v[114:115], v[84:85] op_sel_hi:[1,0,1]
	s_nop 0
	v_pk_mul_f32 v[84:85], v[100:101], v[116:117] op_sel:[0,1]
	s_nop 0
	v_pk_fma_f32 v[138:139], v[98:99], v[116:117], v[84:85] op_sel_hi:[1,0,1]
	s_nop 0
	v_pk_mul_f32 v[84:85], v[100:101], v[138:139] op_sel:[0,1]
	s_nop 0
	v_pk_fma_f32 v[102:103], v[98:99], v[138:139], v[84:85] op_sel_hi:[1,0,1]
	s_nop 0
	v_pk_mul_f32 v[84:85], v[100:101], v[102:103] op_sel:[0,1]
	s_nop 0
	v_pk_fma_f32 v[86:87], v[98:99], v[102:103], v[84:85] op_sel_hi:[1,0,1]
	s_nop 0
	v_pk_mul_f32 v[84:85], v[100:101], v[86:87] op_sel:[0,1]
	s_nop 0
	v_pk_fma_f32 v[96:97], v[98:99], v[86:87], v[84:85] op_sel_hi:[1,0,1]
	s_nop 0
	v_pk_mul_f32 v[84:85], v[100:101], v[96:97] op_sel:[0,1]
	s_nop 0
	v_pk_fma_f32 v[92:93], v[98:99], v[96:97], v[84:85] op_sel_hi:[1,0,1]
	s_nop 0
	v_pk_mul_f32 v[84:85], v[100:101], v[92:93] op_sel:[0,1]
	s_nop 0
	v_pk_fma_f32 v[94:95], v[98:99], v[92:93], v[84:85] op_sel_hi:[1,0,1]
	s_nop 0
	v_pk_mul_f32 v[84:85], v[100:101], v[94:95] op_sel:[0,1]
	s_nop 0
	v_pk_fma_f32 v[90:91], v[98:99], v[94:95], v[84:85] op_sel_hi:[1,0,1]
	s_nop 0
	v_pk_mul_f32 v[84:85], v[100:101], v[90:91] op_sel:[0,1]
	s_nop 0
	v_pk_fma_f32 v[88:89], v[98:99], v[90:91], v[84:85] op_sel_hi:[1,0,1]
	s_nop 0
	v_pk_mul_f32 v[84:85], v[100:101], v[88:89] op_sel:[0,1]
	s_nop 0
	v_pk_fma_f32 v[84:85], v[98:99], v[88:89], v[84:85] op_sel_hi:[1,0,1]
	s_nop 0
	v_xor_b32_e32 v108, 0x80000000, v85
	v_mov_b32_e32 v109, v84
	s_waitcnt lgkmcnt(15)
	s_nop 0
	v_pk_mul_f32 v[108:109], v[108:109], v[202:203] op_sel:[0,1]
	s_nop 0
	v_pk_fma_f32 v[84:85], v[84:85], v[202:203], v[108:109] op_sel_hi:[1,0,1]
	v_xor_b32_e32 v108, 0x80000000, v89
	v_mov_b32_e32 v109, v88
	s_waitcnt lgkmcnt(14)
	v_pk_mul_f32 v[108:109], v[108:109], v[174:175] op_sel:[0,1]
	s_nop 0
	v_pk_fma_f32 v[88:89], v[88:89], v[174:175], v[108:109] op_sel_hi:[1,0,1]
	v_xor_b32_e32 v108, 0x80000000, v91
	v_mov_b32_e32 v109, v90
	s_waitcnt lgkmcnt(13)
	v_pk_mul_f32 v[108:109], v[108:109], v[176:177] op_sel:[0,1]
	s_nop 0
	v_pk_fma_f32 v[90:91], v[90:91], v[176:177], v[108:109] op_sel_hi:[1,0,1]
	v_xor_b32_e32 v108, 0x80000000, v95
	v_mov_b32_e32 v109, v94
	s_waitcnt lgkmcnt(12)
	v_pk_mul_f32 v[108:109], v[108:109], v[178:179] op_sel:[0,1]
	s_nop 0
	v_pk_fma_f32 v[94:95], v[94:95], v[178:179], v[108:109] op_sel_hi:[1,0,1]
	v_xor_b32_e32 v108, 0x80000000, v93
	v_mov_b32_e32 v109, v92
	s_waitcnt lgkmcnt(11)
	v_pk_mul_f32 v[108:109], v[108:109], v[180:181] op_sel:[0,1]
	s_nop 0
	v_pk_fma_f32 v[92:93], v[92:93], v[180:181], v[108:109] op_sel_hi:[1,0,1]
	v_xor_b32_e32 v108, 0x80000000, v97
	v_mov_b32_e32 v109, v96
	s_waitcnt lgkmcnt(10)
	v_pk_mul_f32 v[108:109], v[108:109], v[182:183] op_sel:[0,1]
	s_nop 0
	v_pk_fma_f32 v[96:97], v[96:97], v[182:183], v[108:109] op_sel_hi:[1,0,1]
	s_waitcnt lgkmcnt(8)
	v_pk_mul_f32 v[100:101], v[100:101], v[186:187] op_sel:[0,1]
	s_nop 0
	v_pk_fma_f32 v[104:105], v[98:99], v[186:187], v[100:101] op_sel_hi:[1,0,1]
	v_xor_b32_e32 v100, 0x80000000, v107
	v_mov_b32_e32 v101, v106
	s_waitcnt lgkmcnt(7)
	v_pk_mul_f32 v[100:101], v[100:101], v[188:189] op_sel:[0,1]
	s_nop 0
	v_pk_fma_f32 v[100:101], v[106:107], v[188:189], v[100:101] op_sel_hi:[1,0,1]
	v_xor_b32_e32 v106, 0x80000000, v111
	v_mov_b32_e32 v107, v110
	v_pk_add_f32 v[144:145], v[100:101], v[96:97] neg_lo:[0,1] neg_hi:[0,1]
	s_waitcnt lgkmcnt(6)
	v_pk_mul_f32 v[106:107], v[106:107], v[190:191] op_sel:[0,1]
	s_nop 0
	v_pk_fma_f32 v[98:99], v[110:111], v[190:191], v[106:107] op_sel_hi:[1,0,1]
	v_xor_b32_e32 v110, 0x80000000, v113
	v_mov_b32_e32 v111, v112
	v_pk_add_f32 v[148:149], v[98:99], v[92:93] neg_lo:[0,1] neg_hi:[0,1]
	s_waitcnt lgkmcnt(5)
	v_pk_mul_f32 v[110:111], v[110:111], v[192:193] op_sel:[0,1]
	s_nop 0
	v_pk_fma_f32 v[110:111], v[112:113], v[192:193], v[110:111] op_sel_hi:[1,0,1]
	v_xor_b32_e32 v112, 0x80000000, v115
	v_mov_b32_e32 v113, v114
	s_waitcnt lgkmcnt(4)
	v_pk_mul_f32 v[112:113], v[112:113], v[194:195] op_sel:[0,1]
	s_nop 0
	v_pk_fma_f32 v[112:113], v[114:115], v[194:195], v[112:113] op_sel_hi:[1,0,1]
	v_xor_b32_e32 v114, 0x80000000, v117
	v_mov_b32_e32 v115, v116
	s_waitcnt lgkmcnt(3)
	v_pk_mul_f32 v[114:115], v[114:115], v[196:197] op_sel:[0,1]
	s_nop 0
	v_pk_fma_f32 v[114:115], v[116:117], v[196:197], v[114:115] op_sel_hi:[1,0,1]
	v_xor_b32_e32 v116, 0x80000000, v139
	v_mov_b32_e32 v117, v138
	s_waitcnt lgkmcnt(2)
	v_pk_mul_f32 v[116:117], v[116:117], v[198:199] op_sel:[0,1]
	s_nop 0
	v_pk_fma_f32 v[106:107], v[138:139], v[198:199], v[116:117] op_sel_hi:[1,0,1]
	v_xor_b32_e32 v138, 0x80000000, v103
	v_mov_b32_e32 v139, v102
	s_waitcnt lgkmcnt(1)
	v_pk_mul_f32 v[138:139], v[138:139], v[200:201] op_sel:[0,1]
	s_nop 0
	v_pk_fma_f32 v[102:103], v[102:103], v[200:201], v[138:139] op_sel_hi:[1,0,1]
	v_xor_b32_e32 v138, 0x80000000, v87
	v_mov_b32_e32 v139, v86
	s_waitcnt lgkmcnt(0)
	v_pk_mul_f32 v[138:139], v[138:139], v[172:173] op_sel:[0,1]
	s_nop 0
	v_pk_fma_f32 v[86:87], v[86:87], v[172:173], v[138:139] op_sel_hi:[1,0,1]
	v_pk_add_f32 v[116:117], v[184:185], v[102:103]
	v_pk_add_f32 v[138:139], v[104:105], v[86:87]
	v_pk_add_f32 v[140:141], v[104:105], v[86:87] neg_lo:[0,1] neg_hi:[0,1]
	v_pk_add_f32 v[86:87], v[90:91], v[112:113]
	v_pk_add_f32 v[90:91], v[112:113], v[90:91] neg_lo:[0,1] neg_hi:[0,1]
	v_pk_add_f32 v[104:105], v[86:87], v[138:139]
	v_pk_add_f32 v[112:113], v[138:139], v[86:87] neg_lo:[0,1] neg_hi:[0,1]
	v_xor_b32_e32 v139, 0x80000000, v90
	v_mov_b32_e32 v138, v91
	v_pk_add_f32 v[86:87], v[96:97], v[100:101]
	v_pk_add_f32 v[90:91], v[88:89], v[114:115]
	v_pk_add_f32 v[88:89], v[114:115], v[88:89] neg_lo:[0,1] neg_hi:[0,1]
	v_pk_add_f32 v[96:97], v[86:87], v[90:91]
	v_pk_add_f32 v[100:101], v[86:87], v[90:91] neg_lo:[0,1] neg_hi:[0,1]
	v_xor_b32_e32 v115, 0x80000000, v88
	v_mov_b32_e32 v114, v89
	v_pk_add_f32 v[86:87], v[92:93], v[98:99]
	v_pk_add_f32 v[88:89], v[84:85], v[106:107]
	v_pk_add_f32 v[108:109], v[184:185], v[102:103] neg_lo:[0,1] neg_hi:[0,1]
	v_pk_add_f32 v[102:103], v[94:95], v[110:111]
	v_pk_add_f32 v[90:91], v[86:87], v[88:89]
	v_pk_add_f32 v[94:95], v[110:111], v[94:95] neg_lo:[0,1] neg_hi:[0,1]
	v_pk_add_f32 v[110:111], v[102:103], v[116:117]
	v_pk_add_f32 v[84:85], v[106:107], v[84:85] neg_lo:[0,1] neg_hi:[0,1]
	v_pk_add_f32 v[106:107], v[86:87], v[88:89] neg_lo:[0,1] neg_hi:[0,1]
	v_pk_add_f32 v[86:87], v[90:91], v[104:105]
	v_pk_add_f32 v[90:91], v[104:105], v[90:91] neg_lo:[0,1] neg_hi:[0,1]
	v_pk_add_f32 v[142:143], v[140:141], v[138:139] neg_lo:[0,1] neg_hi:[0,1]
	v_xor_b32_e32 v151, 0x80000000, v84
	v_mov_b32_e32 v150, v85
	v_pk_add_f32 v[84:85], v[96:97], v[110:111]
	v_pk_add_f32 v[96:97], v[110:111], v[96:97] neg_lo:[0,1] neg_hi:[0,1]
	v_xor_b32_e32 v99, 0x80000000, v90
	v_mov_b32_e32 v98, v91
	v_pk_add_f32 v[146:147], v[144:145], v[114:115] neg_lo:[0,1] neg_hi:[0,1]
	v_pk_add_f32 v[92:93], v[148:149], v[150:151] neg_lo:[0,1] neg_hi:[0,1]
	v_pk_add_f32 v[88:89], v[84:85], v[86:87]
	v_pk_add_f32 v[86:87], v[84:85], v[86:87] neg_lo:[0,1] neg_hi:[0,1]
	v_pk_add_f32 v[84:85], v[96:97], v[98:99]
	v_pk_add_f32 v[90:91], v[96:97], v[98:99] neg_lo:[0,1] neg_hi:[0,1]
	v_pk_mul_f32 v[96:97], v[142:143], s[10:11] op_sel:[1,0]
	v_pk_add_f32 v[102:103], v[116:117], v[102:103] neg_lo:[0,1] neg_hi:[0,1]
	v_xor_b32_e32 v117, 0x80000000, v94
	v_mov_b32_e32 v116, v95
	v_pk_fma_f32 v[96:97], v[142:143], s[8:9], v[96:97] op_sel_hi:[0,1,1]
	v_mul_f32_e32 v98, 0x3f3504f3, v146
	s_mov_b32 s8, s31
	s_mov_b32 s9, s30
	v_pk_mul_f32 v[104:105], v[92:93], s[34:35] op_sel:[1,0]
	v_pk_add_f32 v[94:95], v[108:109], v[116:117] neg_lo:[0,1] neg_hi:[0,1]
	v_pk_fma_f32 v[98:99], v[146:147], s[8:9], v[98:99] op_sel:[1,0,0] op_sel_hi:[1,1,0]
	v_pk_fma_f32 v[92:93], v[92:93], s[28:29], v[104:105] op_sel_hi:[0,1,1]
	v_pk_add_f32 v[104:105], v[94:95], v[98:99]
	v_pk_add_f32 v[98:99], v[94:95], v[98:99] neg_lo:[0,1] neg_hi:[0,1]
	v_pk_add_f32 v[94:95], v[96:97], v[92:93]
	v_pk_add_f32 v[92:93], v[96:97], v[92:93] neg_lo:[0,1] neg_hi:[0,1]
	v_pk_add_f32 v[96:97], v[104:105], v[94:95]
	v_pk_add_f32 v[94:95], v[104:105], v[94:95] neg_lo:[0,1] neg_hi:[0,1]
	v_xor_b32_e32 v105, 0x80000000, v92
	v_mov_b32_e32 v104, v93
	s_mov_b32 s10, s20
	s_mov_b32 s11, s36
	v_pk_mul_f32 v[110:111], v[100:101], s[12:13] op_sel:[1,0]
	v_pk_add_f32 v[92:93], v[98:99], v[104:105]
	v_pk_add_f32 v[98:99], v[98:99], v[104:105] neg_lo:[0,1] neg_hi:[0,1]
	v_mul_f32_e32 v104, 0x3f3504f3, v112
	v_pk_fma_f32 v[100:101], v[100:101], s[10:11], v[110:111] op_sel_hi:[0,1,1]
	v_mul_f32_e32 v110, 0xbf3504f3, v107
	v_pk_fma_f32 v[104:105], v[112:113], s[8:9], v[104:105] op_sel:[1,0,0] op_sel_hi:[1,1,0]
	v_pk_fma_f32 v[106:107], v[106:107], s[8:9], v[110:111] op_sel_hi:[0,1,0]
	v_pk_add_f32 v[110:111], v[102:103], v[100:101]
	v_pk_add_f32 v[112:113], v[102:103], v[100:101] neg_lo:[0,1] neg_hi:[0,1]
	v_pk_add_f32 v[100:101], v[106:107], v[104:105]
	v_pk_add_f32 v[106:107], v[104:105], v[106:107] neg_lo:[0,1] neg_hi:[0,1]
	v_pk_add_f32 v[104:105], v[110:111], v[100:101]
	v_pk_add_f32 v[102:103], v[110:111], v[100:101] neg_lo:[0,1] neg_hi:[0,1]
	v_xor_b32_e32 v111, 0x80000000, v106
	v_mov_b32_e32 v110, v107
	v_pk_add_f32 v[100:101], v[112:113], v[110:111]
	v_pk_add_f32 v[106:107], v[112:113], v[110:111] neg_lo:[0,1] neg_hi:[0,1]
	v_pk_add_f32 v[110:111], v[148:149], v[150:151]
	s_mov_b32 s12, s28
	s_mov_b32 s13, s34
	s_mov_b32 s10, s34
	s_mov_b32 s11, s27
	v_pk_mul_f32 v[112:113], v[110:111], s[12:13] op_sel:[1,0]
	v_pk_add_f32 v[108:109], v[116:117], v[108:109]
	v_pk_fma_f32 v[110:111], v[110:111], s[10:11], v[112:113] op_sel_hi:[0,1,1]
	v_pk_add_f32 v[112:113], v[138:139], v[140:141]
	v_pk_add_f32 v[114:115], v[144:145], v[114:115]
	v_pk_mul_f32 v[116:117], v[112:113], s[34:35] op_sel:[1,0]
	s_nop 0
	v_pk_fma_f32 v[112:113], v[112:113], s[28:29], v[116:117] op_sel_hi:[0,1,1]
	v_mul_f32_e32 v116, 0xbf3504f3, v115
	v_pk_fma_f32 v[114:115], v[114:115], s[8:9], v[116:117] op_sel_hi:[0,1,0]
	v_pk_add_f32 v[116:117], v[108:109], v[114:115]
	v_pk_add_f32 v[138:139], v[108:109], v[114:115] neg_lo:[0,1] neg_hi:[0,1]
	v_pk_add_f32 v[108:109], v[112:113], v[110:111]
	v_pk_add_f32 v[112:113], v[112:113], v[110:111] neg_lo:[0,1] neg_hi:[0,1]
	v_pk_add_f32 v[110:111], v[116:117], v[108:109]
	v_pk_add_f32 v[108:109], v[116:117], v[108:109] neg_lo:[0,1] neg_hi:[0,1]
	v_xor_b32_e32 v117, 0x80000000, v112
	v_mov_b32_e32 v116, v113
	v_pk_add_f32 v[114:115], v[138:139], v[116:117]
	v_pk_add_f32 v[112:113], v[138:139], v[116:117] neg_lo:[0,1] neg_hi:[0,1]

.LBB0_1626:
	s_or_b64 exec, exec, s[6:7]
	s_waitcnt lgkmcnt(0)
	s_barrier
	s_and_saveexec_b64 s[6:7], vcc
	s_cbranch_execz .LBB0_1628
	ds_read_b64 v[202:203], v31 offset:61440
	ds_read_b64 v[174:175], v65 offset:57344
	ds_read_b64 v[176:177], v123 offset:53248
	ds_read_b64 v[178:179], v126 offset:49152
	ds_read_b64 v[180:181], v129 offset:45056
	ds_read_b64 v[182:183], v131 offset:40960
	ds_read_b64 v[184:185], v136
	ds_read_b64 v[186:187], v127 offset:4096
	ds_read_b64 v[188:189], v124 offset:8192
	ds_read_b64 v[190:191], v67 offset:12288
	ds_read_b64 v[192:193], v59 offset:16384
	ds_read_b64 v[194:195], v23 offset:20480
	ds_read_b64 v[196:197], v15 offset:24576
	ds_read_b64 v[198:199], v11 offset:28672
	ds_read_b64 v[200:201], v135 offset:32768
	s_waitcnt lgkmcnt(14)
	ds_read_b64 v[172:173], v134 offset:36864
	v_cvt_f32_ubyte0_e32 v84, v132
	v_mul_f32_e32 v84, 0x39800000, v84
	v_cos_f32_e32 v98, v84
	v_sin_f32_e32 v99, v84
	s_mov_b32 s10, s27
	v_mov_b32_e32 v101, v98
	v_xor_b32_e32 v100, 0x80000000, v99
	v_mov_b32_e32 v84, v99
	v_pk_mul_f32 v[84:85], v[100:101], v[84:85] op_sel_hi:[1,0]
	s_mov_b32 s11, s26
	v_pk_fma_f32 v[106:107], v[98:99], v[98:99], v[84:85] op_sel_hi:[1,0,1]
	s_mov_b32 s8, s26
	v_pk_mul_f32 v[84:85], v[100:101], v[106:107] op_sel:[0,1]
	s_mov_b32 s9, s28
	v_pk_fma_f32 v[110:111], v[98:99], v[106:107], v[84:85] op_sel_hi:[1,0,1]
	s_mov_b32 s35, s28
	v_pk_mul_f32 v[84:85], v[100:101], v[110:111] op_sel:[0,1]
	s_mov_b32 s29, s26
	v_pk_fma_f32 v[112:113], v[98:99], v[110:111], v[84:85] op_sel_hi:[1,0,1]
	s_mov_b32 s12, s21
	v_pk_mul_f32 v[84:85], v[100:101], v[112:113] op_sel:[0,1]
	s_mov_b32 s13, s20
	v_pk_fma_f32 v[114:115], v[98:99], v[112:113], v[84:85] op_sel_hi:[1,0,1]
	s_nop 0
	v_pk_mul_f32 v[84:85], v[100:101], v[114:115] op_sel:[0,1]
	s_nop 0
	v_pk_fma_f32 v[138:139], v[98:99], v[114:115], v[84:85] op_sel_hi:[1,0,1]
	s_nop 0
	v_pk_mul_f32 v[84:85], v[100:101], v[138:139] op_sel:[0,1]
	s_nop 0
	v_pk_fma_f32 v[140:141], v[98:99], v[138:139], v[84:85] op_sel_hi:[1,0,1]
	s_nop 0
	v_pk_mul_f32 v[84:85], v[100:101], v[140:141] op_sel:[0,1]
	v_mov_b32_e32 v137, v140
	v_pk_fma_f32 v[102:103], v[98:99], v[140:141], v[84:85] op_sel_hi:[1,0,1]
	s_nop 0
	v_pk_mul_f32 v[84:85], v[100:101], v[102:103] op_sel:[0,1]
	s_nop 0
	v_pk_fma_f32 v[86:87], v[98:99], v[102:103], v[84:85] op_sel_hi:[1,0,1]
	s_nop 0
	v_pk_mul_f32 v[84:85], v[100:101], v[86:87] op_sel:[0,1]
	s_nop 0
	v_pk_fma_f32 v[96:97], v[98:99], v[86:87], v[84:85] op_sel_hi:[1,0,1]
	s_nop 0
	v_pk_mul_f32 v[84:85], v[100:101], v[96:97] op_sel:[0,1]
	s_nop 0
	v_pk_fma_f32 v[92:93], v[98:99], v[96:97], v[84:85] op_sel_hi:[1,0,1]
	s_nop 0
	v_pk_mul_f32 v[84:85], v[100:101], v[92:93] op_sel:[0,1]
	s_nop 0
	v_pk_fma_f32 v[94:95], v[98:99], v[92:93], v[84:85] op_sel_hi:[1,0,1]
	s_nop 0
	v_pk_mul_f32 v[84:85], v[100:101], v[94:95] op_sel:[0,1]
	s_nop 0
	v_pk_fma_f32 v[90:91], v[98:99], v[94:95], v[84:85] op_sel_hi:[1,0,1]
	s_nop 0
	v_pk_mul_f32 v[84:85], v[100:101], v[90:91] op_sel:[0,1]
	s_nop 0
	v_pk_fma_f32 v[88:89], v[98:99], v[90:91], v[84:85] op_sel_hi:[1,0,1]
	s_nop 0
	v_pk_mul_f32 v[84:85], v[100:101], v[88:89] op_sel:[0,1]
	s_nop 0
	v_pk_fma_f32 v[84:85], v[98:99], v[88:89], v[84:85] op_sel_hi:[1,0,1]
	s_nop 0
	v_xor_b32_e32 v108, 0x80000000, v85
	v_mov_b32_e32 v109, v84
	s_waitcnt lgkmcnt(15)
	s_nop 0
	v_pk_mul_f32 v[108:109], v[108:109], v[202:203] op_sel:[0,1]
	s_nop 0
	v_pk_fma_f32 v[84:85], v[84:85], v[202:203], v[108:109] op_sel_hi:[1,0,1]
	v_xor_b32_e32 v108, 0x80000000, v89
	v_mov_b32_e32 v109, v88
	s_waitcnt lgkmcnt(14)
	v_pk_mul_f32 v[108:109], v[108:109], v[174:175] op_sel:[0,1]
	s_nop 0
	v_pk_fma_f32 v[88:89], v[88:89], v[174:175], v[108:109] op_sel_hi:[1,0,1]
	v_xor_b32_e32 v108, 0x80000000, v91
	v_mov_b32_e32 v109, v90
	s_waitcnt lgkmcnt(13)
	v_pk_mul_f32 v[108:109], v[108:109], v[176:177] op_sel:[0,1]
	s_nop 0
	v_pk_fma_f32 v[90:91], v[90:91], v[176:177], v[108:109] op_sel_hi:[1,0,1]
	v_xor_b32_e32 v108, 0x80000000, v95
	v_mov_b32_e32 v109, v94
	s_waitcnt lgkmcnt(12)
	v_pk_mul_f32 v[108:109], v[108:109], v[178:179] op_sel:[0,1]
	s_nop 0
	v_pk_fma_f32 v[94:95], v[94:95], v[178:179], v[108:109] op_sel_hi:[1,0,1]
	v_xor_b32_e32 v108, 0x80000000, v93
	v_mov_b32_e32 v109, v92
	s_waitcnt lgkmcnt(11)
	v_pk_mul_f32 v[108:109], v[108:109], v[180:181] op_sel:[0,1]
	s_nop 0
	v_pk_fma_f32 v[92:93], v[92:93], v[180:181], v[108:109] op_sel_hi:[1,0,1]
	v_xor_b32_e32 v108, 0x80000000, v97
	v_mov_b32_e32 v109, v96
	s_waitcnt lgkmcnt(10)
	v_pk_mul_f32 v[108:109], v[108:109], v[182:183] op_sel:[0,1]
	s_nop 0
	v_pk_fma_f32 v[96:97], v[96:97], v[182:183], v[108:109] op_sel_hi:[1,0,1]
	v_xor_b32_e32 v136, 0x80000000, v141
	s_waitcnt lgkmcnt(8)
	v_pk_mul_f32 v[100:101], v[100:101], v[186:187] op_sel:[0,1]
	s_nop 0
	v_pk_fma_f32 v[104:105], v[98:99], v[186:187], v[100:101] op_sel_hi:[1,0,1]
	v_xor_b32_e32 v100, 0x80000000, v107
	v_mov_b32_e32 v101, v106
	s_waitcnt lgkmcnt(7)
	v_pk_mul_f32 v[100:101], v[100:101], v[188:189] op_sel:[0,1]
	s_nop 0
	v_pk_fma_f32 v[100:101], v[106:107], v[188:189], v[100:101] op_sel_hi:[1,0,1]
	v_xor_b32_e32 v106, 0x80000000, v111
	v_mov_b32_e32 v107, v110
	v_pk_add_f32 v[144:145], v[100:101], v[96:97] neg_lo:[0,1] neg_hi:[0,1]
	s_waitcnt lgkmcnt(6)
	v_pk_mul_f32 v[106:107], v[106:107], v[190:191] op_sel:[0,1]
	s_nop 0
	v_pk_fma_f32 v[98:99], v[110:111], v[190:191], v[106:107] op_sel_hi:[1,0,1]
	v_xor_b32_e32 v110, 0x80000000, v113
	v_mov_b32_e32 v111, v112
	v_pk_add_f32 v[148:149], v[98:99], v[92:93] neg_lo:[0,1] neg_hi:[0,1]
	s_waitcnt lgkmcnt(5)
	v_pk_mul_f32 v[110:111], v[110:111], v[192:193] op_sel:[0,1]
	s_nop 0
	v_pk_fma_f32 v[110:111], v[112:113], v[192:193], v[110:111] op_sel_hi:[1,0,1]
	v_xor_b32_e32 v112, 0x80000000, v115
	v_mov_b32_e32 v113, v114
	s_waitcnt lgkmcnt(4)
	v_pk_mul_f32 v[112:113], v[112:113], v[194:195] op_sel:[0,1]
	s_nop 0
	v_pk_fma_f32 v[112:113], v[114:115], v[194:195], v[112:113] op_sel_hi:[1,0,1]
	v_xor_b32_e32 v114, 0x80000000, v139
	v_mov_b32_e32 v115, v138
	s_waitcnt lgkmcnt(3)
	v_pk_mul_f32 v[114:115], v[114:115], v[196:197] op_sel:[0,1]
	s_nop 0
	v_pk_fma_f32 v[114:115], v[138:139], v[196:197], v[114:115] op_sel_hi:[1,0,1]
	v_xor_b32_e32 v138, 0x80000000, v103
	v_mov_b32_e32 v139, v102
	s_waitcnt lgkmcnt(2)
	v_pk_mul_f32 v[136:137], v[136:137], v[198:199] op_sel:[0,1]
	s_nop 0
	v_pk_fma_f32 v[106:107], v[140:141], v[198:199], v[136:137] op_sel_hi:[1,0,1]
	s_waitcnt lgkmcnt(1)
	v_pk_mul_f32 v[138:139], v[138:139], v[200:201] op_sel:[0,1]
	s_nop 0
	v_pk_fma_f32 v[102:103], v[102:103], v[200:201], v[138:139] op_sel_hi:[1,0,1]
	v_xor_b32_e32 v138, 0x80000000, v87
	v_mov_b32_e32 v139, v86
	s_waitcnt lgkmcnt(0)
	v_pk_mul_f32 v[138:139], v[138:139], v[172:173] op_sel:[0,1]
	s_nop 0
	v_pk_fma_f32 v[86:87], v[86:87], v[172:173], v[138:139] op_sel_hi:[1,0,1]
	v_pk_add_f32 v[136:137], v[184:185], v[102:103]
	v_pk_add_f32 v[138:139], v[104:105], v[86:87]
	v_pk_add_f32 v[140:141], v[104:105], v[86:87] neg_lo:[0,1] neg_hi:[0,1]
	v_pk_add_f32 v[86:87], v[90:91], v[112:113]
	v_pk_add_f32 v[90:91], v[112:113], v[90:91] neg_lo:[0,1] neg_hi:[0,1]
	v_pk_add_f32 v[104:105], v[86:87], v[138:139]
	v_pk_add_f32 v[112:113], v[138:139], v[86:87] neg_lo:[0,1] neg_hi:[0,1]
	v_xor_b32_e32 v139, 0x80000000, v90
	v_mov_b32_e32 v138, v91
	v_pk_add_f32 v[86:87], v[96:97], v[100:101]
	v_pk_add_f32 v[90:91], v[88:89], v[114:115]
	v_pk_add_f32 v[88:89], v[114:115], v[88:89] neg_lo:[0,1] neg_hi:[0,1]
	v_pk_add_f32 v[96:97], v[86:87], v[90:91]
	v_pk_add_f32 v[100:101], v[86:87], v[90:91] neg_lo:[0,1] neg_hi:[0,1]
	v_xor_b32_e32 v115, 0x80000000, v88
	v_mov_b32_e32 v114, v89
	v_pk_add_f32 v[86:87], v[92:93], v[98:99]
	v_pk_add_f32 v[88:89], v[84:85], v[106:107]
	v_pk_add_f32 v[108:109], v[184:185], v[102:103] neg_lo:[0,1] neg_hi:[0,1]
	v_pk_add_f32 v[102:103], v[94:95], v[110:111]
	v_pk_add_f32 v[90:91], v[86:87], v[88:89]
	v_pk_add_f32 v[94:95], v[110:111], v[94:95] neg_lo:[0,1] neg_hi:[0,1]
	v_pk_add_f32 v[110:111], v[102:103], v[136:137]
	v_pk_add_f32 v[84:85], v[106:107], v[84:85] neg_lo:[0,1] neg_hi:[0,1]
	v_pk_add_f32 v[106:107], v[86:87], v[88:89] neg_lo:[0,1] neg_hi:[0,1]
	v_pk_add_f32 v[86:87], v[90:91], v[104:105]
	v_pk_add_f32 v[90:91], v[104:105], v[90:91] neg_lo:[0,1] neg_hi:[0,1]
	v_pk_add_f32 v[142:143], v[140:141], v[138:139] neg_lo:[0,1] neg_hi:[0,1]
	v_xor_b32_e32 v151, 0x80000000, v84
	v_mov_b32_e32 v150, v85
	v_pk_add_f32 v[84:85], v[96:97], v[110:111]
	v_pk_add_f32 v[96:97], v[110:111], v[96:97] neg_lo:[0,1] neg_hi:[0,1]
	v_xor_b32_e32 v99, 0x80000000, v90
	v_mov_b32_e32 v98, v91
	v_pk_add_f32 v[146:147], v[144:145], v[114:115] neg_lo:[0,1] neg_hi:[0,1]
	v_pk_add_f32 v[92:93], v[148:149], v[150:151] neg_lo:[0,1] neg_hi:[0,1]
	v_pk_add_f32 v[88:89], v[84:85], v[86:87]
	v_pk_add_f32 v[86:87], v[84:85], v[86:87] neg_lo:[0,1] neg_hi:[0,1]
	v_pk_add_f32 v[84:85], v[96:97], v[98:99]
	v_pk_add_f32 v[90:91], v[96:97], v[98:99] neg_lo:[0,1] neg_hi:[0,1]
	v_pk_mul_f32 v[96:97], v[142:143], s[10:11] op_sel:[1,0]
	v_pk_add_f32 v[102:103], v[136:137], v[102:103] neg_lo:[0,1] neg_hi:[0,1]
	v_xor_b32_e32 v137, 0x80000000, v94
	v_mov_b32_e32 v136, v95
	v_pk_fma_f32 v[96:97], v[142:143], s[8:9], v[96:97] op_sel_hi:[0,1,1]
	v_mul_f32_e32 v98, 0x3f3504f3, v146
	s_mov_b32 s8, s31
	s_mov_b32 s9, s30
	v_pk_mul_f32 v[104:105], v[92:93], s[34:35] op_sel:[1,0]
	v_pk_add_f32 v[94:95], v[108:109], v[136:137] neg_lo:[0,1] neg_hi:[0,1]
	v_pk_fma_f32 v[98:99], v[146:147], s[8:9], v[98:99] op_sel:[1,0,0] op_sel_hi:[1,1,0]
	v_pk_fma_f32 v[92:93], v[92:93], s[28:29], v[104:105] op_sel_hi:[0,1,1]
	v_pk_add_f32 v[104:105], v[94:95], v[98:99]
	v_pk_add_f32 v[98:99], v[94:95], v[98:99] neg_lo:[0,1] neg_hi:[0,1]
	v_pk_add_f32 v[94:95], v[96:97], v[92:93]
	v_pk_add_f32 v[92:93], v[96:97], v[92:93] neg_lo:[0,1] neg_hi:[0,1]
	v_pk_add_f32 v[96:97], v[104:105], v[94:95]
	v_pk_add_f32 v[94:95], v[104:105], v[94:95] neg_lo:[0,1] neg_hi:[0,1]
	v_xor_b32_e32 v105, 0x80000000, v92
	v_mov_b32_e32 v104, v93
	s_mov_b32 s10, s20
	s_mov_b32 s11, s36
	v_pk_mul_f32 v[110:111], v[100:101], s[12:13] op_sel:[1,0]
	v_pk_add_f32 v[92:93], v[98:99], v[104:105]
	v_pk_add_f32 v[98:99], v[98:99], v[104:105] neg_lo:[0,1] neg_hi:[0,1]
	v_mul_f32_e32 v104, 0x3f3504f3, v112
	v_pk_fma_f32 v[100:101], v[100:101], s[10:11], v[110:111] op_sel_hi:[0,1,1]
	v_mul_f32_e32 v110, 0xbf3504f3, v107
	v_pk_fma_f32 v[104:105], v[112:113], s[8:9], v[104:105] op_sel:[1,0,0] op_sel_hi:[1,1,0]
	v_pk_fma_f32 v[106:107], v[106:107], s[8:9], v[110:111] op_sel_hi:[0,1,0]
	v_pk_add_f32 v[110:111], v[102:103], v[100:101]
	v_pk_add_f32 v[112:113], v[102:103], v[100:101] neg_lo:[0,1] neg_hi:[0,1]
	v_pk_add_f32 v[100:101], v[106:107], v[104:105]
	v_pk_add_f32 v[106:107], v[104:105], v[106:107] neg_lo:[0,1] neg_hi:[0,1]
	v_pk_add_f32 v[104:105], v[110:111], v[100:101]
	v_pk_add_f32 v[102:103], v[110:111], v[100:101] neg_lo:[0,1] neg_hi:[0,1]
	v_xor_b32_e32 v111, 0x80000000, v106
	v_mov_b32_e32 v110, v107
	v_pk_add_f32 v[100:101], v[112:113], v[110:111]
	v_pk_add_f32 v[106:107], v[112:113], v[110:111] neg_lo:[0,1] neg_hi:[0,1]
	v_pk_add_f32 v[110:111], v[148:149], v[150:151]
	s_mov_b32 s12, s28
	s_mov_b32 s13, s34
	s_mov_b32 s10, s34
	s_mov_b32 s11, s27
	v_pk_mul_f32 v[112:113], v[110:111], s[12:13] op_sel:[1,0]
	v_pk_add_f32 v[108:109], v[136:137], v[108:109]
	v_pk_fma_f32 v[110:111], v[110:111], s[10:11], v[112:113] op_sel_hi:[0,1,1]
	v_pk_add_f32 v[112:113], v[138:139], v[140:141]
	v_pk_add_f32 v[114:115], v[144:145], v[114:115]
	v_pk_mul_f32 v[136:137], v[112:113], s[34:35] op_sel:[1,0]
	s_nop 0
	v_pk_fma_f32 v[112:113], v[112:113], s[28:29], v[136:137] op_sel_hi:[0,1,1]
	v_mul_f32_e32 v136, 0xbf3504f3, v115
	v_pk_fma_f32 v[114:115], v[114:115], s[8:9], v[136:137] op_sel_hi:[0,1,0]
	v_pk_add_f32 v[136:137], v[108:109], v[114:115]
	v_pk_add_f32 v[138:139], v[108:109], v[114:115] neg_lo:[0,1] neg_hi:[0,1]
	v_pk_add_f32 v[108:109], v[112:113], v[110:111]
	v_pk_add_f32 v[112:113], v[112:113], v[110:111] neg_lo:[0,1] neg_hi:[0,1]
	v_pk_add_f32 v[110:111], v[136:137], v[108:109]
	v_pk_add_f32 v[108:109], v[136:137], v[108:109] neg_lo:[0,1] neg_hi:[0,1]
	v_xor_b32_e32 v137, 0x80000000, v112
	v_mov_b32_e32 v136, v113
	v_pk_add_f32 v[114:115], v[138:139], v[136:137]
	v_pk_add_f32 v[112:113], v[138:139], v[136:137] neg_lo:[0,1] neg_hi:[0,1]

.LBB0_1630:
	s_or_b64 exec, exec, s[6:7]
	s_waitcnt lgkmcnt(0)
	s_barrier
	s_and_saveexec_b64 s[6:7], vcc
	s_cbranch_execz .LBB0_1632
	ds_read_b64 v[176:177], v135 offset:32768
	v_cvt_f32_i32_e32 v86, v132
	v_lshlrev_b32_e32 v88, 3, v133
	v_lshlrev_b32_e32 v89, 3, v132
	v_mul_f32_e32 v86, 0x39000000, v86
	v_sin_f32_e32 v87, v86
	v_cos_f32_e32 v86, v86
	v_add3_u32 v92, 0, v88, v89
	ds_read_b64 v[178:179], v92
	ds_read_b64 v[180:181], v134 offset:36864
	ds_read_b64 v[182:183], v127 offset:4096
	ds_read_b64 v[184:185], v131 offset:40960
	ds_read_b64 v[186:187], v124 offset:8192
	ds_read_b64 v[188:189], v129 offset:45056
	ds_read_b64 v[190:191], v67 offset:12288
	ds_read_b64 v[192:193], v126 offset:49152
	ds_read_b64 v[194:195], v59 offset:16384
	ds_read_b64 v[196:197], v123 offset:53248
	ds_read_b64 v[198:199], v23 offset:20480
	ds_read_b64 v[172:173], v65 offset:57344
	ds_read_b64 v[174:175], v15 offset:24576
	v_xor_b32_e32 v90, 0x80000000, v87
	v_mov_b32_e32 v91, v86
	v_cvt_f32_i32_e32 v93, v130
	s_waitcnt lgkmcnt(14)
	s_waitcnt lgkmcnt(13)
	v_pk_mul_f32 v[90:91], v[90:91], v[176:177] op_sel:[0,1]
	v_cvt_f32_i32_e32 v63, v63
	v_pk_fma_f32 v[84:85], v[86:87], v[176:177], v[90:91] op_sel_hi:[1,0,1]
	ds_read_b64 v[86:87], v31 offset:61440
	ds_read_b64 v[88:89], v11 offset:28672
	v_cvt_f32_i32_e32 v27, v27
	s_waitcnt lgkmcnt(14)
	v_pk_add_f32 v[84:85], v[178:179], v[84:85]
	ds_write_b64 v92, v[84:85]
	v_mul_f32_e32 v85, 0x39000000, v93
	v_cos_f32_e32 v84, v85
	v_sin_f32_e32 v85, v85
	v_cvt_f32_i32_e32 v92, v128
	v_mov_b32_e32 v91, v84
	v_xor_b32_e32 v90, 0x80000000, v85
	s_waitcnt lgkmcnt(14)
	v_pk_mul_f32 v[90:91], v[90:91], v[180:181] op_sel:[0,1]
	v_cvt_f32_i32_e32 v19, v19
	v_pk_fma_f32 v[84:85], v[84:85], v[180:181], v[90:91] op_sel_hi:[1,0,1]
	s_waitcnt lgkmcnt(13)
	v_pk_add_f32 v[84:85], v[182:183], v[84:85]
	ds_write_b64 v127, v[84:85] offset:4096
	v_mul_f32_e32 v85, 0x39000000, v92
	v_cos_f32_e32 v84, v85
	v_sin_f32_e32 v85, v85
	v_cvt_f32_i32_e32 v92, v125
	v_mov_b32_e32 v91, v84
	v_xor_b32_e32 v90, 0x80000000, v85
	s_waitcnt lgkmcnt(13)
	v_pk_mul_f32 v[90:91], v[90:91], v[184:185] op_sel:[0,1]
	s_nop 0
	v_pk_fma_f32 v[84:85], v[84:85], v[184:185], v[90:91] op_sel_hi:[1,0,1]
	s_waitcnt lgkmcnt(12)
	v_pk_add_f32 v[84:85], v[186:187], v[84:85]
	ds_write_b64 v124, v[84:85] offset:8192
	v_mul_f32_e32 v85, 0x39000000, v92
	v_cos_f32_e32 v84, v85
	v_sin_f32_e32 v85, v85
	v_cvt_f32_i32_e32 v92, v122
	v_mov_b32_e32 v91, v84
	v_xor_b32_e32 v90, 0x80000000, v85
	s_waitcnt lgkmcnt(12)
	v_pk_mul_f32 v[90:91], v[90:91], v[188:189] op_sel:[0,1]
	s_nop 0
	v_pk_fma_f32 v[84:85], v[84:85], v[188:189], v[90:91] op_sel_hi:[1,0,1]
	s_waitcnt lgkmcnt(11)
	v_pk_add_f32 v[84:85], v[190:191], v[84:85]
	ds_write_b64 v67, v[84:85] offset:12288
	v_mul_f32_e32 v67, 0x39000000, v92
	v_cos_f32_e32 v84, v67
	v_sin_f32_e32 v85, v67
	s_nop 0
	v_mov_b32_e32 v91, v84
	v_xor_b32_e32 v90, 0x80000000, v85
	s_waitcnt lgkmcnt(11)
	v_pk_mul_f32 v[90:91], v[90:91], v[192:193] op_sel:[0,1]
	s_nop 0
	v_pk_fma_f32 v[84:85], v[84:85], v[192:193], v[90:91] op_sel_hi:[1,0,1]
	s_waitcnt lgkmcnt(10)
	v_pk_add_f32 v[84:85], v[194:195], v[84:85]
	ds_write_b64 v59, v[84:85] offset:16384
	v_mul_f32_e32 v59, 0x39000000, v63
	v_cos_f32_e32 v84, v59
	v_sin_f32_e32 v85, v59
	s_nop 0
	v_mov_b32_e32 v91, v84
	v_xor_b32_e32 v90, 0x80000000, v85
	s_waitcnt lgkmcnt(10)
	v_pk_mul_f32 v[90:91], v[90:91], v[196:197] op_sel:[0,1]
	s_nop 0
	v_pk_fma_f32 v[84:85], v[84:85], v[196:197], v[90:91] op_sel_hi:[1,0,1]
	s_waitcnt lgkmcnt(9)
	v_pk_add_f32 v[84:85], v[198:199], v[84:85]
	ds_write_b64 v23, v[84:85] offset:20480
	v_mul_f32_e32 v23, 0x39000000, v27
	v_cos_f32_e32 v84, v23
	v_sin_f32_e32 v85, v23
	s_nop 0
	v_mov_b32_e32 v91, v84
	v_xor_b32_e32 v90, 0x80000000, v85
	s_waitcnt lgkmcnt(9)
	v_pk_mul_f32 v[90:91], v[90:91], v[172:173] op_sel:[0,1]
	s_nop 0
	v_pk_fma_f32 v[84:85], v[84:85], v[172:173], v[90:91] op_sel_hi:[1,0,1]
	s_waitcnt lgkmcnt(8)
	v_pk_add_f32 v[84:85], v[174:175], v[84:85]
	ds_write_b64 v15, v[84:85] offset:24576
	v_mul_f32_e32 v15, 0x39000000, v19
	v_cos_f32_e32 v84, v15
	v_sin_f32_e32 v85, v15
	s_nop 0
	v_mov_b32_e32 v91, v84
	v_xor_b32_e32 v90, 0x80000000, v85
	s_waitcnt lgkmcnt(8)
	v_pk_mul_f32 v[90:91], v[90:91], v[86:87] op_sel:[0,1]
	s_nop 0
	v_pk_fma_f32 v[84:85], v[84:85], v[86:87], v[90:91] op_sel_hi:[1,0,1]
	s_waitcnt lgkmcnt(7)
	v_pk_add_f32 v[84:85], v[88:89], v[84:85]
	ds_write_b64 v11, v[84:85] offset:28672

.LBB0_1652:
	s_or_b64 exec, exec, s[6:7]
	v_add_u32_e32 v114, 0x1000, v126
	v_ashrrev_i32_e32 v114, 4, v114
	v_lshlrev_b32_e32 v114, 3, v114
	v_lshlrev_b32_e32 v133, 3, v126
	v_add3_u32 v132, 0, v114, v133
	v_add_u32_e32 v114, 0x1200, v126
	v_ashrrev_i32_e32 v114, 4, v114
	v_lshlrev_b32_e32 v114, 3, v114
	v_add3_u32 v131, 0, v114, v133
	v_add_u32_e32 v114, 0x1400, v126
	v_ashrrev_i32_e32 v114, 4, v114
	v_lshlrev_b32_e32 v114, 3, v114
	v_add3_u32 v130, 0, v114, v133
	v_add_u32_e32 v114, 0x1600, v126
	v_ashrrev_i32_e32 v114, 4, v114
	v_lshlrev_b32_e32 v114, 3, v114
	v_add3_u32 v129, 0, v114, v133
	v_add_u32_e32 v114, 0x1800, v126
	v_ashrrev_i32_e32 v114, 4, v114
	v_lshlrev_b32_e32 v114, 3, v114
	v_add3_u32 v128, 0, v114, v133
	v_add_u32_e32 v114, 0x1a00, v126
	v_ashrrev_i32_e32 v114, 4, v114
	v_lshlrev_b32_e32 v114, 3, v114
	v_add3_u32 v127, 0, v114, v133
	v_add_u32_e32 v114, 0x1c00, v126
	v_ashrrev_i32_e32 v114, 4, v114
	v_lshlrev_b32_e32 v114, 3, v114
	v_add3_u32 v115, 0, v114, v133
	v_add_u32_e32 v114, 0x1e00, v126
	v_ashrrev_i32_e32 v114, 4, v114
	s_waitcnt lgkmcnt(0)
	s_barrier
	v_lshlrev_b32_e32 v114, 3, v114
	v_add3_u32 v114, 0, v114, v133
	s_and_saveexec_b64 s[6:7], vcc
	s_cbranch_execz .LBB0_1654
	ds_read_b64 v[172:173], v134
	ds_read_b64 v[174:175], v122 offset:4096
	ds_read_b64 v[176:177], v116 offset:8192
	ds_read_b64 v[178:179], v63 offset:12288
	ds_read_b64 v[180:181], v31 offset:16384
	ds_read_b64 v[182:183], v23 offset:20480
	ds_read_b64 v[184:185], v15 offset:24576
	ds_read_b64 v[186:187], v11 offset:28672
	ds_read_b64 v[188:189], v132 offset:32768
	ds_read_b64 v[190:191], v131 offset:36864
	ds_read_b64 v[192:193], v130 offset:40960
	ds_read_b64 v[194:195], v129 offset:45056
	ds_read_b64 v[196:197], v128 offset:49152
	ds_read_b64 v[198:199], v127 offset:53248
	ds_read_b64 v[200:201], v115 offset:57344
	s_waitcnt lgkmcnt(14)
	ds_read_b64 v[202:203], v114 offset:61440
	v_and_b32_e32 v106, 15, v126
	v_cvt_f32_ubyte0_e32 v106, v106
	v_mul_f32_e32 v107, 0x3b800000, v106
	v_cos_f32_e32 v106, v107
	v_sin_f32_e32 v108, v107
	s_waitcnt lgkmcnt(15)
	v_mov_b32_e32 v109, v106
	v_xor_b32_e32 v107, 0x80000000, v108
	v_pk_mul_f32 v[140:141], v[108:109], v[108:109] op_sel_hi:[1,0] neg_lo:[0,1] neg_hi:[0,1]
	s_mov_b32 s29, s26
	v_pk_fma_f32 v[140:141], v[106:107], v[106:107], v[140:141] op_sel_hi:[1,0,1]
	s_mov_b32 s8, s26
	v_pk_mul_f32 v[142:143], v[108:109], v[140:141] op_sel:[0,1]
	s_mov_b32 s9, s28
	v_pk_fma_f32 v[142:143], v[106:107], v[140:141], v[142:143] op_sel_hi:[1,0,1]
	s_mov_b32 s37, s20
	v_pk_mul_f32 v[144:145], v[108:109], v[142:143] op_sel:[0,1]
	s_mov_b32 s10, s27
	v_pk_fma_f32 v[144:145], v[106:107], v[142:143], v[144:145] op_sel_hi:[1,0,1]
	s_mov_b32 s11, s34
	v_pk_mul_f32 v[146:147], v[108:109], v[144:145] op_sel:[0,1]
	s_mov_b32 s35, s28
	v_pk_fma_f32 v[146:147], v[106:107], v[144:145], v[146:147] op_sel_hi:[1,0,1]
	s_nop 0
	v_pk_mul_f32 v[148:149], v[108:109], v[146:147] op_sel:[0,1]
	s_nop 0
	v_pk_fma_f32 v[148:149], v[106:107], v[146:147], v[148:149] op_sel_hi:[1,0,1]
	s_nop 0
	v_pk_mul_f32 v[150:151], v[108:109], v[148:149] op_sel:[0,1]
	s_nop 0
	v_pk_fma_f32 v[150:151], v[106:107], v[148:149], v[150:151] op_sel_hi:[1,0,1]
	s_nop 0
	v_pk_mul_f32 v[152:153], v[108:109], v[150:151] op_sel:[0,1]
	s_nop 0
	v_pk_fma_f32 v[152:153], v[106:107], v[150:151], v[152:153] op_sel_hi:[1,0,1]
	s_nop 0
	v_pk_mul_f32 v[154:155], v[108:109], v[152:153] op_sel:[0,1]
	s_nop 0
	v_pk_fma_f32 v[154:155], v[106:107], v[152:153], v[154:155] op_sel_hi:[1,0,1]
	s_nop 0
	v_pk_mul_f32 v[156:157], v[108:109], v[154:155] op_sel:[0,1]
	s_nop 0
	v_pk_fma_f32 v[156:157], v[106:107], v[154:155], v[156:157] op_sel_hi:[1,0,1]
	s_nop 0
	v_pk_mul_f32 v[158:159], v[108:109], v[156:157] op_sel:[0,1]
	s_nop 0
	v_pk_fma_f32 v[158:159], v[106:107], v[156:157], v[158:159] op_sel_hi:[1,0,1]
	s_nop 0
	v_pk_mul_f32 v[160:161], v[108:109], v[158:159] op_sel:[0,1]
	s_nop 0
	v_pk_fma_f32 v[160:161], v[106:107], v[158:159], v[160:161] op_sel_hi:[1,0,1]
	s_nop 0
	v_pk_mul_f32 v[162:163], v[108:109], v[160:161] op_sel:[0,1]
	s_nop 0
	v_pk_fma_f32 v[162:163], v[106:107], v[160:161], v[162:163] op_sel_hi:[1,0,1]
	s_nop 0
	v_pk_mul_f32 v[164:165], v[108:109], v[162:163] op_sel:[0,1]
	s_nop 0
	v_pk_fma_f32 v[164:165], v[106:107], v[162:163], v[164:165] op_sel_hi:[1,0,1]
	s_nop 0
	v_pk_mul_f32 v[166:167], v[108:109], v[164:165] op_sel:[0,1]
	s_waitcnt lgkmcnt(14)
	v_pk_mul_f32 v[108:109], v[108:109], v[174:175] op_sel:[0,1]
	v_pk_fma_f32 v[166:167], v[106:107], v[164:165], v[166:167] op_sel_hi:[1,0,1]
	v_pk_fma_f32 v[84:85], v[106:107], v[174:175], v[108:109] op_sel_hi:[1,0,1]
	v_xor_b32_e32 v168, 0x80000000, v167
	v_mov_b32_e32 v169, v166
	s_waitcnt lgkmcnt(0)
	v_pk_mul_f32 v[168:169], v[168:169], v[202:203] op_sel:[0,1]
	s_nop 0
	v_pk_fma_f32 v[138:139], v[166:167], v[202:203], v[168:169] op_sel_hi:[1,0,1]
	v_xor_b32_e32 v166, 0x80000000, v165
	v_mov_b32_e32 v167, v164
	v_pk_mul_f32 v[166:167], v[166:167], v[200:201] op_sel:[0,1]
	s_nop 0
	v_pk_fma_f32 v[136:137], v[164:165], v[200:201], v[166:167] op_sel_hi:[1,0,1]
	v_xor_b32_e32 v164, 0x80000000, v163
	v_mov_b32_e32 v165, v162
	v_pk_mul_f32 v[164:165], v[164:165], v[198:199] op_sel:[0,1]
	s_nop 0
	v_pk_fma_f32 v[112:113], v[162:163], v[198:199], v[164:165] op_sel_hi:[1,0,1]
	v_xor_b32_e32 v162, 0x80000000, v161
	v_mov_b32_e32 v163, v160
	v_pk_mul_f32 v[162:163], v[162:163], v[196:197] op_sel:[0,1]
	s_nop 0
	v_pk_fma_f32 v[110:111], v[160:161], v[196:197], v[162:163] op_sel_hi:[1,0,1]
	v_xor_b32_e32 v160, 0x80000000, v159
	v_mov_b32_e32 v161, v158
	v_pk_mul_f32 v[160:161], v[160:161], v[194:195] op_sel:[0,1]
	s_nop 0
	v_pk_fma_f32 v[104:105], v[158:159], v[194:195], v[160:161] op_sel_hi:[1,0,1]
	v_xor_b32_e32 v158, 0x80000000, v157
	v_mov_b32_e32 v159, v156
	v_pk_mul_f32 v[158:159], v[158:159], v[192:193] op_sel:[0,1]
	s_nop 0
	v_pk_fma_f32 v[102:103], v[156:157], v[192:193], v[158:159] op_sel_hi:[1,0,1]
	v_xor_b32_e32 v156, 0x80000000, v155
	v_mov_b32_e32 v157, v154
	v_pk_mul_f32 v[156:157], v[156:157], v[190:191] op_sel:[0,1]
	s_nop 0
	v_pk_fma_f32 v[100:101], v[154:155], v[190:191], v[156:157] op_sel_hi:[1,0,1]
	v_xor_b32_e32 v154, 0x80000000, v153
	v_mov_b32_e32 v155, v152
	v_pk_mul_f32 v[154:155], v[154:155], v[188:189] op_sel:[0,1]
	s_nop 0
	v_pk_fma_f32 v[98:99], v[152:153], v[188:189], v[154:155] op_sel_hi:[1,0,1]
	v_xor_b32_e32 v152, 0x80000000, v151
	v_mov_b32_e32 v153, v150
	v_pk_mul_f32 v[152:153], v[152:153], v[186:187] op_sel:[0,1]
	v_pk_add_f32 v[106:107], v[172:173], v[98:99]
	v_pk_fma_f32 v[96:97], v[150:151], v[186:187], v[152:153] op_sel_hi:[1,0,1]
	v_xor_b32_e32 v150, 0x80000000, v149
	v_mov_b32_e32 v151, v148
	v_pk_mul_f32 v[150:151], v[150:151], v[184:185] op_sel:[0,1]
	v_pk_add_f32 v[108:109], v[172:173], v[98:99] neg_lo:[0,1] neg_hi:[0,1]
	v_pk_fma_f32 v[94:95], v[148:149], v[184:185], v[150:151] op_sel_hi:[1,0,1]
	v_xor_b32_e32 v148, 0x80000000, v147
	v_mov_b32_e32 v149, v146
	v_pk_mul_f32 v[148:149], v[148:149], v[182:183] op_sel:[0,1]
	s_nop 0
	v_pk_fma_f32 v[92:93], v[146:147], v[182:183], v[148:149] op_sel_hi:[1,0,1]
	v_xor_b32_e32 v146, 0x80000000, v145
	v_mov_b32_e32 v147, v144
	v_pk_mul_f32 v[146:147], v[146:147], v[180:181] op_sel:[0,1]
	s_nop 0
	v_pk_fma_f32 v[90:91], v[144:145], v[180:181], v[146:147] op_sel_hi:[1,0,1]
	v_xor_b32_e32 v144, 0x80000000, v143
	v_mov_b32_e32 v145, v142
	v_pk_mul_f32 v[144:145], v[144:145], v[178:179] op_sel:[0,1]
	v_pk_add_f32 v[70:71], v[90:91], v[110:111]
	v_pk_fma_f32 v[88:89], v[142:143], v[178:179], v[144:145] op_sel_hi:[1,0,1]
	v_xor_b32_e32 v142, 0x80000000, v141
	v_mov_b32_e32 v143, v140
	v_pk_mul_f32 v[142:143], v[142:143], v[176:177] op_sel:[0,1]
	v_pk_add_f32 v[98:99], v[106:107], v[70:71]
	v_pk_fma_f32 v[86:87], v[140:141], v[176:177], v[142:143] op_sel_hi:[1,0,1]
	v_pk_add_f32 v[106:107], v[106:107], v[70:71] neg_lo:[0,1] neg_hi:[0,1]
	v_pk_add_f32 v[70:71], v[84:85], v[100:101]
	v_pk_add_f32 v[140:141], v[84:85], v[100:101] neg_lo:[0,1] neg_hi:[0,1]
	v_pk_add_f32 v[84:85], v[92:93], v[112:113]
	v_pk_add_f32 v[92:93], v[92:93], v[112:113] neg_lo:[0,1] neg_hi:[0,1]
	v_pk_add_f32 v[100:101], v[70:71], v[84:85]
	v_pk_add_f32 v[112:113], v[70:71], v[84:85] neg_lo:[0,1] neg_hi:[0,1]
	v_pk_add_f32 v[70:71], v[86:87], v[102:103]
	v_pk_add_f32 v[84:85], v[94:95], v[136:137]
	v_pk_add_f32 v[144:145], v[86:87], v[102:103] neg_lo:[0,1] neg_hi:[0,1]
	v_pk_add_f32 v[86:87], v[94:95], v[136:137] neg_lo:[0,1] neg_hi:[0,1]
	v_pk_add_f32 v[94:95], v[70:71], v[84:85]
	v_pk_add_f32 v[102:103], v[70:71], v[84:85] neg_lo:[0,1] neg_hi:[0,1]
	v_pk_add_f32 v[70:71], v[88:89], v[104:105]
	v_pk_add_f32 v[84:85], v[96:97], v[138:139]
	v_xor_b32_e32 v137, 0x80000000, v86
	v_mov_b32_e32 v136, v87
	v_pk_add_f32 v[148:149], v[88:89], v[104:105] neg_lo:[0,1] neg_hi:[0,1]
	v_pk_add_f32 v[86:87], v[96:97], v[138:139] neg_lo:[0,1] neg_hi:[0,1]
	v_pk_add_f32 v[88:89], v[70:71], v[84:85]
	v_xor_b32_e32 v143, 0x80000000, v92
	v_mov_b32_e32 v142, v93
	v_pk_add_f32 v[104:105], v[70:71], v[84:85] neg_lo:[0,1] neg_hi:[0,1]
	v_xor_b32_e32 v139, 0x80000000, v86
	v_mov_b32_e32 v138, v87
	v_pk_add_f32 v[70:71], v[98:99], v[94:95]
	v_pk_add_f32 v[84:85], v[100:101], v[88:89]
	v_pk_add_f32 v[86:87], v[100:101], v[88:89] neg_lo:[0,1] neg_hi:[0,1]
	v_pk_add_f32 v[92:93], v[140:141], v[142:143]
	v_pk_add_f32 v[94:95], v[98:99], v[94:95] neg_lo:[0,1] neg_hi:[0,1]
	v_pk_add_f32 v[88:89], v[70:71], v[84:85]
	v_pk_add_f32 v[84:85], v[70:71], v[84:85] neg_lo:[0,1] neg_hi:[0,1]
	v_xor_b32_e32 v71, 0x80000000, v86
	v_mov_b32_e32 v70, v87
	v_pk_add_f32 v[90:91], v[90:91], v[110:111] neg_lo:[0,1] neg_hi:[0,1]
	v_pk_add_f32 v[146:147], v[144:145], v[136:137]
	v_pk_add_f32 v[96:97], v[148:149], v[138:139]
	v_pk_add_f32 v[86:87], v[94:95], v[70:71]
	v_pk_add_f32 v[70:71], v[94:95], v[70:71] neg_lo:[0,1] neg_hi:[0,1]
	v_pk_mul_f32 v[94:95], v[92:93], s[28:29] op_sel:[1,0]
	v_xor_b32_e32 v111, 0x80000000, v90
	v_mov_b32_e32 v110, v91
	v_pk_fma_f32 v[92:93], v[92:93], s[26:27], v[94:95] op_sel_hi:[0,1,1]
	v_mul_f32_e32 v94, 0x3f3504f3, v147
	s_mov_b32 s29, s34
	v_pk_mul_f32 v[98:99], v[96:97], s[8:9] op_sel:[1,0]
	v_pk_add_f32 v[90:91], v[108:109], v[110:111]
	v_pk_fma_f32 v[94:95], v[146:147], s[30:31], v[94:95] op_sel_hi:[0,1,0]
	v_pk_fma_f32 v[96:97], v[96:97], s[28:29], v[98:99] op_sel_hi:[0,1,1]
	v_pk_add_f32 v[98:99], v[90:91], v[94:95]
	v_pk_add_f32 v[90:91], v[90:91], v[94:95] neg_lo:[0,1] neg_hi:[0,1]
	v_pk_add_f32 v[94:95], v[92:93], v[96:97]
	v_pk_add_f32 v[100:101], v[92:93], v[96:97] neg_lo:[0,1] neg_hi:[0,1]
	v_pk_add_f32 v[96:97], v[98:99], v[94:95]
	v_pk_add_f32 v[92:93], v[98:99], v[94:95] neg_lo:[0,1] neg_hi:[0,1]
	v_xor_b32_e32 v99, 0x80000000, v100
	v_mov_b32_e32 v98, v101
	v_pk_mul_f32 v[100:101], v[102:103], s[36:37] op_sel:[1,0]
	v_pk_add_f32 v[94:95], v[90:91], v[98:99]
	v_pk_add_f32 v[90:91], v[90:91], v[98:99] neg_lo:[0,1] neg_hi:[0,1]
	v_mul_f32_e32 v98, 0x3f3504f3, v113
	v_pk_fma_f32 v[100:101], v[102:103], s[20:21], v[100:101] op_sel_hi:[0,1,1]
	v_mul_f32_e32 v102, 0xbf3504f3, v104
	v_pk_fma_f32 v[98:99], v[112:113], s[30:31], v[98:99] op_sel_hi:[0,1,0]
	v_pk_fma_f32 v[102:103], v[104:105], s[30:31], v[102:103] op_sel:[1,0,0] op_sel_hi:[1,1,0]
	v_pk_add_f32 v[112:113], v[106:107], v[100:101]
	v_pk_add_f32 v[106:107], v[106:107], v[100:101] neg_lo:[0,1] neg_hi:[0,1]
	v_pk_add_f32 v[100:101], v[98:99], v[102:103]
	v_pk_add_f32 v[98:99], v[98:99], v[102:103] neg_lo:[0,1] neg_hi:[0,1]
	v_pk_add_f32 v[104:105], v[112:113], v[100:101]
	v_pk_add_f32 v[100:101], v[112:113], v[100:101] neg_lo:[0,1] neg_hi:[0,1]
	v_xor_b32_e32 v113, 0x80000000, v98
	v_mov_b32_e32 v112, v99
	v_pk_add_f32 v[102:103], v[106:107], v[112:113]
	v_pk_add_f32 v[98:99], v[106:107], v[112:113] neg_lo:[0,1] neg_hi:[0,1]
	v_pk_add_f32 v[106:107], v[148:149], v[138:139] neg_lo:[0,1] neg_hi:[0,1]
	v_pk_add_f32 v[108:109], v[108:109], v[110:111] neg_lo:[0,1] neg_hi:[0,1]
	v_pk_mul_f32 v[112:113], v[106:107], s[10:11] op_sel:[1,0]
	v_pk_add_f32 v[110:111], v[140:141], v[142:143] neg_lo:[0,1] neg_hi:[0,1]
	v_pk_fma_f32 v[106:107], v[106:107], s[34:35], v[112:113] op_sel_hi:[0,1,1]
	v_pk_mul_f32 v[112:113], v[110:111], s[8:9] op_sel:[1,0]
	s_nop 0
	v_pk_fma_f32 v[110:111], v[110:111], s[28:29], v[112:113] op_sel_hi:[0,1,1]
	v_pk_add_f32 v[112:113], v[144:145], v[136:137] neg_lo:[0,1] neg_hi:[0,1]
	v_pk_add_f32 v[138:139], v[110:111], v[106:107] neg_lo:[0,1] neg_hi:[0,1]
	v_mul_f32_e32 v136, 0xbf3504f3, v112
	v_pk_fma_f32 v[112:113], v[112:113], s[30:31], v[136:137] op_sel:[1,0,0] op_sel_hi:[1,1,0]
	s_nop 0
	v_pk_add_f32 v[136:137], v[108:109], v[112:113]
	v_pk_add_f32 v[112:113], v[108:109], v[112:113] neg_lo:[0,1] neg_hi:[0,1]
	v_pk_add_f32 v[108:109], v[110:111], v[106:107]
	s_nop 0
	v_pk_add_f32 v[110:111], v[136:137], v[108:109]
	v_pk_add_f32 v[106:107], v[136:137], v[108:109] neg_lo:[0,1] neg_hi:[0,1]
	v_xor_b32_e32 v137, 0x80000000, v138
	v_mov_b32_e32 v136, v139
	v_pk_add_f32 v[108:109], v[112:113], v[136:137]
	v_pk_add_f32 v[112:113], v[112:113], v[136:137] neg_lo:[0,1] neg_hi:[0,1]

.LBB0_1656:
	s_or_b64 exec, exec, s[6:7]
	s_waitcnt lgkmcnt(0)
	s_barrier
	s_and_saveexec_b64 s[6:7], vcc
	s_cbranch_execz .LBB0_1658
	ds_read_b64 v[172:173], v134
	ds_read_b64 v[174:175], v122 offset:4096
	ds_read_b64 v[176:177], v116 offset:8192
	ds_read_b64 v[178:179], v63 offset:12288
	ds_read_b64 v[180:181], v31 offset:16384
	ds_read_b64 v[182:183], v23 offset:20480
	ds_read_b64 v[184:185], v15 offset:24576
	ds_read_b64 v[186:187], v11 offset:28672
	ds_read_b64 v[188:189], v132 offset:32768
	ds_read_b64 v[190:191], v131 offset:36864
	ds_read_b64 v[192:193], v130 offset:40960
	ds_read_b64 v[194:195], v129 offset:45056
	ds_read_b64 v[196:197], v128 offset:49152
	ds_read_b64 v[198:199], v127 offset:53248
	ds_read_b64 v[200:201], v115 offset:57344
	s_waitcnt lgkmcnt(14)
	ds_read_b64 v[202:203], v114 offset:61440
	v_cvt_f32_ubyte0_e32 v106, v126
	v_mul_f32_e32 v107, 0x39800000, v106
	v_cos_f32_e32 v106, v107
	v_sin_f32_e32 v108, v107
	s_waitcnt lgkmcnt(15)
	v_mov_b32_e32 v109, v106
	v_xor_b32_e32 v107, 0x80000000, v108
	v_pk_mul_f32 v[140:141], v[108:109], v[108:109] op_sel_hi:[1,0] neg_lo:[0,1] neg_hi:[0,1]
	s_mov_b32 s29, s26
	v_pk_fma_f32 v[140:141], v[106:107], v[106:107], v[140:141] op_sel_hi:[1,0,1]
	s_mov_b32 s8, s26
	v_pk_mul_f32 v[142:143], v[108:109], v[140:141] op_sel:[0,1]
	s_mov_b32 s9, s28
	v_pk_fma_f32 v[142:143], v[106:107], v[140:141], v[142:143] op_sel_hi:[1,0,1]
	s_mov_b32 s37, s20
	v_pk_mul_f32 v[144:145], v[108:109], v[142:143] op_sel:[0,1]
	s_mov_b32 s10, s27
	v_pk_fma_f32 v[144:145], v[106:107], v[142:143], v[144:145] op_sel_hi:[1,0,1]
	s_mov_b32 s11, s34
	v_pk_mul_f32 v[146:147], v[108:109], v[144:145] op_sel:[0,1]
	s_mov_b32 s35, s28
	v_pk_fma_f32 v[146:147], v[106:107], v[144:145], v[146:147] op_sel_hi:[1,0,1]
	s_nop 0
	v_pk_mul_f32 v[148:149], v[108:109], v[146:147] op_sel:[0,1]
	s_nop 0
	v_pk_fma_f32 v[148:149], v[106:107], v[146:147], v[148:149] op_sel_hi:[1,0,1]
	s_nop 0
	v_pk_mul_f32 v[150:151], v[108:109], v[148:149] op_sel:[0,1]
	s_nop 0
	v_pk_fma_f32 v[150:151], v[106:107], v[148:149], v[150:151] op_sel_hi:[1,0,1]
	s_nop 0
	v_pk_mul_f32 v[152:153], v[108:109], v[150:151] op_sel:[0,1]
	s_nop 0
	v_pk_fma_f32 v[152:153], v[106:107], v[150:151], v[152:153] op_sel_hi:[1,0,1]
	s_nop 0
	v_pk_mul_f32 v[154:155], v[108:109], v[152:153] op_sel:[0,1]
	s_nop 0
	v_pk_fma_f32 v[154:155], v[106:107], v[152:153], v[154:155] op_sel_hi:[1,0,1]
	s_nop 0
	v_pk_mul_f32 v[156:157], v[108:109], v[154:155] op_sel:[0,1]
	s_nop 0
	v_pk_fma_f32 v[156:157], v[106:107], v[154:155], v[156:157] op_sel_hi:[1,0,1]
	s_nop 0
	v_pk_mul_f32 v[158:159], v[108:109], v[156:157] op_sel:[0,1]
	s_nop 0
	v_pk_fma_f32 v[158:159], v[106:107], v[156:157], v[158:159] op_sel_hi:[1,0,1]
	s_nop 0
	v_pk_mul_f32 v[160:161], v[108:109], v[158:159] op_sel:[0,1]
	s_nop 0
	v_pk_fma_f32 v[160:161], v[106:107], v[158:159], v[160:161] op_sel_hi:[1,0,1]
	s_nop 0
	v_pk_mul_f32 v[162:163], v[108:109], v[160:161] op_sel:[0,1]
	s_nop 0
	v_pk_fma_f32 v[162:163], v[106:107], v[160:161], v[162:163] op_sel_hi:[1,0,1]
	s_nop 0
	v_pk_mul_f32 v[164:165], v[108:109], v[162:163] op_sel:[0,1]
	s_nop 0
	v_pk_fma_f32 v[164:165], v[106:107], v[162:163], v[164:165] op_sel_hi:[1,0,1]
	s_nop 0
	v_pk_mul_f32 v[166:167], v[108:109], v[164:165] op_sel:[0,1]
	s_waitcnt lgkmcnt(14)
	v_pk_mul_f32 v[108:109], v[108:109], v[174:175] op_sel:[0,1]
	v_pk_fma_f32 v[166:167], v[106:107], v[164:165], v[166:167] op_sel_hi:[1,0,1]
	v_pk_fma_f32 v[84:85], v[106:107], v[174:175], v[108:109] op_sel_hi:[1,0,1]
	v_xor_b32_e32 v168, 0x80000000, v167
	v_mov_b32_e32 v169, v166
	s_waitcnt lgkmcnt(0)
	v_pk_mul_f32 v[168:169], v[168:169], v[202:203] op_sel:[0,1]
	s_nop 0
	v_pk_fma_f32 v[138:139], v[166:167], v[202:203], v[168:169] op_sel_hi:[1,0,1]
	v_xor_b32_e32 v166, 0x80000000, v165
	v_mov_b32_e32 v167, v164
	v_pk_mul_f32 v[166:167], v[166:167], v[200:201] op_sel:[0,1]
	s_nop 0
	v_pk_fma_f32 v[136:137], v[164:165], v[200:201], v[166:167] op_sel_hi:[1,0,1]
	v_xor_b32_e32 v164, 0x80000000, v163
	v_mov_b32_e32 v165, v162
	v_pk_mul_f32 v[164:165], v[164:165], v[198:199] op_sel:[0,1]
	s_nop 0
	v_pk_fma_f32 v[112:113], v[162:163], v[198:199], v[164:165] op_sel_hi:[1,0,1]
	v_xor_b32_e32 v162, 0x80000000, v161
	v_mov_b32_e32 v163, v160
	v_pk_mul_f32 v[162:163], v[162:163], v[196:197] op_sel:[0,1]
	s_nop 0
	v_pk_fma_f32 v[110:111], v[160:161], v[196:197], v[162:163] op_sel_hi:[1,0,1]
	v_xor_b32_e32 v160, 0x80000000, v159
	v_mov_b32_e32 v161, v158
	v_pk_mul_f32 v[160:161], v[160:161], v[194:195] op_sel:[0,1]
	s_nop 0
	v_pk_fma_f32 v[104:105], v[158:159], v[194:195], v[160:161] op_sel_hi:[1,0,1]
	v_xor_b32_e32 v158, 0x80000000, v157
	v_mov_b32_e32 v159, v156
	v_pk_mul_f32 v[158:159], v[158:159], v[192:193] op_sel:[0,1]
	s_nop 0
	v_pk_fma_f32 v[102:103], v[156:157], v[192:193], v[158:159] op_sel_hi:[1,0,1]
	v_xor_b32_e32 v156, 0x80000000, v155
	v_mov_b32_e32 v157, v154
	v_pk_mul_f32 v[156:157], v[156:157], v[190:191] op_sel:[0,1]
	s_nop 0
	v_pk_fma_f32 v[100:101], v[154:155], v[190:191], v[156:157] op_sel_hi:[1,0,1]
	v_xor_b32_e32 v154, 0x80000000, v153
	v_mov_b32_e32 v155, v152
	v_pk_mul_f32 v[154:155], v[154:155], v[188:189] op_sel:[0,1]
	s_nop 0
	v_pk_fma_f32 v[98:99], v[152:153], v[188:189], v[154:155] op_sel_hi:[1,0,1]
	v_xor_b32_e32 v152, 0x80000000, v151
	v_mov_b32_e32 v153, v150
	v_pk_mul_f32 v[152:153], v[152:153], v[186:187] op_sel:[0,1]
	v_pk_add_f32 v[106:107], v[172:173], v[98:99]
	v_pk_fma_f32 v[96:97], v[150:151], v[186:187], v[152:153] op_sel_hi:[1,0,1]
	v_xor_b32_e32 v150, 0x80000000, v149
	v_mov_b32_e32 v151, v148
	v_pk_mul_f32 v[150:151], v[150:151], v[184:185] op_sel:[0,1]
	v_pk_add_f32 v[108:109], v[172:173], v[98:99] neg_lo:[0,1] neg_hi:[0,1]
	v_pk_fma_f32 v[94:95], v[148:149], v[184:185], v[150:151] op_sel_hi:[1,0,1]
	v_xor_b32_e32 v148, 0x80000000, v147
	v_mov_b32_e32 v149, v146
	v_pk_mul_f32 v[148:149], v[148:149], v[182:183] op_sel:[0,1]
	s_nop 0
	v_pk_fma_f32 v[92:93], v[146:147], v[182:183], v[148:149] op_sel_hi:[1,0,1]
	v_xor_b32_e32 v146, 0x80000000, v145
	v_mov_b32_e32 v147, v144
	v_pk_mul_f32 v[146:147], v[146:147], v[180:181] op_sel:[0,1]
	s_nop 0
	v_pk_fma_f32 v[90:91], v[144:145], v[180:181], v[146:147] op_sel_hi:[1,0,1]
	v_xor_b32_e32 v144, 0x80000000, v143
	v_mov_b32_e32 v145, v142
	v_pk_mul_f32 v[144:145], v[144:145], v[178:179] op_sel:[0,1]
	v_pk_add_f32 v[70:71], v[90:91], v[110:111]
	v_pk_fma_f32 v[88:89], v[142:143], v[178:179], v[144:145] op_sel_hi:[1,0,1]
	v_xor_b32_e32 v142, 0x80000000, v141
	v_mov_b32_e32 v143, v140
	v_pk_mul_f32 v[142:143], v[142:143], v[176:177] op_sel:[0,1]
	v_pk_add_f32 v[98:99], v[106:107], v[70:71]
	v_pk_fma_f32 v[86:87], v[140:141], v[176:177], v[142:143] op_sel_hi:[1,0,1]
	v_pk_add_f32 v[106:107], v[106:107], v[70:71] neg_lo:[0,1] neg_hi:[0,1]
	v_pk_add_f32 v[70:71], v[84:85], v[100:101]
	v_pk_add_f32 v[140:141], v[84:85], v[100:101] neg_lo:[0,1] neg_hi:[0,1]
	v_pk_add_f32 v[84:85], v[92:93], v[112:113]
	v_pk_add_f32 v[92:93], v[92:93], v[112:113] neg_lo:[0,1] neg_hi:[0,1]
	v_pk_add_f32 v[100:101], v[70:71], v[84:85]
	v_pk_add_f32 v[112:113], v[70:71], v[84:85] neg_lo:[0,1] neg_hi:[0,1]
	v_pk_add_f32 v[70:71], v[86:87], v[102:103]
	v_pk_add_f32 v[84:85], v[94:95], v[136:137]
	v_pk_add_f32 v[144:145], v[86:87], v[102:103] neg_lo:[0,1] neg_hi:[0,1]
	v_pk_add_f32 v[86:87], v[94:95], v[136:137] neg_lo:[0,1] neg_hi:[0,1]
	v_pk_add_f32 v[94:95], v[70:71], v[84:85]
	v_pk_add_f32 v[102:103], v[70:71], v[84:85] neg_lo:[0,1] neg_hi:[0,1]
	v_pk_add_f32 v[70:71], v[88:89], v[104:105]
	v_pk_add_f32 v[84:85], v[96:97], v[138:139]
	v_xor_b32_e32 v137, 0x80000000, v86
	v_mov_b32_e32 v136, v87
	v_pk_add_f32 v[148:149], v[88:89], v[104:105] neg_lo:[0,1] neg_hi:[0,1]
	v_pk_add_f32 v[86:87], v[96:97], v[138:139] neg_lo:[0,1] neg_hi:[0,1]
	v_pk_add_f32 v[88:89], v[70:71], v[84:85]
	v_xor_b32_e32 v143, 0x80000000, v92
	v_mov_b32_e32 v142, v93
	v_pk_add_f32 v[104:105], v[70:71], v[84:85] neg_lo:[0,1] neg_hi:[0,1]
	v_xor_b32_e32 v139, 0x80000000, v86
	v_mov_b32_e32 v138, v87
	v_pk_add_f32 v[70:71], v[98:99], v[94:95]
	v_pk_add_f32 v[84:85], v[100:101], v[88:89]
	v_pk_add_f32 v[86:87], v[100:101], v[88:89] neg_lo:[0,1] neg_hi:[0,1]
	v_pk_add_f32 v[92:93], v[140:141], v[142:143]
	v_pk_add_f32 v[94:95], v[98:99], v[94:95] neg_lo:[0,1] neg_hi:[0,1]
	v_pk_add_f32 v[88:89], v[70:71], v[84:85]
	v_pk_add_f32 v[84:85], v[70:71], v[84:85] neg_lo:[0,1] neg_hi:[0,1]
	v_xor_b32_e32 v71, 0x80000000, v86
	v_mov_b32_e32 v70, v87
	v_pk_add_f32 v[90:91], v[90:91], v[110:111] neg_lo:[0,1] neg_hi:[0,1]
	v_pk_add_f32 v[146:147], v[144:145], v[136:137]
	v_pk_add_f32 v[96:97], v[148:149], v[138:139]
	v_pk_add_f32 v[86:87], v[94:95], v[70:71]
	v_pk_add_f32 v[70:71], v[94:95], v[70:71] neg_lo:[0,1] neg_hi:[0,1]
	v_pk_mul_f32 v[94:95], v[92:93], s[28:29] op_sel:[1,0]
	v_xor_b32_e32 v111, 0x80000000, v90
	v_mov_b32_e32 v110, v91
	v_pk_fma_f32 v[92:93], v[92:93], s[26:27], v[94:95] op_sel_hi:[0,1,1]
	v_mul_f32_e32 v94, 0x3f3504f3, v147
	s_mov_b32 s29, s34
	v_pk_mul_f32 v[98:99], v[96:97], s[8:9] op_sel:[1,0]
	v_pk_add_f32 v[90:91], v[108:109], v[110:111]
	v_pk_fma_f32 v[94:95], v[146:147], s[30:31], v[94:95] op_sel_hi:[0,1,0]
	v_pk_fma_f32 v[96:97], v[96:97], s[28:29], v[98:99] op_sel_hi:[0,1,1]
	v_pk_add_f32 v[98:99], v[90:91], v[94:95]
	v_pk_add_f32 v[90:91], v[90:91], v[94:95] neg_lo:[0,1] neg_hi:[0,1]
	v_pk_add_f32 v[94:95], v[92:93], v[96:97]
	v_pk_add_f32 v[100:101], v[92:93], v[96:97] neg_lo:[0,1] neg_hi:[0,1]
	v_pk_add_f32 v[96:97], v[98:99], v[94:95]
	v_pk_add_f32 v[92:93], v[98:99], v[94:95] neg_lo:[0,1] neg_hi:[0,1]
	v_xor_b32_e32 v99, 0x80000000, v100
	v_mov_b32_e32 v98, v101
	v_pk_mul_f32 v[100:101], v[102:103], s[36:37] op_sel:[1,0]
	v_pk_add_f32 v[94:95], v[90:91], v[98:99]
	v_pk_add_f32 v[90:91], v[90:91], v[98:99] neg_lo:[0,1] neg_hi:[0,1]
	v_mul_f32_e32 v98, 0x3f3504f3, v113
	v_pk_fma_f32 v[100:101], v[102:103], s[20:21], v[100:101] op_sel_hi:[0,1,1]
	v_mul_f32_e32 v102, 0xbf3504f3, v104
	v_pk_fma_f32 v[98:99], v[112:113], s[30:31], v[98:99] op_sel_hi:[0,1,0]
	v_pk_fma_f32 v[102:103], v[104:105], s[30:31], v[102:103] op_sel:[1,0,0] op_sel_hi:[1,1,0]
	v_pk_add_f32 v[112:113], v[106:107], v[100:101]
	v_pk_add_f32 v[106:107], v[106:107], v[100:101] neg_lo:[0,1] neg_hi:[0,1]
	v_pk_add_f32 v[100:101], v[98:99], v[102:103]
	v_pk_add_f32 v[98:99], v[98:99], v[102:103] neg_lo:[0,1] neg_hi:[0,1]
	v_pk_add_f32 v[104:105], v[112:113], v[100:101]
	v_pk_add_f32 v[100:101], v[112:113], v[100:101] neg_lo:[0,1] neg_hi:[0,1]
	v_xor_b32_e32 v113, 0x80000000, v98
	v_mov_b32_e32 v112, v99
	v_pk_add_f32 v[102:103], v[106:107], v[112:113]
	v_pk_add_f32 v[98:99], v[106:107], v[112:113] neg_lo:[0,1] neg_hi:[0,1]
	v_pk_add_f32 v[106:107], v[148:149], v[138:139] neg_lo:[0,1] neg_hi:[0,1]
	v_pk_add_f32 v[108:109], v[108:109], v[110:111] neg_lo:[0,1] neg_hi:[0,1]
	v_pk_mul_f32 v[112:113], v[106:107], s[10:11] op_sel:[1,0]
	v_pk_add_f32 v[110:111], v[140:141], v[142:143] neg_lo:[0,1] neg_hi:[0,1]
	v_pk_fma_f32 v[106:107], v[106:107], s[34:35], v[112:113] op_sel_hi:[0,1,1]
	v_pk_mul_f32 v[112:113], v[110:111], s[8:9] op_sel:[1,0]
	s_nop 0
	v_pk_fma_f32 v[110:111], v[110:111], s[28:29], v[112:113] op_sel_hi:[0,1,1]
	v_pk_add_f32 v[112:113], v[144:145], v[136:137] neg_lo:[0,1] neg_hi:[0,1]
	v_pk_add_f32 v[138:139], v[110:111], v[106:107] neg_lo:[0,1] neg_hi:[0,1]
	v_mul_f32_e32 v134, 0xbf3504f3, v112
	v_pk_fma_f32 v[112:113], v[112:113], s[30:31], v[134:135] op_sel:[1,0,0] op_sel_hi:[1,1,0]
	s_nop 0
	v_pk_add_f32 v[136:137], v[108:109], v[112:113]
	v_pk_add_f32 v[112:113], v[108:109], v[112:113] neg_lo:[0,1] neg_hi:[0,1]
	v_pk_add_f32 v[108:109], v[110:111], v[106:107]
	s_nop 0
	v_pk_add_f32 v[110:111], v[136:137], v[108:109]
	v_pk_add_f32 v[106:107], v[136:137], v[108:109] neg_lo:[0,1] neg_hi:[0,1]
	v_xor_b32_e32 v137, 0x80000000, v138
	v_mov_b32_e32 v136, v139
	v_pk_add_f32 v[108:109], v[112:113], v[136:137]
	v_pk_add_f32 v[112:113], v[112:113], v[136:137] neg_lo:[0,1] neg_hi:[0,1]

.LBB0_1660:
	s_or_b64 exec, exec, s[6:7]
	s_waitcnt lgkmcnt(0)
	s_barrier
	s_and_saveexec_b64 s[6:7], vcc
	s_cbranch_execz .LBB0_1662
	ds_read_b64 v[176:177], v132 offset:32768
	v_cvt_f32_i32_e32 v84, v126
	v_lshlrev_b32_e32 v85, 3, v125
	v_add3_u32 v90, 0, v85, v133
	ds_read_b64 v[178:179], v90
	ds_read_b64 v[180:181], v131 offset:36864
	ds_read_b64 v[182:183], v122 offset:4096
	ds_read_b64 v[184:185], v130 offset:40960
	ds_read_b64 v[186:187], v116 offset:8192
	ds_read_b64 v[188:189], v129 offset:45056
	ds_read_b64 v[190:191], v63 offset:12288
	ds_read_b64 v[192:193], v128 offset:49152
	ds_read_b64 v[194:195], v31 offset:16384
	ds_read_b64 v[196:197], v127 offset:53248
	ds_read_b64 v[198:199], v23 offset:20480
	ds_read_b64 v[172:173], v115 offset:57344
	ds_read_b64 v[174:175], v15 offset:24576
	v_mul_f32_e32 v86, 0x39000000, v84
	v_sin_f32_e32 v84, v86
	v_cos_f32_e32 v86, v86
	v_cvt_f32_i32_e32 v65, v65
	v_xor_b32_e32 v87, 0x80000000, v84
	v_mov_b32_e32 v85, v86
	s_waitcnt lgkmcnt(14)
	s_waitcnt lgkmcnt(13)
	v_pk_mul_f32 v[84:85], v[84:85], v[176:177] op_sel:[0,1]
	v_cvt_f32_i32_e32 v59, v59
	v_pk_fma_f32 v[70:71], v[86:87], v[176:177], v[84:85] op_sel_hi:[1,0,1]
	v_cvt_f32_i32_e32 v86, v124
	s_waitcnt lgkmcnt(12)
	v_pk_add_f32 v[84:85], v[178:179], v[70:71]
	v_pk_add_f32 v[70:71], v[178:179], v[70:71] neg_lo:[0,1] neg_hi:[0,1]
	ds_write_b64 v90, v[84:85]
	ds_write_b64 v132, v[70:71] offset:32768
	v_mul_f32_e32 v71, 0x39000000, v86
	v_cos_f32_e32 v70, v71
	v_sin_f32_e32 v84, v71
	v_cvt_f32_i32_e32 v27, v27
	v_mov_b32_e32 v85, v70
	v_xor_b32_e32 v71, 0x80000000, v84
	s_waitcnt lgkmcnt(13)
	v_pk_mul_f32 v[84:85], v[84:85], v[180:181] op_sel:[0,1]
	v_cvt_f32_i32_e32 v19, v19
	v_pk_fma_f32 v[70:71], v[70:71], v[180:181], v[84:85] op_sel_hi:[1,0,1]
	v_cvt_f32_i32_e32 v86, v123
	s_waitcnt lgkmcnt(12)
	v_pk_add_f32 v[84:85], v[182:183], v[70:71]
	v_pk_add_f32 v[70:71], v[182:183], v[70:71] neg_lo:[0,1] neg_hi:[0,1]
	ds_write_b64 v122, v[84:85] offset:4096
	ds_write_b64 v131, v[70:71] offset:36864
	v_mul_f32_e32 v71, 0x39000000, v86
	v_cos_f32_e32 v70, v71
	v_sin_f32_e32 v84, v71
	s_nop 0
	v_mov_b32_e32 v85, v70
	v_xor_b32_e32 v71, 0x80000000, v84
	s_waitcnt lgkmcnt(13)
	v_pk_mul_f32 v[84:85], v[84:85], v[184:185] op_sel:[0,1]
	s_nop 0
	v_pk_fma_f32 v[70:71], v[70:71], v[184:185], v[84:85] op_sel_hi:[1,0,1]
	v_cvt_f32_i32_e32 v86, v117
	s_waitcnt lgkmcnt(12)
	v_pk_add_f32 v[84:85], v[186:187], v[70:71]
	v_pk_add_f32 v[70:71], v[186:187], v[70:71] neg_lo:[0,1] neg_hi:[0,1]
	ds_write_b64 v116, v[84:85] offset:8192
	ds_write_b64 v130, v[70:71] offset:40960
	v_mul_f32_e32 v71, 0x39000000, v86
	ds_read_b64 v[86:87], v114 offset:61440
	s_waitcnt lgkmcnt(14)
	ds_read_b64 v[88:89], v11 offset:28672
	v_cos_f32_e32 v70, v71
	v_sin_f32_e32 v84, v71
	s_nop 0
	v_mov_b32_e32 v85, v70
	v_xor_b32_e32 v71, 0x80000000, v84
	s_nop 0
	v_pk_mul_f32 v[84:85], v[84:85], v[188:189] op_sel:[0,1]
	s_nop 0
	v_pk_fma_f32 v[70:71], v[70:71], v[188:189], v[84:85] op_sel_hi:[1,0,1]
	s_waitcnt lgkmcnt(14)
	v_pk_add_f32 v[84:85], v[190:191], v[70:71]
	ds_write_b64 v63, v[84:85] offset:12288
	v_pk_add_f32 v[70:71], v[190:191], v[70:71] neg_lo:[0,1] neg_hi:[0,1]
	v_mul_f32_e32 v63, 0x39000000, v65
	s_waitcnt lgkmcnt(14)
	ds_write_b64 v129, v[70:71] offset:45056
	v_cos_f32_e32 v70, v63
	v_sin_f32_e32 v84, v63
	s_nop 0
	v_mov_b32_e32 v85, v70
	v_xor_b32_e32 v71, 0x80000000, v84
	s_nop 0
	v_pk_mul_f32 v[84:85], v[84:85], v[192:193] op_sel:[0,1]
	s_nop 0
	v_pk_fma_f32 v[70:71], v[70:71], v[192:193], v[84:85] op_sel_hi:[1,0,1]
	s_waitcnt lgkmcnt(14)
	v_pk_add_f32 v[84:85], v[194:195], v[70:71]
	ds_write_b64 v31, v[84:85] offset:16384
	v_pk_add_f32 v[70:71], v[194:195], v[70:71] neg_lo:[0,1] neg_hi:[0,1]
	v_mul_f32_e32 v31, 0x39000000, v59
	s_waitcnt lgkmcnt(14)
	ds_write_b64 v128, v[70:71] offset:49152
	v_cos_f32_e32 v70, v31
	v_sin_f32_e32 v84, v31
	s_nop 0
	v_mov_b32_e32 v85, v70
	v_xor_b32_e32 v71, 0x80000000, v84
	s_nop 0
	v_pk_mul_f32 v[84:85], v[84:85], v[196:197] op_sel:[0,1]
	s_nop 0
	v_pk_fma_f32 v[70:71], v[70:71], v[196:197], v[84:85] op_sel_hi:[1,0,1]
	s_waitcnt lgkmcnt(14)
	v_pk_add_f32 v[84:85], v[198:199], v[70:71]
	ds_write_b64 v23, v[84:85] offset:20480
	v_pk_add_f32 v[70:71], v[198:199], v[70:71] neg_lo:[0,1] neg_hi:[0,1]
	v_mul_f32_e32 v23, 0x39000000, v27
	s_waitcnt lgkmcnt(14)
	ds_write_b64 v127, v[70:71] offset:53248
	v_cos_f32_e32 v70, v23
	v_sin_f32_e32 v84, v23
	s_nop 0
	v_mov_b32_e32 v85, v70
	v_xor_b32_e32 v71, 0x80000000, v84
	s_nop 0
	v_pk_mul_f32 v[84:85], v[84:85], v[172:173] op_sel:[0,1]
	s_nop 0
	v_pk_fma_f32 v[70:71], v[70:71], v[172:173], v[84:85] op_sel_hi:[1,0,1]
	s_waitcnt lgkmcnt(14)
	v_pk_add_f32 v[84:85], v[174:175], v[70:71]
	ds_write_b64 v15, v[84:85] offset:24576
	v_pk_add_f32 v[70:71], v[174:175], v[70:71] neg_lo:[0,1] neg_hi:[0,1]
	v_mul_f32_e32 v15, 0x39000000, v19
	s_waitcnt lgkmcnt(14)
	ds_write_b64 v115, v[70:71] offset:57344
	v_cos_f32_e32 v70, v15
	v_sin_f32_e32 v84, v15
	s_nop 0
	v_mov_b32_e32 v85, v70
	v_xor_b32_e32 v71, 0x80000000, v84
	s_waitcnt lgkmcnt(9)
	v_pk_mul_f32 v[84:85], v[84:85], v[86:87] op_sel:[0,1]
	s_nop 0
	v_pk_fma_f32 v[70:71], v[70:71], v[86:87], v[84:85] op_sel_hi:[1,0,1]
	s_waitcnt lgkmcnt(8)
	v_pk_add_f32 v[84:85], v[88:89], v[70:71]
	v_pk_add_f32 v[70:71], v[88:89], v[70:71] neg_lo:[0,1] neg_hi:[0,1]
	ds_write_b64 v11, v[84:85] offset:28672
	ds_write_b64 v114, v[70:71] offset:61440

.LBB0_1669:
	s_or_b64 exec, exec, s[6:7]
	s_waitcnt lgkmcnt(0)
	s_barrier
	s_and_saveexec_b64 s[6:7], vcc
	s_cbranch_execz .LBB0_1671
	ds_read_b64 v[202:203], v27 offset:61440
	ds_read_b64 v[174:175], v63 offset:57344
	ds_read_b64 v[176:177], v117 offset:53248
	ds_read_b64 v[178:179], v124 offset:49152
	ds_read_b64 v[180:181], v127 offset:45056
	ds_read_b64 v[182:183], v129 offset:40960
	ds_read_b64 v[184:185], v134
	ds_read_b64 v[186:187], v125 offset:4096
	ds_read_b64 v[188:189], v122 offset:8192
	ds_read_b64 v[190:191], v65 offset:12288
	ds_read_b64 v[192:193], v31 offset:16384
	ds_read_b64 v[194:195], v19 offset:20480
	ds_read_b64 v[196:197], v11 offset:24576
	ds_read_b64 v[198:199], v7 offset:28672
	ds_read_b64 v[200:201], v133 offset:32768
	s_waitcnt lgkmcnt(14)
	ds_read_b64 v[172:173], v132 offset:36864
	v_and_b32_e32 v70, 15, v130
	v_cvt_f32_ubyte0_e32 v70, v70
	v_mul_f32_e32 v70, 0x3b800000, v70
	v_cos_f32_e32 v96, v70
	v_sin_f32_e32 v97, v70
	s_mov_b32 s10, s27
	v_mov_b32_e32 v99, v96
	v_xor_b32_e32 v98, 0x80000000, v97
	v_mov_b32_e32 v70, v97
	v_pk_mul_f32 v[70:71], v[98:99], v[70:71] op_sel_hi:[1,0]
	s_mov_b32 s11, s26
	v_pk_fma_f32 v[104:105], v[96:97], v[96:97], v[70:71] op_sel_hi:[1,0,1]
	s_mov_b32 s8, s26
	v_pk_mul_f32 v[70:71], v[98:99], v[104:105] op_sel:[0,1]
	s_mov_b32 s9, s28
	v_pk_fma_f32 v[108:109], v[96:97], v[104:105], v[70:71] op_sel_hi:[1,0,1]
	s_mov_b32 s35, s28
	v_pk_mul_f32 v[70:71], v[98:99], v[108:109] op_sel:[0,1]
	s_mov_b32 s29, s26
	v_pk_fma_f32 v[110:111], v[96:97], v[108:109], v[70:71] op_sel_hi:[1,0,1]
	s_mov_b32 s12, s21
	v_pk_mul_f32 v[70:71], v[98:99], v[110:111] op_sel:[0,1]
	s_mov_b32 s13, s20
	v_pk_fma_f32 v[112:113], v[96:97], v[110:111], v[70:71] op_sel_hi:[1,0,1]
	s_nop 0
	v_pk_mul_f32 v[70:71], v[98:99], v[112:113] op_sel:[0,1]
	s_nop 0
	v_pk_fma_f32 v[114:115], v[96:97], v[112:113], v[70:71] op_sel_hi:[1,0,1]
	s_nop 0
	v_pk_mul_f32 v[70:71], v[98:99], v[114:115] op_sel:[0,1]
	s_nop 0
	v_pk_fma_f32 v[136:137], v[96:97], v[114:115], v[70:71] op_sel_hi:[1,0,1]
	s_nop 0
	v_pk_mul_f32 v[70:71], v[98:99], v[136:137] op_sel:[0,1]
	s_nop 0
	v_pk_fma_f32 v[100:101], v[96:97], v[136:137], v[70:71] op_sel_hi:[1,0,1]
	s_nop 0
	v_pk_mul_f32 v[70:71], v[98:99], v[100:101] op_sel:[0,1]
	s_nop 0
	v_pk_fma_f32 v[84:85], v[96:97], v[100:101], v[70:71] op_sel_hi:[1,0,1]
	s_nop 0
	v_pk_mul_f32 v[70:71], v[98:99], v[84:85] op_sel:[0,1]
	s_nop 0
	v_pk_fma_f32 v[94:95], v[96:97], v[84:85], v[70:71] op_sel_hi:[1,0,1]
	s_nop 0
	v_pk_mul_f32 v[70:71], v[98:99], v[94:95] op_sel:[0,1]
	s_nop 0
	v_pk_fma_f32 v[90:91], v[96:97], v[94:95], v[70:71] op_sel_hi:[1,0,1]
	s_nop 0
	v_pk_mul_f32 v[70:71], v[98:99], v[90:91] op_sel:[0,1]
	s_nop 0
	v_pk_fma_f32 v[92:93], v[96:97], v[90:91], v[70:71] op_sel_hi:[1,0,1]
	s_nop 0
	v_pk_mul_f32 v[70:71], v[98:99], v[92:93] op_sel:[0,1]
	s_nop 0
	v_pk_fma_f32 v[88:89], v[96:97], v[92:93], v[70:71] op_sel_hi:[1,0,1]
	s_nop 0
	v_pk_mul_f32 v[70:71], v[98:99], v[88:89] op_sel:[0,1]
	s_nop 0
	v_pk_fma_f32 v[86:87], v[96:97], v[88:89], v[70:71] op_sel_hi:[1,0,1]
	s_nop 0
	v_pk_mul_f32 v[70:71], v[98:99], v[86:87] op_sel:[0,1]
	s_nop 0
	v_pk_fma_f32 v[70:71], v[96:97], v[86:87], v[70:71] op_sel_hi:[1,0,1]
	s_nop 0
	v_xor_b32_e32 v106, 0x80000000, v71
	v_mov_b32_e32 v107, v70
	s_waitcnt lgkmcnt(15)
	s_nop 0
	v_pk_mul_f32 v[106:107], v[106:107], v[202:203] op_sel:[0,1]
	s_nop 0
	v_pk_fma_f32 v[70:71], v[70:71], v[202:203], v[106:107] op_sel_hi:[1,0,1]
	v_xor_b32_e32 v106, 0x80000000, v87
	v_mov_b32_e32 v107, v86
	s_waitcnt lgkmcnt(14)
	v_pk_mul_f32 v[106:107], v[106:107], v[174:175] op_sel:[0,1]
	s_nop 0
	v_pk_fma_f32 v[86:87], v[86:87], v[174:175], v[106:107] op_sel_hi:[1,0,1]
	v_xor_b32_e32 v106, 0x80000000, v89
	v_mov_b32_e32 v107, v88
	s_waitcnt lgkmcnt(13)
	v_pk_mul_f32 v[106:107], v[106:107], v[176:177] op_sel:[0,1]
	s_nop 0
	v_pk_fma_f32 v[88:89], v[88:89], v[176:177], v[106:107] op_sel_hi:[1,0,1]
	v_xor_b32_e32 v106, 0x80000000, v93
	v_mov_b32_e32 v107, v92
	s_waitcnt lgkmcnt(12)
	v_pk_mul_f32 v[106:107], v[106:107], v[178:179] op_sel:[0,1]
	s_nop 0
	v_pk_fma_f32 v[92:93], v[92:93], v[178:179], v[106:107] op_sel_hi:[1,0,1]
	v_xor_b32_e32 v106, 0x80000000, v91
	v_mov_b32_e32 v107, v90
	s_waitcnt lgkmcnt(11)
	v_pk_mul_f32 v[106:107], v[106:107], v[180:181] op_sel:[0,1]
	s_nop 0
	v_pk_fma_f32 v[90:91], v[90:91], v[180:181], v[106:107] op_sel_hi:[1,0,1]
	v_xor_b32_e32 v106, 0x80000000, v95
	v_mov_b32_e32 v107, v94
	s_waitcnt lgkmcnt(10)
	v_pk_mul_f32 v[106:107], v[106:107], v[182:183] op_sel:[0,1]
	s_nop 0
	v_pk_fma_f32 v[94:95], v[94:95], v[182:183], v[106:107] op_sel_hi:[1,0,1]
	s_waitcnt lgkmcnt(8)
	v_pk_mul_f32 v[98:99], v[98:99], v[186:187] op_sel:[0,1]
	s_nop 0
	v_pk_fma_f32 v[102:103], v[96:97], v[186:187], v[98:99] op_sel_hi:[1,0,1]
	v_xor_b32_e32 v98, 0x80000000, v105
	v_mov_b32_e32 v99, v104
	s_waitcnt lgkmcnt(7)
	v_pk_mul_f32 v[98:99], v[98:99], v[188:189] op_sel:[0,1]
	s_nop 0
	v_pk_fma_f32 v[98:99], v[104:105], v[188:189], v[98:99] op_sel_hi:[1,0,1]
	v_xor_b32_e32 v104, 0x80000000, v109
	v_mov_b32_e32 v105, v108
	v_pk_add_f32 v[142:143], v[98:99], v[94:95] neg_lo:[0,1] neg_hi:[0,1]
	s_waitcnt lgkmcnt(6)
	v_pk_mul_f32 v[104:105], v[104:105], v[190:191] op_sel:[0,1]
	s_nop 0
	v_pk_fma_f32 v[96:97], v[108:109], v[190:191], v[104:105] op_sel_hi:[1,0,1]
	v_xor_b32_e32 v108, 0x80000000, v111
	v_mov_b32_e32 v109, v110
	v_pk_add_f32 v[146:147], v[96:97], v[90:91] neg_lo:[0,1] neg_hi:[0,1]
	s_waitcnt lgkmcnt(5)
	v_pk_mul_f32 v[108:109], v[108:109], v[192:193] op_sel:[0,1]
	s_nop 0
	v_pk_fma_f32 v[108:109], v[110:111], v[192:193], v[108:109] op_sel_hi:[1,0,1]
	v_xor_b32_e32 v110, 0x80000000, v113
	v_mov_b32_e32 v111, v112
	s_waitcnt lgkmcnt(4)
	v_pk_mul_f32 v[110:111], v[110:111], v[194:195] op_sel:[0,1]
	s_nop 0
	v_pk_fma_f32 v[110:111], v[112:113], v[194:195], v[110:111] op_sel_hi:[1,0,1]
	v_xor_b32_e32 v112, 0x80000000, v115
	v_mov_b32_e32 v113, v114
	s_waitcnt lgkmcnt(3)
	v_pk_mul_f32 v[112:113], v[112:113], v[196:197] op_sel:[0,1]
	s_nop 0
	v_pk_fma_f32 v[112:113], v[114:115], v[196:197], v[112:113] op_sel_hi:[1,0,1]
	v_xor_b32_e32 v114, 0x80000000, v137
	v_mov_b32_e32 v115, v136
	s_waitcnt lgkmcnt(2)
	v_pk_mul_f32 v[114:115], v[114:115], v[198:199] op_sel:[0,1]
	s_nop 0
	v_pk_fma_f32 v[104:105], v[136:137], v[198:199], v[114:115] op_sel_hi:[1,0,1]
	v_xor_b32_e32 v136, 0x80000000, v101
	v_mov_b32_e32 v137, v100
	s_waitcnt lgkmcnt(1)
	v_pk_mul_f32 v[136:137], v[136:137], v[200:201] op_sel:[0,1]
	s_nop 0
	v_pk_fma_f32 v[100:101], v[100:101], v[200:201], v[136:137] op_sel_hi:[1,0,1]
	v_xor_b32_e32 v136, 0x80000000, v85
	v_mov_b32_e32 v137, v84
	s_waitcnt lgkmcnt(0)
	v_pk_mul_f32 v[136:137], v[136:137], v[172:173] op_sel:[0,1]
	s_nop 0
	v_pk_fma_f32 v[84:85], v[84:85], v[172:173], v[136:137] op_sel_hi:[1,0,1]
	v_pk_add_f32 v[114:115], v[184:185], v[100:101]
	v_pk_add_f32 v[136:137], v[102:103], v[84:85]
	v_pk_add_f32 v[138:139], v[102:103], v[84:85] neg_lo:[0,1] neg_hi:[0,1]
	v_pk_add_f32 v[84:85], v[88:89], v[110:111]
	v_pk_add_f32 v[88:89], v[110:111], v[88:89] neg_lo:[0,1] neg_hi:[0,1]
	v_pk_add_f32 v[102:103], v[84:85], v[136:137]
	v_pk_add_f32 v[110:111], v[136:137], v[84:85] neg_lo:[0,1] neg_hi:[0,1]
	v_xor_b32_e32 v137, 0x80000000, v88
	v_mov_b32_e32 v136, v89
	v_pk_add_f32 v[84:85], v[94:95], v[98:99]
	v_pk_add_f32 v[88:89], v[86:87], v[112:113]
	v_pk_add_f32 v[86:87], v[112:113], v[86:87] neg_lo:[0,1] neg_hi:[0,1]
	v_pk_add_f32 v[94:95], v[84:85], v[88:89]
	v_pk_add_f32 v[98:99], v[84:85], v[88:89] neg_lo:[0,1] neg_hi:[0,1]
	v_xor_b32_e32 v113, 0x80000000, v86
	v_mov_b32_e32 v112, v87
	v_pk_add_f32 v[84:85], v[90:91], v[96:97]
	v_pk_add_f32 v[86:87], v[70:71], v[104:105]
	v_pk_add_f32 v[106:107], v[184:185], v[100:101] neg_lo:[0,1] neg_hi:[0,1]
	v_pk_add_f32 v[100:101], v[92:93], v[108:109]
	v_pk_add_f32 v[88:89], v[84:85], v[86:87]
	v_pk_add_f32 v[92:93], v[108:109], v[92:93] neg_lo:[0,1] neg_hi:[0,1]
	v_pk_add_f32 v[108:109], v[100:101], v[114:115]
	v_pk_add_f32 v[70:71], v[104:105], v[70:71] neg_lo:[0,1] neg_hi:[0,1]
	v_pk_add_f32 v[104:105], v[84:85], v[86:87] neg_lo:[0,1] neg_hi:[0,1]
	v_pk_add_f32 v[84:85], v[88:89], v[102:103]
	v_pk_add_f32 v[88:89], v[102:103], v[88:89] neg_lo:[0,1] neg_hi:[0,1]
	v_pk_add_f32 v[140:141], v[138:139], v[136:137] neg_lo:[0,1] neg_hi:[0,1]
	v_xor_b32_e32 v149, 0x80000000, v70
	v_mov_b32_e32 v148, v71
	v_pk_add_f32 v[70:71], v[94:95], v[108:109]
	v_pk_add_f32 v[94:95], v[108:109], v[94:95] neg_lo:[0,1] neg_hi:[0,1]
	v_xor_b32_e32 v97, 0x80000000, v88
	v_mov_b32_e32 v96, v89
	v_pk_add_f32 v[144:145], v[142:143], v[112:113] neg_lo:[0,1] neg_hi:[0,1]
	v_pk_add_f32 v[90:91], v[146:147], v[148:149] neg_lo:[0,1] neg_hi:[0,1]
	v_pk_add_f32 v[86:87], v[70:71], v[84:85]
	v_pk_add_f32 v[84:85], v[70:71], v[84:85] neg_lo:[0,1] neg_hi:[0,1]
	v_pk_add_f32 v[70:71], v[94:95], v[96:97]
	v_pk_add_f32 v[88:89], v[94:95], v[96:97] neg_lo:[0,1] neg_hi:[0,1]
	v_pk_mul_f32 v[94:95], v[140:141], s[10:11] op_sel:[1,0]
	v_pk_add_f32 v[100:101], v[114:115], v[100:101] neg_lo:[0,1] neg_hi:[0,1]
	v_xor_b32_e32 v115, 0x80000000, v92
	v_mov_b32_e32 v114, v93
	v_pk_fma_f32 v[94:95], v[140:141], s[8:9], v[94:95] op_sel_hi:[0,1,1]
	v_mul_f32_e32 v96, 0x3f3504f3, v144
	s_mov_b32 s8, s31
	s_mov_b32 s9, s30
	v_pk_mul_f32 v[102:103], v[90:91], s[34:35] op_sel:[1,0]
	v_pk_add_f32 v[92:93], v[106:107], v[114:115] neg_lo:[0,1] neg_hi:[0,1]
	v_pk_fma_f32 v[96:97], v[144:145], s[8:9], v[96:97] op_sel:[1,0,0] op_sel_hi:[1,1,0]
	v_pk_fma_f32 v[90:91], v[90:91], s[28:29], v[102:103] op_sel_hi:[0,1,1]
	v_pk_add_f32 v[102:103], v[92:93], v[96:97]
	v_pk_add_f32 v[96:97], v[92:93], v[96:97] neg_lo:[0,1] neg_hi:[0,1]
	v_pk_add_f32 v[92:93], v[94:95], v[90:91]
	v_pk_add_f32 v[90:91], v[94:95], v[90:91] neg_lo:[0,1] neg_hi:[0,1]
	v_pk_add_f32 v[94:95], v[102:103], v[92:93]
	v_pk_add_f32 v[92:93], v[102:103], v[92:93] neg_lo:[0,1] neg_hi:[0,1]
	v_xor_b32_e32 v103, 0x80000000, v90
	v_mov_b32_e32 v102, v91
	s_mov_b32 s10, s20
	s_mov_b32 s11, s36
	v_pk_mul_f32 v[108:109], v[98:99], s[12:13] op_sel:[1,0]
	v_pk_add_f32 v[90:91], v[96:97], v[102:103]
	v_pk_add_f32 v[96:97], v[96:97], v[102:103] neg_lo:[0,1] neg_hi:[0,1]
	v_mul_f32_e32 v102, 0x3f3504f3, v110
	v_pk_fma_f32 v[98:99], v[98:99], s[10:11], v[108:109] op_sel_hi:[0,1,1]
	v_mul_f32_e32 v108, 0xbf3504f3, v105
	v_pk_fma_f32 v[102:103], v[110:111], s[8:9], v[102:103] op_sel:[1,0,0] op_sel_hi:[1,1,0]
	v_pk_fma_f32 v[104:105], v[104:105], s[8:9], v[108:109] op_sel_hi:[0,1,0]
	v_pk_add_f32 v[108:109], v[100:101], v[98:99]
	v_pk_add_f32 v[110:111], v[100:101], v[98:99] neg_lo:[0,1] neg_hi:[0,1]
	v_pk_add_f32 v[98:99], v[104:105], v[102:103]
	v_pk_add_f32 v[104:105], v[102:103], v[104:105] neg_lo:[0,1] neg_hi:[0,1]
	v_pk_add_f32 v[102:103], v[108:109], v[98:99]
	v_pk_add_f32 v[100:101], v[108:109], v[98:99] neg_lo:[0,1] neg_hi:[0,1]
	v_xor_b32_e32 v109, 0x80000000, v104
	v_mov_b32_e32 v108, v105
	v_pk_add_f32 v[98:99], v[110:111], v[108:109]
	v_pk_add_f32 v[104:105], v[110:111], v[108:109] neg_lo:[0,1] neg_hi:[0,1]
	v_pk_add_f32 v[108:109], v[146:147], v[148:149]
	s_mov_b32 s12, s28
	s_mov_b32 s13, s34
	s_mov_b32 s10, s34
	s_mov_b32 s11, s27
	v_pk_mul_f32 v[110:111], v[108:109], s[12:13] op_sel:[1,0]
	v_pk_add_f32 v[106:107], v[114:115], v[106:107]
	v_pk_fma_f32 v[108:109], v[108:109], s[10:11], v[110:111] op_sel_hi:[0,1,1]
	v_pk_add_f32 v[110:111], v[136:137], v[138:139]
	v_pk_add_f32 v[112:113], v[142:143], v[112:113]
	v_pk_mul_f32 v[114:115], v[110:111], s[34:35] op_sel:[1,0]
	s_nop 0
	v_pk_fma_f32 v[110:111], v[110:111], s[28:29], v[114:115] op_sel_hi:[0,1,1]
	v_mul_f32_e32 v114, 0xbf3504f3, v113
	v_pk_fma_f32 v[112:113], v[112:113], s[8:9], v[114:115] op_sel_hi:[0,1,0]
	v_pk_add_f32 v[114:115], v[106:107], v[112:113]
	v_pk_add_f32 v[136:137], v[106:107], v[112:113] neg_lo:[0,1] neg_hi:[0,1]
	v_pk_add_f32 v[106:107], v[110:111], v[108:109]
	v_pk_add_f32 v[110:111], v[110:111], v[108:109] neg_lo:[0,1] neg_hi:[0,1]
	v_pk_add_f32 v[108:109], v[114:115], v[106:107]
	v_pk_add_f32 v[106:107], v[114:115], v[106:107] neg_lo:[0,1] neg_hi:[0,1]
	v_xor_b32_e32 v115, 0x80000000, v110
	v_mov_b32_e32 v114, v111
	v_pk_add_f32 v[112:113], v[136:137], v[114:115]
	v_pk_add_f32 v[110:111], v[136:137], v[114:115] neg_lo:[0,1] neg_hi:[0,1]

.LBB0_1673:
	s_or_b64 exec, exec, s[6:7]
	s_waitcnt lgkmcnt(0)
	s_barrier
	s_and_saveexec_b64 s[6:7], vcc
	s_cbranch_execz .LBB0_1675
	ds_read_b64 v[202:203], v27 offset:61440
	ds_read_b64 v[174:175], v63 offset:57344
	ds_read_b64 v[176:177], v117 offset:53248
	ds_read_b64 v[178:179], v124 offset:49152
	ds_read_b64 v[180:181], v127 offset:45056
	ds_read_b64 v[182:183], v129 offset:40960
	ds_read_b64 v[184:185], v134
	ds_read_b64 v[186:187], v125 offset:4096
	ds_read_b64 v[188:189], v122 offset:8192
	ds_read_b64 v[190:191], v65 offset:12288
	ds_read_b64 v[192:193], v31 offset:16384
	ds_read_b64 v[194:195], v19 offset:20480
	ds_read_b64 v[196:197], v11 offset:24576
	ds_read_b64 v[198:199], v7 offset:28672
	ds_read_b64 v[200:201], v133 offset:32768
	s_waitcnt lgkmcnt(14)
	ds_read_b64 v[172:173], v132 offset:36864
	v_cvt_f32_ubyte0_e32 v70, v130
	v_mul_f32_e32 v70, 0x39800000, v70
	v_cos_f32_e32 v96, v70
	v_sin_f32_e32 v97, v70
	s_mov_b32 s10, s27
	v_mov_b32_e32 v99, v96
	v_xor_b32_e32 v98, 0x80000000, v97
	v_mov_b32_e32 v70, v97
	v_pk_mul_f32 v[70:71], v[98:99], v[70:71] op_sel_hi:[1,0]
	s_mov_b32 s11, s26
	v_pk_fma_f32 v[104:105], v[96:97], v[96:97], v[70:71] op_sel_hi:[1,0,1]
	s_mov_b32 s8, s26
	v_pk_mul_f32 v[70:71], v[98:99], v[104:105] op_sel:[0,1]
	s_mov_b32 s9, s28
	v_pk_fma_f32 v[108:109], v[96:97], v[104:105], v[70:71] op_sel_hi:[1,0,1]
	s_mov_b32 s35, s28
	v_pk_mul_f32 v[70:71], v[98:99], v[108:109] op_sel:[0,1]
	s_mov_b32 s29, s26
	v_pk_fma_f32 v[110:111], v[96:97], v[108:109], v[70:71] op_sel_hi:[1,0,1]
	s_mov_b32 s12, s21
	v_pk_mul_f32 v[70:71], v[98:99], v[110:111] op_sel:[0,1]
	s_mov_b32 s13, s20
	v_pk_fma_f32 v[112:113], v[96:97], v[110:111], v[70:71] op_sel_hi:[1,0,1]
	s_nop 0
	v_pk_mul_f32 v[70:71], v[98:99], v[112:113] op_sel:[0,1]
	s_nop 0
	v_pk_fma_f32 v[136:137], v[96:97], v[112:113], v[70:71] op_sel_hi:[1,0,1]
	s_nop 0
	v_pk_mul_f32 v[70:71], v[98:99], v[136:137] op_sel:[0,1]
	s_nop 0
	v_pk_fma_f32 v[138:139], v[96:97], v[136:137], v[70:71] op_sel_hi:[1,0,1]
	s_nop 0
	v_pk_mul_f32 v[70:71], v[98:99], v[138:139] op_sel:[0,1]
	v_mov_b32_e32 v135, v138
	v_pk_fma_f32 v[100:101], v[96:97], v[138:139], v[70:71] op_sel_hi:[1,0,1]
	s_nop 0
	v_pk_mul_f32 v[70:71], v[98:99], v[100:101] op_sel:[0,1]
	s_nop 0
	v_pk_fma_f32 v[84:85], v[96:97], v[100:101], v[70:71] op_sel_hi:[1,0,1]
	s_nop 0
	v_pk_mul_f32 v[70:71], v[98:99], v[84:85] op_sel:[0,1]
	s_nop 0
	v_pk_fma_f32 v[94:95], v[96:97], v[84:85], v[70:71] op_sel_hi:[1,0,1]
	s_nop 0
	v_pk_mul_f32 v[70:71], v[98:99], v[94:95] op_sel:[0,1]
	s_nop 0
	v_pk_fma_f32 v[90:91], v[96:97], v[94:95], v[70:71] op_sel_hi:[1,0,1]
	s_nop 0
	v_pk_mul_f32 v[70:71], v[98:99], v[90:91] op_sel:[0,1]
	s_nop 0
	v_pk_fma_f32 v[92:93], v[96:97], v[90:91], v[70:71] op_sel_hi:[1,0,1]
	s_nop 0
	v_pk_mul_f32 v[70:71], v[98:99], v[92:93] op_sel:[0,1]
	s_nop 0
	v_pk_fma_f32 v[88:89], v[96:97], v[92:93], v[70:71] op_sel_hi:[1,0,1]
	s_nop 0
	v_pk_mul_f32 v[70:71], v[98:99], v[88:89] op_sel:[0,1]
	s_nop 0
	v_pk_fma_f32 v[86:87], v[96:97], v[88:89], v[70:71] op_sel_hi:[1,0,1]
	s_nop 0
	v_pk_mul_f32 v[70:71], v[98:99], v[86:87] op_sel:[0,1]
	s_nop 0
	v_pk_fma_f32 v[70:71], v[96:97], v[86:87], v[70:71] op_sel_hi:[1,0,1]
	s_nop 0
	v_xor_b32_e32 v106, 0x80000000, v71
	v_mov_b32_e32 v107, v70
	s_waitcnt lgkmcnt(15)
	s_nop 0
	v_pk_mul_f32 v[106:107], v[106:107], v[202:203] op_sel:[0,1]
	s_nop 0
	v_pk_fma_f32 v[70:71], v[70:71], v[202:203], v[106:107] op_sel_hi:[1,0,1]
	v_xor_b32_e32 v106, 0x80000000, v87
	v_mov_b32_e32 v107, v86
	s_waitcnt lgkmcnt(14)
	v_pk_mul_f32 v[106:107], v[106:107], v[174:175] op_sel:[0,1]
	s_nop 0
	v_pk_fma_f32 v[86:87], v[86:87], v[174:175], v[106:107] op_sel_hi:[1,0,1]
	v_xor_b32_e32 v106, 0x80000000, v89
	v_mov_b32_e32 v107, v88
	s_waitcnt lgkmcnt(13)
	v_pk_mul_f32 v[106:107], v[106:107], v[176:177] op_sel:[0,1]
	s_nop 0
	v_pk_fma_f32 v[88:89], v[88:89], v[176:177], v[106:107] op_sel_hi:[1,0,1]
	v_xor_b32_e32 v106, 0x80000000, v93
	v_mov_b32_e32 v107, v92
	s_waitcnt lgkmcnt(12)
	v_pk_mul_f32 v[106:107], v[106:107], v[178:179] op_sel:[0,1]
	s_nop 0
	v_pk_fma_f32 v[92:93], v[92:93], v[178:179], v[106:107] op_sel_hi:[1,0,1]
	v_xor_b32_e32 v106, 0x80000000, v91
	v_mov_b32_e32 v107, v90
	s_waitcnt lgkmcnt(11)
	v_pk_mul_f32 v[106:107], v[106:107], v[180:181] op_sel:[0,1]
	s_nop 0
	v_pk_fma_f32 v[90:91], v[90:91], v[180:181], v[106:107] op_sel_hi:[1,0,1]
	v_xor_b32_e32 v106, 0x80000000, v95
	v_mov_b32_e32 v107, v94
	s_waitcnt lgkmcnt(10)
	v_pk_mul_f32 v[106:107], v[106:107], v[182:183] op_sel:[0,1]
	s_nop 0
	v_pk_fma_f32 v[94:95], v[94:95], v[182:183], v[106:107] op_sel_hi:[1,0,1]
	v_xor_b32_e32 v134, 0x80000000, v139
	s_waitcnt lgkmcnt(8)
	v_pk_mul_f32 v[98:99], v[98:99], v[186:187] op_sel:[0,1]
	s_nop 0
	v_pk_fma_f32 v[102:103], v[96:97], v[186:187], v[98:99] op_sel_hi:[1,0,1]
	v_xor_b32_e32 v98, 0x80000000, v105
	v_mov_b32_e32 v99, v104
	s_waitcnt lgkmcnt(7)
	v_pk_mul_f32 v[98:99], v[98:99], v[188:189] op_sel:[0,1]
	s_nop 0
	v_pk_fma_f32 v[98:99], v[104:105], v[188:189], v[98:99] op_sel_hi:[1,0,1]
	v_xor_b32_e32 v104, 0x80000000, v109
	v_mov_b32_e32 v105, v108
	v_pk_add_f32 v[142:143], v[98:99], v[94:95] neg_lo:[0,1] neg_hi:[0,1]
	s_waitcnt lgkmcnt(6)
	v_pk_mul_f32 v[104:105], v[104:105], v[190:191] op_sel:[0,1]
	s_nop 0
	v_pk_fma_f32 v[96:97], v[108:109], v[190:191], v[104:105] op_sel_hi:[1,0,1]
	v_xor_b32_e32 v108, 0x80000000, v111
	v_mov_b32_e32 v109, v110
	v_pk_add_f32 v[146:147], v[96:97], v[90:91] neg_lo:[0,1] neg_hi:[0,1]
	s_waitcnt lgkmcnt(5)
	v_pk_mul_f32 v[108:109], v[108:109], v[192:193] op_sel:[0,1]
	s_nop 0
	v_pk_fma_f32 v[108:109], v[110:111], v[192:193], v[108:109] op_sel_hi:[1,0,1]
	v_xor_b32_e32 v110, 0x80000000, v113
	v_mov_b32_e32 v111, v112
	s_waitcnt lgkmcnt(4)
	v_pk_mul_f32 v[110:111], v[110:111], v[194:195] op_sel:[0,1]
	s_nop 0
	v_pk_fma_f32 v[110:111], v[112:113], v[194:195], v[110:111] op_sel_hi:[1,0,1]
	v_xor_b32_e32 v112, 0x80000000, v137
	v_mov_b32_e32 v113, v136
	s_waitcnt lgkmcnt(3)
	v_pk_mul_f32 v[112:113], v[112:113], v[196:197] op_sel:[0,1]
	s_nop 0
	v_pk_fma_f32 v[112:113], v[136:137], v[196:197], v[112:113] op_sel_hi:[1,0,1]
	v_xor_b32_e32 v136, 0x80000000, v101
	v_mov_b32_e32 v137, v100
	s_waitcnt lgkmcnt(2)
	v_pk_mul_f32 v[134:135], v[134:135], v[198:199] op_sel:[0,1]
	s_nop 0
	v_pk_fma_f32 v[104:105], v[138:139], v[198:199], v[134:135] op_sel_hi:[1,0,1]
	s_waitcnt lgkmcnt(1)
	v_pk_mul_f32 v[136:137], v[136:137], v[200:201] op_sel:[0,1]
	s_nop 0
	v_pk_fma_f32 v[100:101], v[100:101], v[200:201], v[136:137] op_sel_hi:[1,0,1]
	v_xor_b32_e32 v136, 0x80000000, v85
	v_mov_b32_e32 v137, v84
	s_waitcnt lgkmcnt(0)
	v_pk_mul_f32 v[136:137], v[136:137], v[172:173] op_sel:[0,1]
	s_nop 0
	v_pk_fma_f32 v[84:85], v[84:85], v[172:173], v[136:137] op_sel_hi:[1,0,1]
	v_pk_add_f32 v[134:135], v[184:185], v[100:101]
	v_pk_add_f32 v[136:137], v[102:103], v[84:85]
	v_pk_add_f32 v[138:139], v[102:103], v[84:85] neg_lo:[0,1] neg_hi:[0,1]
	v_pk_add_f32 v[84:85], v[88:89], v[110:111]
	v_pk_add_f32 v[88:89], v[110:111], v[88:89] neg_lo:[0,1] neg_hi:[0,1]
	v_pk_add_f32 v[102:103], v[84:85], v[136:137]
	v_pk_add_f32 v[110:111], v[136:137], v[84:85] neg_lo:[0,1] neg_hi:[0,1]
	v_xor_b32_e32 v137, 0x80000000, v88
	v_mov_b32_e32 v136, v89
	v_pk_add_f32 v[84:85], v[94:95], v[98:99]
	v_pk_add_f32 v[88:89], v[86:87], v[112:113]
	v_pk_add_f32 v[86:87], v[112:113], v[86:87] neg_lo:[0,1] neg_hi:[0,1]
	v_pk_add_f32 v[94:95], v[84:85], v[88:89]
	v_pk_add_f32 v[98:99], v[84:85], v[88:89] neg_lo:[0,1] neg_hi:[0,1]
	v_xor_b32_e32 v113, 0x80000000, v86
	v_mov_b32_e32 v112, v87
	v_pk_add_f32 v[84:85], v[90:91], v[96:97]
	v_pk_add_f32 v[86:87], v[70:71], v[104:105]
	v_pk_add_f32 v[106:107], v[184:185], v[100:101] neg_lo:[0,1] neg_hi:[0,1]
	v_pk_add_f32 v[100:101], v[92:93], v[108:109]
	v_pk_add_f32 v[88:89], v[84:85], v[86:87]
	v_pk_add_f32 v[92:93], v[108:109], v[92:93] neg_lo:[0,1] neg_hi:[0,1]
	v_pk_add_f32 v[108:109], v[100:101], v[134:135]
	v_pk_add_f32 v[70:71], v[104:105], v[70:71] neg_lo:[0,1] neg_hi:[0,1]
	v_pk_add_f32 v[104:105], v[84:85], v[86:87] neg_lo:[0,1] neg_hi:[0,1]
	v_pk_add_f32 v[84:85], v[88:89], v[102:103]
	v_pk_add_f32 v[88:89], v[102:103], v[88:89] neg_lo:[0,1] neg_hi:[0,1]
	v_pk_add_f32 v[140:141], v[138:139], v[136:137] neg_lo:[0,1] neg_hi:[0,1]
	v_xor_b32_e32 v149, 0x80000000, v70
	v_mov_b32_e32 v148, v71
	v_pk_add_f32 v[70:71], v[94:95], v[108:109]
	v_pk_add_f32 v[94:95], v[108:109], v[94:95] neg_lo:[0,1] neg_hi:[0,1]
	v_xor_b32_e32 v97, 0x80000000, v88
	v_mov_b32_e32 v96, v89
	v_pk_add_f32 v[144:145], v[142:143], v[112:113] neg_lo:[0,1] neg_hi:[0,1]
	v_pk_add_f32 v[90:91], v[146:147], v[148:149] neg_lo:[0,1] neg_hi:[0,1]
	v_pk_add_f32 v[86:87], v[70:71], v[84:85]
	v_pk_add_f32 v[84:85], v[70:71], v[84:85] neg_lo:[0,1] neg_hi:[0,1]
	v_pk_add_f32 v[70:71], v[94:95], v[96:97]
	v_pk_add_f32 v[88:89], v[94:95], v[96:97] neg_lo:[0,1] neg_hi:[0,1]
	v_pk_mul_f32 v[94:95], v[140:141], s[10:11] op_sel:[1,0]
	v_pk_add_f32 v[100:101], v[134:135], v[100:101] neg_lo:[0,1] neg_hi:[0,1]
	v_xor_b32_e32 v135, 0x80000000, v92
	v_mov_b32_e32 v134, v93
	v_pk_fma_f32 v[94:95], v[140:141], s[8:9], v[94:95] op_sel_hi:[0,1,1]
	v_mul_f32_e32 v96, 0x3f3504f3, v144
	s_mov_b32 s8, s31
	s_mov_b32 s9, s30
	v_pk_mul_f32 v[102:103], v[90:91], s[34:35] op_sel:[1,0]
	v_pk_add_f32 v[92:93], v[106:107], v[134:135] neg_lo:[0,1] neg_hi:[0,1]
	v_pk_fma_f32 v[96:97], v[144:145], s[8:9], v[96:97] op_sel:[1,0,0] op_sel_hi:[1,1,0]
	v_pk_fma_f32 v[90:91], v[90:91], s[28:29], v[102:103] op_sel_hi:[0,1,1]
	v_pk_add_f32 v[102:103], v[92:93], v[96:97]
	v_pk_add_f32 v[96:97], v[92:93], v[96:97] neg_lo:[0,1] neg_hi:[0,1]
	v_pk_add_f32 v[92:93], v[94:95], v[90:91]
	v_pk_add_f32 v[90:91], v[94:95], v[90:91] neg_lo:[0,1] neg_hi:[0,1]
	v_pk_add_f32 v[94:95], v[102:103], v[92:93]
	v_pk_add_f32 v[92:93], v[102:103], v[92:93] neg_lo:[0,1] neg_hi:[0,1]
	v_xor_b32_e32 v103, 0x80000000, v90
	v_mov_b32_e32 v102, v91
	s_mov_b32 s10, s20
	s_mov_b32 s11, s36
	v_pk_mul_f32 v[108:109], v[98:99], s[12:13] op_sel:[1,0]
	v_pk_add_f32 v[90:91], v[96:97], v[102:103]
	v_pk_add_f32 v[96:97], v[96:97], v[102:103] neg_lo:[0,1] neg_hi:[0,1]
	v_mul_f32_e32 v102, 0x3f3504f3, v110
	v_pk_fma_f32 v[98:99], v[98:99], s[10:11], v[108:109] op_sel_hi:[0,1,1]
	v_mul_f32_e32 v108, 0xbf3504f3, v105
	v_pk_fma_f32 v[102:103], v[110:111], s[8:9], v[102:103] op_sel:[1,0,0] op_sel_hi:[1,1,0]
	v_pk_fma_f32 v[104:105], v[104:105], s[8:9], v[108:109] op_sel_hi:[0,1,0]
	v_pk_add_f32 v[108:109], v[100:101], v[98:99]
	v_pk_add_f32 v[110:111], v[100:101], v[98:99] neg_lo:[0,1] neg_hi:[0,1]
	v_pk_add_f32 v[98:99], v[104:105], v[102:103]
	v_pk_add_f32 v[104:105], v[102:103], v[104:105] neg_lo:[0,1] neg_hi:[0,1]
	v_pk_add_f32 v[102:103], v[108:109], v[98:99]
	v_pk_add_f32 v[100:101], v[108:109], v[98:99] neg_lo:[0,1] neg_hi:[0,1]
	v_xor_b32_e32 v109, 0x80000000, v104
	v_mov_b32_e32 v108, v105
	v_pk_add_f32 v[98:99], v[110:111], v[108:109]
	v_pk_add_f32 v[104:105], v[110:111], v[108:109] neg_lo:[0,1] neg_hi:[0,1]
	v_pk_add_f32 v[108:109], v[146:147], v[148:149]
	s_mov_b32 s12, s28
	s_mov_b32 s13, s34
	s_mov_b32 s10, s34
	s_mov_b32 s11, s27
	v_pk_mul_f32 v[110:111], v[108:109], s[12:13] op_sel:[1,0]
	v_pk_add_f32 v[106:107], v[134:135], v[106:107]
	v_pk_fma_f32 v[108:109], v[108:109], s[10:11], v[110:111] op_sel_hi:[0,1,1]
	v_pk_add_f32 v[110:111], v[136:137], v[138:139]
	v_pk_add_f32 v[112:113], v[142:143], v[112:113]
	v_pk_mul_f32 v[134:135], v[110:111], s[34:35] op_sel:[1,0]
	s_nop 0
	v_pk_fma_f32 v[110:111], v[110:111], s[28:29], v[134:135] op_sel_hi:[0,1,1]
	v_mul_f32_e32 v134, 0xbf3504f3, v113
	v_pk_fma_f32 v[112:113], v[112:113], s[8:9], v[134:135] op_sel_hi:[0,1,0]
	v_pk_add_f32 v[134:135], v[106:107], v[112:113]
	v_pk_add_f32 v[136:137], v[106:107], v[112:113] neg_lo:[0,1] neg_hi:[0,1]
	v_pk_add_f32 v[106:107], v[110:111], v[108:109]
	v_pk_add_f32 v[110:111], v[110:111], v[108:109] neg_lo:[0,1] neg_hi:[0,1]
	v_pk_add_f32 v[108:109], v[134:135], v[106:107]
	v_pk_add_f32 v[106:107], v[134:135], v[106:107] neg_lo:[0,1] neg_hi:[0,1]
	v_xor_b32_e32 v135, 0x80000000, v110
	v_mov_b32_e32 v134, v111
	v_pk_add_f32 v[112:113], v[136:137], v[134:135]
	v_pk_add_f32 v[110:111], v[136:137], v[134:135] neg_lo:[0,1] neg_hi:[0,1]

.LBB0_1677:
	s_or_b64 exec, exec, s[6:7]
	s_waitcnt lgkmcnt(0)
	s_barrier
	s_and_saveexec_b64 s[6:7], vcc
	s_cbranch_execz .LBB0_1679
	ds_read_b64 v[176:177], v133 offset:32768
	v_cvt_f32_i32_e32 v84, v130
	v_lshlrev_b32_e32 v86, 3, v131
	v_lshlrev_b32_e32 v87, 3, v130
	v_mul_f32_e32 v84, 0x39000000, v84
	v_sin_f32_e32 v85, v84
	v_cos_f32_e32 v84, v84
	v_add3_u32 v90, 0, v86, v87
	ds_read_b64 v[178:179], v90
	ds_read_b64 v[180:181], v132 offset:36864
	ds_read_b64 v[182:183], v125 offset:4096
	ds_read_b64 v[184:185], v129 offset:40960
	ds_read_b64 v[186:187], v122 offset:8192
	ds_read_b64 v[188:189], v127 offset:45056
	ds_read_b64 v[190:191], v65 offset:12288
	ds_read_b64 v[192:193], v124 offset:49152
	ds_read_b64 v[194:195], v31 offset:16384
	ds_read_b64 v[196:197], v117 offset:53248
	ds_read_b64 v[198:199], v19 offset:20480
	ds_read_b64 v[172:173], v63 offset:57344
	ds_read_b64 v[174:175], v11 offset:24576
	v_xor_b32_e32 v88, 0x80000000, v85
	v_mov_b32_e32 v89, v84
	v_cvt_f32_i32_e32 v91, v128
	s_waitcnt lgkmcnt(14)
	s_waitcnt lgkmcnt(13)
	v_pk_mul_f32 v[88:89], v[88:89], v[176:177] op_sel:[0,1]
	v_cvt_f32_i32_e32 v59, v59
	v_pk_fma_f32 v[70:71], v[84:85], v[176:177], v[88:89] op_sel_hi:[1,0,1]
	ds_read_b64 v[84:85], v27 offset:61440
	ds_read_b64 v[86:87], v7 offset:28672
	v_cvt_f32_i32_e32 v23, v23
	s_waitcnt lgkmcnt(14)
	v_pk_add_f32 v[70:71], v[178:179], v[70:71]
	ds_write_b64 v90, v[70:71]
	v_mul_f32_e32 v71, 0x39000000, v91
	v_cos_f32_e32 v70, v71
	v_sin_f32_e32 v71, v71
	v_cvt_f32_i32_e32 v90, v126
	v_mov_b32_e32 v89, v70
	v_xor_b32_e32 v88, 0x80000000, v71
	s_waitcnt lgkmcnt(14)
	v_pk_mul_f32 v[88:89], v[88:89], v[180:181] op_sel:[0,1]
	v_cvt_f32_i32_e32 v15, v15
	v_pk_fma_f32 v[70:71], v[70:71], v[180:181], v[88:89] op_sel_hi:[1,0,1]
	s_waitcnt lgkmcnt(13)
	v_pk_add_f32 v[70:71], v[182:183], v[70:71]
	ds_write_b64 v125, v[70:71] offset:4096
	v_mul_f32_e32 v71, 0x39000000, v90
	v_cos_f32_e32 v70, v71
	v_sin_f32_e32 v71, v71
	v_cvt_f32_i32_e32 v90, v123
	v_mov_b32_e32 v89, v70
	v_xor_b32_e32 v88, 0x80000000, v71
	s_waitcnt lgkmcnt(13)
	v_pk_mul_f32 v[88:89], v[88:89], v[184:185] op_sel:[0,1]
	s_nop 0
	v_pk_fma_f32 v[70:71], v[70:71], v[184:185], v[88:89] op_sel_hi:[1,0,1]
	s_waitcnt lgkmcnt(12)
	v_pk_add_f32 v[70:71], v[186:187], v[70:71]
	ds_write_b64 v122, v[70:71] offset:8192
	v_mul_f32_e32 v71, 0x39000000, v90
	v_cos_f32_e32 v70, v71
	v_sin_f32_e32 v71, v71
	v_cvt_f32_i32_e32 v90, v116
	v_mov_b32_e32 v89, v70
	v_xor_b32_e32 v88, 0x80000000, v71
	s_waitcnt lgkmcnt(12)
	v_pk_mul_f32 v[88:89], v[88:89], v[188:189] op_sel:[0,1]
	s_nop 0
	v_pk_fma_f32 v[70:71], v[70:71], v[188:189], v[88:89] op_sel_hi:[1,0,1]
	s_waitcnt lgkmcnt(11)
	v_pk_add_f32 v[70:71], v[190:191], v[70:71]
	ds_write_b64 v65, v[70:71] offset:12288
	v_mul_f32_e32 v65, 0x39000000, v90
	v_cos_f32_e32 v70, v65
	v_sin_f32_e32 v71, v65
	s_nop 0
	v_mov_b32_e32 v89, v70
	v_xor_b32_e32 v88, 0x80000000, v71
	s_waitcnt lgkmcnt(11)
	v_pk_mul_f32 v[88:89], v[88:89], v[192:193] op_sel:[0,1]
	s_nop 0
	v_pk_fma_f32 v[70:71], v[70:71], v[192:193], v[88:89] op_sel_hi:[1,0,1]
	s_waitcnt lgkmcnt(10)
	v_pk_add_f32 v[70:71], v[194:195], v[70:71]
	ds_write_b64 v31, v[70:71] offset:16384
	v_mul_f32_e32 v31, 0x39000000, v59
	v_cos_f32_e32 v70, v31
	v_sin_f32_e32 v71, v31
	s_nop 0
	v_mov_b32_e32 v89, v70
	v_xor_b32_e32 v88, 0x80000000, v71
	s_waitcnt lgkmcnt(10)
	v_pk_mul_f32 v[88:89], v[88:89], v[196:197] op_sel:[0,1]
	s_nop 0
	v_pk_fma_f32 v[70:71], v[70:71], v[196:197], v[88:89] op_sel_hi:[1,0,1]
	s_waitcnt lgkmcnt(9)
	v_pk_add_f32 v[70:71], v[198:199], v[70:71]
	ds_write_b64 v19, v[70:71] offset:20480
	v_mul_f32_e32 v19, 0x39000000, v23
	v_cos_f32_e32 v70, v19
	v_sin_f32_e32 v71, v19
	s_nop 0
	v_mov_b32_e32 v89, v70
	v_xor_b32_e32 v88, 0x80000000, v71
	s_waitcnt lgkmcnt(9)
	v_pk_mul_f32 v[88:89], v[88:89], v[172:173] op_sel:[0,1]
	s_nop 0
	v_pk_fma_f32 v[70:71], v[70:71], v[172:173], v[88:89] op_sel_hi:[1,0,1]
	s_waitcnt lgkmcnt(8)
	v_pk_add_f32 v[70:71], v[174:175], v[70:71]
	ds_write_b64 v11, v[70:71] offset:24576
	v_mul_f32_e32 v11, 0x39000000, v15
	v_cos_f32_e32 v70, v11
	v_sin_f32_e32 v71, v11
	s_nop 0
	v_mov_b32_e32 v89, v70
	v_xor_b32_e32 v88, 0x80000000, v71
	s_waitcnt lgkmcnt(8)
	v_pk_mul_f32 v[88:89], v[88:89], v[84:85] op_sel:[0,1]
	s_nop 0
	v_pk_fma_f32 v[70:71], v[70:71], v[84:85], v[88:89] op_sel_hi:[1,0,1]
	s_waitcnt lgkmcnt(7)
	v_pk_add_f32 v[70:71], v[86:87], v[70:71]
	ds_write_b64 v7, v[70:71] offset:28672

.LBB0_2026:
	s_mov_b64 s[12:13], exec
	v_readlane_b32 s1, v239, 2
	s_lshl_b32 s1, s1, 8
	v_mbcnt_lo_u32_b32 v1, s12, 0
	s_add_u32 s10, s96, s1
	v_mbcnt_hi_u32_b32 v1, s13, v1
	s_addc_u32 s11, s97, 0
	v_cmp_eq_u32_e32 vcc, 0, v1
	s_and_saveexec_b64 s[14:15], vcc
	s_cbranch_execz .LBB0_2028
	s_bcnt1_i32_b64 s1, s[12:13]
	v_mov_b32_e32 v3, 0x1000
	v_mov_b32_e32 v4, s1
	buffer_inv sc1
	global_atomic_add v3, v3, v4, s[10:11] offset:1024 sc0

.LBB0_2041:
	s_or_b64 exec, exec, s[14:15]
	s_waitcnt vmcnt(0)
	s_waitcnt vmcnt(0)

.LBB0_2059:
	s_or_b64 exec, exec, s[12:13]
	s_mov_b64 s[12:13], exec
	v_mbcnt_lo_u32_b32 v0, s12, 0
	v_mbcnt_hi_u32_b32 v0, s13, v0
	v_cmp_eq_u32_e32 vcc, 0, v0
	s_waitcnt vmcnt(0)
	s_and_saveexec_b64 s[14:15], vcc
	s_cbranch_execz .LBB0_2061
	s_bcnt1_i32_b64 s1, s[12:13]
	v_mov_b32_e32 v0, 0x2000
	v_mov_b32_e32 v1, s1
	global_atomic_add v0, v1, s[10:11] offset:1024

.LBB0_2118:
	s_mov_b64 s[14:15], exec
	v_readlane_b32 s1, v239, 2
	s_lshl_b32 s1, s1, 8
	v_mbcnt_lo_u32_b32 v1, s14, 0
	s_add_u32 s12, s96, s1
	v_mbcnt_hi_u32_b32 v1, s15, v1
	s_addc_u32 s13, s97, 0
	v_cmp_eq_u32_e32 vcc, 0, v1
	s_and_saveexec_b64 s[16:17], vcc
	s_cbranch_execz .LBB0_2120
	s_bcnt1_i32_b64 s1, s[14:15]
	v_mov_b32_e32 v3, 0x1000
	v_mov_b32_e32 v4, s1
	buffer_inv sc1
	global_atomic_add v3, v3, v4, s[12:13] offset:1024 sc0

.LBB0_2133:
	s_or_b64 exec, exec, s[16:17]
	s_waitcnt vmcnt(0)
	s_waitcnt vmcnt(0)

.LBB0_2151:
	s_or_b64 exec, exec, s[14:15]
	s_mov_b64 s[14:15], exec
	v_mbcnt_lo_u32_b32 v0, s14, 0
	v_mbcnt_hi_u32_b32 v0, s15, v0
	v_cmp_eq_u32_e32 vcc, 0, v0
	s_waitcnt vmcnt(0)
	s_and_saveexec_b64 s[16:17], vcc
	s_cbranch_execz .LBB0_2153
	s_bcnt1_i32_b64 s1, s[14:15]
	v_mov_b32_e32 v0, 0x2000
	v_mov_b32_e32 v1, s1
	global_atomic_add v0, v1, s[12:13] offset:1024

.LBB0_2353:
	s_mov_b64 s[16:17], exec
	v_readlane_b32 s1, v239, 2
	s_lshl_b32 s1, s1, 8
	v_mbcnt_lo_u32_b32 v1, s16, 0
	s_add_u32 s12, s96, s1
	v_mbcnt_hi_u32_b32 v1, s17, v1
	s_addc_u32 s13, s97, 0
	v_cmp_eq_u32_e32 vcc, 0, v1
	s_and_saveexec_b64 s[18:19], vcc
	s_cbranch_execz .LBB0_2355
	s_bcnt1_i32_b64 s1, s[16:17]
	v_mov_b32_e32 v3, 0x1000
	v_mov_b32_e32 v4, s1
	buffer_inv sc1
	global_atomic_add v3, v3, v4, s[12:13] offset:1024 sc0

.LBB0_2368:
	s_or_b64 exec, exec, s[18:19]
	s_waitcnt vmcnt(0)
	s_waitcnt vmcnt(0)

.LBB0_2386:
	s_or_b64 exec, exec, s[16:17]
	s_mov_b64 s[16:17], exec
	v_mbcnt_lo_u32_b32 v0, s16, 0
	v_mbcnt_hi_u32_b32 v0, s17, v0
	v_cmp_eq_u32_e32 vcc, 0, v0
	s_waitcnt vmcnt(0)
	s_and_saveexec_b64 s[18:19], vcc
	s_cbranch_execz .LBB0_2388
	s_bcnt1_i32_b64 s1, s[16:17]
	v_mov_b32_e32 v0, 0x2000
	v_mov_b32_e32 v1, s1
	global_atomic_add v0, v1, s[12:13] offset:1024

.LBB0_2464:
	v_add_u32_e32 v30, s47, v34
	s_lshl_b32 s40, s46, 1
	v_ashrrev_i32_e32 v31, 31, v30
	s_and_b32 s40, s40, 30
	v_lshlrev_b64 v[30:31], 6, v[30:31]
	s_or_b32 s40, s40, s3
	v_or_b32_e32 v30, s5, v30
	v_readlane_b32 s44, v239, 51
	v_or_b32_e32 v30, s40, v30
	v_readlane_b32 s45, v239, 52
	s_mul_i32 s41, s64, 0x44
	s_add_i32 s41, s41, s63
	v_lshl_add_u64 v[108:109], v[30:31], 2, s[44:45]
	global_load_dword v107, v[108:109], off
	s_lshl_b32 s41, s41, 6
	s_lshl_b32 s40, s40, 1
	v_readlane_b32 s46, v239, 53
	v_readlane_b32 s47, v239, 54
	s_or_b32 s40, s41, s40
	s_andn2_b64 vcc, exec, s[36:37]
	s_or_b32 s40, s40, s2
	s_mov_b64 s[46:47], -1
	v_readlane_b32 s48, v239, 55
	v_readlane_b32 s49, v239, 56
	v_readlane_b32 s50, v239, 57
	v_readlane_b32 s51, v239, 58
	v_readlane_b32 s52, v239, 59
	v_readlane_b32 s53, v239, 60
	v_readlane_b32 s54, v239, 61
	v_readlane_b32 s55, v239, 62
	v_readlane_b32 s56, v239, 63
	v_readlane_b32 s57, v238, 0
	v_readlane_b32 s58, v238, 1
	v_readlane_b32 s59, v238, 2
	s_waitcnt vmcnt(0)
	ds_bpermute_b32 v187, v17, v107
	s_waitcnt lgkmcnt(1)
	s_waitcnt lgkmcnt(0)
	v_add_f32_e32 v108, v107, v187
	v_cndmask_b32_e64 v107, v108, v107, s[12:13]
	ds_bpermute_b32 v187, v25, v107
	s_waitcnt lgkmcnt(0)
	v_add_f32_e32 v108, v107, v187
	v_cndmask_b32_e64 v107, v108, v107, s[14:15]
	ds_bpermute_b32 v187, v27, v107
	s_waitcnt lgkmcnt(0)
	v_add_f32_e32 v108, v107, v187
	v_cndmask_b32_e64 v107, v108, v107, s[16:17]
	ds_bpermute_b32 v187, v36, v107
	s_waitcnt lgkmcnt(0)
	v_add_f32_e32 v108, v107, v187
	v_cndmask_b32_e64 v107, v108, v107, s[18:19]
	ds_bpermute_b32 v187, v37, v107
	s_waitcnt lgkmcnt(0)
	v_add_f32_e32 v108, v107, v187
	v_cndmask_b32_e64 v107, v108, v107, s[20:21]
	ds_bpermute_b32 v187, v38, v107
	s_waitcnt lgkmcnt(0)
	v_add_f32_e32 v108, v107, v187
	v_cndmask_b32_e64 v107, v108, v107, s[22:23]
	s_cbranch_vccnz .LBB0_2476
	v_readlane_b32 s44, v239, 51
	v_readlane_b32 s46, v239, 53
	v_readlane_b32 s47, v239, 54
	s_mov_b32 s41, 3
	s_mov_b32 s65, 60
	v_lshl_add_u64 v[30:31], v[30:31], 2, s[46:47]
	global_load_dword v30, v[30:31], off
	v_mov_b32_e32 v31, v104
	v_readlane_b32 s45, v239, 52
	v_readlane_b32 s48, v239, 55
	v_readlane_b32 s49, v239, 56
	v_readlane_b32 s50, v239, 57
	v_readlane_b32 s51, v239, 58
	v_readlane_b32 s52, v239, 59
	v_readlane_b32 s53, v239, 60
	v_readlane_b32 s54, v239, 61
	v_readlane_b32 s55, v239, 62
	v_readlane_b32 s56, v239, 63
	v_readlane_b32 s57, v238, 0
	v_readlane_b32 s58, v238, 1
	v_readlane_b32 s59, v238, 2
	s_and_b64 s[46:47], s[10:11], exec
	s_cbranch_scc0 .Lprep_lbuild_rev
	ds_read_b32 v108, v35 offset:34816
	ds_read_b32 v109, v35 offset:35076
	ds_read_b32 v110, v35 offset:35336
	ds_read_b32 v111, v35 offset:35596
	ds_read_b32 v112, v35 offset:35856
	ds_read_b32 v113, v35 offset:36116
	ds_read_b32 v114, v35 offset:36376
	s_waitcnt vmcnt(0)
	ds_read_b32 v115, v35 offset:36636
	v_readlane_b32 s66, v107, 0
	v_readlane_b32 s98, v30, 0
	v_cmp_gt_i32_e32 vcc, 0, v16
	s_nop 0
	v_sub_f32_e32 v124, s66, v107
	v_mul_f32_e32 v124, 0x3fb8aa3b, v124
	v_exp_f32_e32 v124, v124
	s_waitcnt lgkmcnt(7)
	v_mul_f32_e32 v132, s98, v108
	v_mul_f32_e32 v124, v124, v132
	v_cndmask_b32_e32 v124, 0, v124, vcc
	ds_write_b32 v104, v124 offset:0
	ds_read_b32 v116, v35 offset:36896
	v_readlane_b32 s67, v107, 1
	v_readlane_b32 s99, v30, 1
	v_cmp_gt_i32_e32 vcc, 1, v16
	s_nop 0
	v_sub_f32_e32 v125, s67, v107
	v_mul_f32_e32 v125, 0x3fb8aa3b, v125
	v_exp_f32_e32 v125, v125
	s_waitcnt lgkmcnt(8)
	v_mul_f32_e32 v133, s99, v109
	v_mul_f32_e32 v125, v125, v133
	v_cndmask_b32_e32 v125, 0, v125, vcc
	ds_write_b32 v104, v125 offset:256
	ds_read_b32 v117, v35 offset:37156
	v_readlane_b32 s68, v107, 2
	v_readlane_b32 s100, v30, 2
	v_cmp_gt_i32_e32 vcc, 2, v16
	s_nop 0
	v_sub_f32_e32 v126, s68, v107
	v_mul_f32_e32 v126, 0x3fb8aa3b, v126
	v_exp_f32_e32 v126, v126
	s_waitcnt lgkmcnt(9)
	v_mul_f32_e32 v134, s100, v110
	v_mul_f32_e32 v126, v126, v134
	v_cndmask_b32_e32 v126, 0, v126, vcc
	ds_write_b32 v104, v126 offset:512
	ds_read_b32 v118, v35 offset:37416
	v_readlane_b32 s69, v107, 3
	v_readlane_b32 s101, v30, 3
	v_cmp_gt_i32_e32 vcc, 3, v16
	s_nop 0
	v_sub_f32_e32 v127, s69, v107
	v_mul_f32_e32 v127, 0x3fb8aa3b, v127
	v_exp_f32_e32 v127, v127
	s_waitcnt lgkmcnt(10)
	v_mul_f32_e32 v135, s101, v111
	v_mul_f32_e32 v127, v127, v135
	v_cndmask_b32_e32 v127, 0, v127, vcc
	ds_write_b32 v104, v127 offset:768
	ds_read_b32 v119, v35 offset:37676
	v_readlane_b32 s66, v107, 4
	v_readlane_b32 s98, v30, 4
	v_cmp_gt_i32_e32 vcc, 4, v16
	s_nop 0
	v_sub_f32_e32 v128, s66, v107
	v_mul_f32_e32 v128, 0x3fb8aa3b, v128
	v_exp_f32_e32 v128, v128
	s_waitcnt lgkmcnt(11)
	v_mul_f32_e32 v136, s98, v112
	v_mul_f32_e32 v128, v128, v136
	v_cndmask_b32_e32 v128, 0, v128, vcc
	ds_write_b32 v104, v128 offset:1024
	ds_read_b32 v120, v35 offset:37936
	v_readlane_b32 s67, v107, 5
	v_readlane_b32 s99, v30, 5
	v_cmp_gt_i32_e32 vcc, 5, v16
	s_nop 0
	v_sub_f32_e32 v129, s67, v107
	v_mul_f32_e32 v129, 0x3fb8aa3b, v129
	v_exp_f32_e32 v129, v129
	s_waitcnt lgkmcnt(12)
	v_mul_f32_e32 v137, s99, v113
	v_mul_f32_e32 v129, v129, v137
	v_cndmask_b32_e32 v129, 0, v129, vcc
	ds_write_b32 v104, v129 offset:1280
	ds_read_b32 v121, v35 offset:38196
	v_readlane_b32 s68, v107, 6
	v_readlane_b32 s100, v30, 6
	v_cmp_gt_i32_e32 vcc, 6, v16
	s_nop 0
	v_sub_f32_e32 v130, s68, v107
	v_mul_f32_e32 v130, 0x3fb8aa3b, v130
	v_exp_f32_e32 v130, v130
	s_waitcnt lgkmcnt(13)
	v_mul_f32_e32 v138, s100, v114
	v_mul_f32_e32 v130, v130, v138
	v_cndmask_b32_e32 v130, 0, v130, vcc
	ds_write_b32 v104, v130 offset:1536
	ds_read_b32 v122, v35 offset:38456
	v_readlane_b32 s69, v107, 7
	v_readlane_b32 s101, v30, 7
	v_cmp_gt_i32_e32 vcc, 7, v16
	s_nop 0
	v_sub_f32_e32 v131, s69, v107
	v_mul_f32_e32 v131, 0x3fb8aa3b, v131
	v_exp_f32_e32 v131, v131
	s_waitcnt lgkmcnt(14)
	v_mul_f32_e32 v139, s101, v115
	v_mul_f32_e32 v131, v131, v139
	v_cndmask_b32_e32 v131, 0, v131, vcc
	ds_write_b32 v104, v131 offset:1792
	ds_read_b32 v123, v35 offset:38716
	v_readlane_b32 s66, v107, 8
	v_readlane_b32 s98, v30, 8
	v_cmp_gt_i32_e32 vcc, 8, v16
	s_nop 0
	v_sub_f32_e32 v124, s66, v107
	v_mul_f32_e32 v124, 0x3fb8aa3b, v124
	v_exp_f32_e32 v124, v124
	s_waitcnt lgkmcnt(14)
	v_mul_f32_e32 v132, s98, v116
	v_mul_f32_e32 v124, v124, v132
	v_cndmask_b32_e32 v124, 0, v124, vcc
	ds_write_b32 v104, v124 offset:2048
	ds_read_b32 v108, v35 offset:38976
	v_readlane_b32 s67, v107, 9
	v_readlane_b32 s99, v30, 9
	v_cmp_gt_i32_e32 vcc, 9, v16
	s_nop 0
	v_sub_f32_e32 v125, s67, v107
	v_mul_f32_e32 v125, 0x3fb8aa3b, v125
	v_exp_f32_e32 v125, v125
	s_waitcnt lgkmcnt(14)
	v_mul_f32_e32 v133, s99, v117
	v_mul_f32_e32 v125, v125, v133
	v_cndmask_b32_e32 v125, 0, v125, vcc
	ds_write_b32 v104, v125 offset:2304
	ds_read_b32 v109, v35 offset:39236
	v_readlane_b32 s68, v107, 10
	v_readlane_b32 s100, v30, 10
	v_cmp_gt_i32_e32 vcc, 10, v16
	s_nop 0
	v_sub_f32_e32 v126, s68, v107
	v_mul_f32_e32 v126, 0x3fb8aa3b, v126
	v_exp_f32_e32 v126, v126
	s_waitcnt lgkmcnt(14)
	v_mul_f32_e32 v134, s100, v118
	v_mul_f32_e32 v126, v126, v134
	v_cndmask_b32_e32 v126, 0, v126, vcc
	ds_write_b32 v104, v126 offset:2560
	ds_read_b32 v110, v35 offset:39496
	v_readlane_b32 s69, v107, 11
	v_readlane_b32 s101, v30, 11
	v_cmp_gt_i32_e32 vcc, 11, v16
	s_nop 0
	v_sub_f32_e32 v127, s69, v107
	v_mul_f32_e32 v127, 0x3fb8aa3b, v127
	v_exp_f32_e32 v127, v127
	s_waitcnt lgkmcnt(14)
	v_mul_f32_e32 v135, s101, v119
	v_mul_f32_e32 v127, v127, v135
	v_cndmask_b32_e32 v127, 0, v127, vcc
	ds_write_b32 v104, v127 offset:2816
	ds_read_b32 v111, v35 offset:39756
	v_readlane_b32 s66, v107, 12
	v_readlane_b32 s98, v30, 12
	v_cmp_gt_i32_e32 vcc, 12, v16
	s_nop 0
	v_sub_f32_e32 v128, s66, v107
	v_mul_f32_e32 v128, 0x3fb8aa3b, v128
	v_exp_f32_e32 v128, v128
	s_waitcnt lgkmcnt(14)
	v_mul_f32_e32 v136, s98, v120
	v_mul_f32_e32 v128, v128, v136
	v_cndmask_b32_e32 v128, 0, v128, vcc
	ds_write_b32 v104, v128 offset:3072
	ds_read_b32 v112, v35 offset:40016
	v_readlane_b32 s67, v107, 13
	v_readlane_b32 s99, v30, 13
	v_cmp_gt_i32_e32 vcc, 13, v16
	s_nop 0
	v_sub_f32_e32 v129, s67, v107
	v_mul_f32_e32 v129, 0x3fb8aa3b, v129
	v_exp_f32_e32 v129, v129
	s_waitcnt lgkmcnt(14)
	v_mul_f32_e32 v137, s99, v121
	v_mul_f32_e32 v129, v129, v137
	v_cndmask_b32_e32 v129, 0, v129, vcc
	ds_write_b32 v104, v129 offset:3328
	ds_read_b32 v113, v35 offset:40276
	v_readlane_b32 s68, v107, 14
	v_readlane_b32 s100, v30, 14
	v_cmp_gt_i32_e32 vcc, 14, v16
	s_nop 0
	v_sub_f32_e32 v130, s68, v107
	v_mul_f32_e32 v130, 0x3fb8aa3b, v130
	v_exp_f32_e32 v130, v130
	s_waitcnt lgkmcnt(14)
	v_mul_f32_e32 v138, s100, v122
	v_mul_f32_e32 v130, v130, v138
	v_cndmask_b32_e32 v130, 0, v130, vcc
	ds_write_b32 v104, v130 offset:3584
	ds_read_b32 v114, v35 offset:40536
	v_readlane_b32 s69, v107, 15
	v_readlane_b32 s101, v30, 15
	v_cmp_gt_i32_e32 vcc, 15, v16
	s_nop 0
	v_sub_f32_e32 v131, s69, v107
	v_mul_f32_e32 v131, 0x3fb8aa3b, v131
	v_exp_f32_e32 v131, v131
	s_waitcnt lgkmcnt(14)
	v_mul_f32_e32 v139, s101, v123
	v_mul_f32_e32 v131, v131, v139
	v_cndmask_b32_e32 v131, 0, v131, vcc
	ds_write_b32 v104, v131 offset:3840
	ds_read_b32 v115, v35 offset:40796
	v_readlane_b32 s66, v107, 16
	v_readlane_b32 s98, v30, 16
	v_cmp_gt_i32_e32 vcc, 16, v16
	s_nop 0
	v_sub_f32_e32 v124, s66, v107
	v_mul_f32_e32 v124, 0x3fb8aa3b, v124
	v_exp_f32_e32 v124, v124
	s_waitcnt lgkmcnt(14)
	v_mul_f32_e32 v132, s98, v108
	v_mul_f32_e32 v124, v124, v132
	v_cndmask_b32_e32 v124, 0, v124, vcc
	ds_write_b32 v104, v124 offset:4096
	ds_read_b32 v116, v35 offset:41056
	v_readlane_b32 s67, v107, 17
	v_readlane_b32 s99, v30, 17
	v_cmp_gt_i32_e32 vcc, 17, v16
	s_nop 0
	v_sub_f32_e32 v125, s67, v107
	v_mul_f32_e32 v125, 0x3fb8aa3b, v125
	v_exp_f32_e32 v125, v125
	s_waitcnt lgkmcnt(14)
	v_mul_f32_e32 v133, s99, v109
	v_mul_f32_e32 v125, v125, v133
	v_cndmask_b32_e32 v125, 0, v125, vcc
	ds_write_b32 v104, v125 offset:4352
	ds_read_b32 v117, v35 offset:41316
	v_readlane_b32 s68, v107, 18
	v_readlane_b32 s100, v30, 18
	v_cmp_gt_i32_e32 vcc, 18, v16
	s_nop 0
	v_sub_f32_e32 v126, s68, v107
	v_mul_f32_e32 v126, 0x3fb8aa3b, v126
	v_exp_f32_e32 v126, v126
	s_waitcnt lgkmcnt(14)
	v_mul_f32_e32 v134, s100, v110
	v_mul_f32_e32 v126, v126, v134
	v_cndmask_b32_e32 v126, 0, v126, vcc
	ds_write_b32 v104, v126 offset:4608
	ds_read_b32 v118, v35 offset:41576
	v_readlane_b32 s69, v107, 19
	v_readlane_b32 s101, v30, 19
	v_cmp_gt_i32_e32 vcc, 19, v16
	s_nop 0
	v_sub_f32_e32 v127, s69, v107
	v_mul_f32_e32 v127, 0x3fb8aa3b, v127
	v_exp_f32_e32 v127, v127
	s_waitcnt lgkmcnt(14)
	v_mul_f32_e32 v135, s101, v111
	v_mul_f32_e32 v127, v127, v135
	v_cndmask_b32_e32 v127, 0, v127, vcc
	ds_write_b32 v104, v127 offset:4864
	ds_read_b32 v119, v35 offset:41836
	v_readlane_b32 s66, v107, 20
	v_readlane_b32 s98, v30, 20
	v_cmp_gt_i32_e32 vcc, 20, v16
	s_nop 0
	v_sub_f32_e32 v128, s66, v107
	v_mul_f32_e32 v128, 0x3fb8aa3b, v128
	v_exp_f32_e32 v128, v128
	s_waitcnt lgkmcnt(14)
	v_mul_f32_e32 v136, s98, v112
	v_mul_f32_e32 v128, v128, v136
	v_cndmask_b32_e32 v128, 0, v128, vcc
	ds_write_b32 v104, v128 offset:5120
	ds_read_b32 v120, v35 offset:42096
	v_readlane_b32 s67, v107, 21
	v_readlane_b32 s99, v30, 21
	v_cmp_gt_i32_e32 vcc, 21, v16
	s_nop 0
	v_sub_f32_e32 v129, s67, v107
	v_mul_f32_e32 v129, 0x3fb8aa3b, v129
	v_exp_f32_e32 v129, v129
	s_waitcnt lgkmcnt(14)
	v_mul_f32_e32 v137, s99, v113
	v_mul_f32_e32 v129, v129, v137
	v_cndmask_b32_e32 v129, 0, v129, vcc
	ds_write_b32 v104, v129 offset:5376
	ds_read_b32 v121, v35 offset:42356
	v_readlane_b32 s68, v107, 22
	v_readlane_b32 s100, v30, 22
	v_cmp_gt_i32_e32 vcc, 22, v16
	s_nop 0
	v_sub_f32_e32 v130, s68, v107
	v_mul_f32_e32 v130, 0x3fb8aa3b, v130
	v_exp_f32_e32 v130, v130
	s_waitcnt lgkmcnt(14)
	v_mul_f32_e32 v138, s100, v114
	v_mul_f32_e32 v130, v130, v138
	v_cndmask_b32_e32 v130, 0, v130, vcc
	ds_write_b32 v104, v130 offset:5632
	ds_read_b32 v122, v35 offset:42616
	v_readlane_b32 s69, v107, 23
	v_readlane_b32 s101, v30, 23
	v_cmp_gt_i32_e32 vcc, 23, v16
	s_nop 0
	v_sub_f32_e32 v131, s69, v107
	v_mul_f32_e32 v131, 0x3fb8aa3b, v131
	v_exp_f32_e32 v131, v131
	s_waitcnt lgkmcnt(14)
	v_mul_f32_e32 v139, s101, v115
	v_mul_f32_e32 v131, v131, v139
	v_cndmask_b32_e32 v131, 0, v131, vcc
	ds_write_b32 v104, v131 offset:5888
	ds_read_b32 v123, v35 offset:42876
	v_readlane_b32 s66, v107, 24
	v_readlane_b32 s98, v30, 24
	v_cmp_gt_i32_e32 vcc, 24, v16
	s_nop 0
	v_sub_f32_e32 v124, s66, v107
	v_mul_f32_e32 v124, 0x3fb8aa3b, v124
	v_exp_f32_e32 v124, v124
	s_waitcnt lgkmcnt(14)
	v_mul_f32_e32 v132, s98, v116
	v_mul_f32_e32 v124, v124, v132
	v_cndmask_b32_e32 v124, 0, v124, vcc
	ds_write_b32 v104, v124 offset:6144
	ds_read_b32 v108, v35 offset:43136
	v_readlane_b32 s67, v107, 25
	v_readlane_b32 s99, v30, 25
	v_cmp_gt_i32_e32 vcc, 25, v16
	s_nop 0
	v_sub_f32_e32 v125, s67, v107
	v_mul_f32_e32 v125, 0x3fb8aa3b, v125
	v_exp_f32_e32 v125, v125
	s_waitcnt lgkmcnt(14)
	v_mul_f32_e32 v133, s99, v117
	v_mul_f32_e32 v125, v125, v133
	v_cndmask_b32_e32 v125, 0, v125, vcc
	ds_write_b32 v104, v125 offset:6400
	ds_read_b32 v109, v35 offset:43396
	v_readlane_b32 s68, v107, 26
	v_readlane_b32 s100, v30, 26
	v_cmp_gt_i32_e32 vcc, 26, v16
	s_nop 0
	v_sub_f32_e32 v126, s68, v107
	v_mul_f32_e32 v126, 0x3fb8aa3b, v126
	v_exp_f32_e32 v126, v126
	s_waitcnt lgkmcnt(14)
	v_mul_f32_e32 v134, s100, v118
	v_mul_f32_e32 v126, v126, v134
	v_cndmask_b32_e32 v126, 0, v126, vcc
	ds_write_b32 v104, v126 offset:6656
	ds_read_b32 v110, v35 offset:43656
	v_readlane_b32 s69, v107, 27
	v_readlane_b32 s101, v30, 27
	v_cmp_gt_i32_e32 vcc, 27, v16
	s_nop 0
	v_sub_f32_e32 v127, s69, v107
	v_mul_f32_e32 v127, 0x3fb8aa3b, v127
	v_exp_f32_e32 v127, v127
	s_waitcnt lgkmcnt(14)
	v_mul_f32_e32 v135, s101, v119
	v_mul_f32_e32 v127, v127, v135
	v_cndmask_b32_e32 v127, 0, v127, vcc
	ds_write_b32 v104, v127 offset:6912
	ds_read_b32 v111, v35 offset:43916
	v_readlane_b32 s66, v107, 28
	v_readlane_b32 s98, v30, 28
	v_cmp_gt_i32_e32 vcc, 28, v16
	s_nop 0
	v_sub_f32_e32 v128, s66, v107
	v_mul_f32_e32 v128, 0x3fb8aa3b, v128
	v_exp_f32_e32 v128, v128
	s_waitcnt lgkmcnt(14)
	v_mul_f32_e32 v136, s98, v120
	v_mul_f32_e32 v128, v128, v136
	v_cndmask_b32_e32 v128, 0, v128, vcc
	ds_write_b32 v104, v128 offset:7168
	ds_read_b32 v112, v35 offset:44176
	v_readlane_b32 s67, v107, 29
	v_readlane_b32 s99, v30, 29
	v_cmp_gt_i32_e32 vcc, 29, v16
	s_nop 0
	v_sub_f32_e32 v129, s67, v107
	v_mul_f32_e32 v129, 0x3fb8aa3b, v129
	v_exp_f32_e32 v129, v129
	s_waitcnt lgkmcnt(14)
	v_mul_f32_e32 v137, s99, v121
	v_mul_f32_e32 v129, v129, v137
	v_cndmask_b32_e32 v129, 0, v129, vcc
	ds_write_b32 v104, v129 offset:7424
	ds_read_b32 v113, v35 offset:44436
	v_readlane_b32 s68, v107, 30
	v_readlane_b32 s100, v30, 30
	v_cmp_gt_i32_e32 vcc, 30, v16
	s_nop 0
	v_sub_f32_e32 v130, s68, v107
	v_mul_f32_e32 v130, 0x3fb8aa3b, v130
	v_exp_f32_e32 v130, v130
	s_waitcnt lgkmcnt(14)
	v_mul_f32_e32 v138, s100, v122
	v_mul_f32_e32 v130, v130, v138
	v_cndmask_b32_e32 v130, 0, v130, vcc
	ds_write_b32 v104, v130 offset:7680
	ds_read_b32 v114, v35 offset:44696
	v_readlane_b32 s69, v107, 31
	v_readlane_b32 s101, v30, 31
	v_cmp_gt_i32_e32 vcc, 31, v16
	s_nop 0
	v_sub_f32_e32 v131, s69, v107
	v_mul_f32_e32 v131, 0x3fb8aa3b, v131
	v_exp_f32_e32 v131, v131
	s_waitcnt lgkmcnt(14)
	v_mul_f32_e32 v139, s101, v123
	v_mul_f32_e32 v131, v131, v139
	v_cndmask_b32_e32 v131, 0, v131, vcc
	ds_write_b32 v104, v131 offset:7936
	ds_read_b32 v115, v35 offset:44956
	v_readlane_b32 s66, v107, 32
	v_readlane_b32 s98, v30, 32
	v_cmp_gt_i32_e32 vcc, 32, v16
	s_nop 0
	v_sub_f32_e32 v124, s66, v107
	v_mul_f32_e32 v124, 0x3fb8aa3b, v124
	v_exp_f32_e32 v124, v124
	s_waitcnt lgkmcnt(14)
	v_mul_f32_e32 v132, s98, v108
	v_mul_f32_e32 v124, v124, v132
	v_cndmask_b32_e32 v124, 0, v124, vcc
	ds_write_b32 v104, v124 offset:8192
	ds_read_b32 v116, v35 offset:45216
	v_readlane_b32 s67, v107, 33
	v_readlane_b32 s99, v30, 33
	v_cmp_gt_i32_e32 vcc, 33, v16
	s_nop 0
	v_sub_f32_e32 v125, s67, v107
	v_mul_f32_e32 v125, 0x3fb8aa3b, v125
	v_exp_f32_e32 v125, v125
	s_waitcnt lgkmcnt(14)
	v_mul_f32_e32 v133, s99, v109
	v_mul_f32_e32 v125, v125, v133
	v_cndmask_b32_e32 v125, 0, v125, vcc
	ds_write_b32 v104, v125 offset:8448
	ds_read_b32 v117, v35 offset:45476
	v_readlane_b32 s68, v107, 34
	v_readlane_b32 s100, v30, 34
	v_cmp_gt_i32_e32 vcc, 34, v16
	s_nop 0
	v_sub_f32_e32 v126, s68, v107
	v_mul_f32_e32 v126, 0x3fb8aa3b, v126
	v_exp_f32_e32 v126, v126
	s_waitcnt lgkmcnt(14)
	v_mul_f32_e32 v134, s100, v110
	v_mul_f32_e32 v126, v126, v134
	v_cndmask_b32_e32 v126, 0, v126, vcc
	ds_write_b32 v104, v126 offset:8704
	ds_read_b32 v118, v35 offset:45736
	v_readlane_b32 s69, v107, 35
	v_readlane_b32 s101, v30, 35
	v_cmp_gt_i32_e32 vcc, 35, v16
	s_nop 0
	v_sub_f32_e32 v127, s69, v107
	v_mul_f32_e32 v127, 0x3fb8aa3b, v127
	v_exp_f32_e32 v127, v127
	s_waitcnt lgkmcnt(14)
	v_mul_f32_e32 v135, s101, v111
	v_mul_f32_e32 v127, v127, v135
	v_cndmask_b32_e32 v127, 0, v127, vcc
	ds_write_b32 v104, v127 offset:8960
	ds_read_b32 v119, v35 offset:45996
	v_readlane_b32 s66, v107, 36
	v_readlane_b32 s98, v30, 36
	v_cmp_gt_i32_e32 vcc, 36, v16
	s_nop 0
	v_sub_f32_e32 v128, s66, v107
	v_mul_f32_e32 v128, 0x3fb8aa3b, v128
	v_exp_f32_e32 v128, v128
	s_waitcnt lgkmcnt(14)
	v_mul_f32_e32 v136, s98, v112
	v_mul_f32_e32 v128, v128, v136
	v_cndmask_b32_e32 v128, 0, v128, vcc
	ds_write_b32 v104, v128 offset:9216
	ds_read_b32 v120, v35 offset:46256
	v_readlane_b32 s67, v107, 37
	v_readlane_b32 s99, v30, 37
	v_cmp_gt_i32_e32 vcc, 37, v16
	s_nop 0
	v_sub_f32_e32 v129, s67, v107
	v_mul_f32_e32 v129, 0x3fb8aa3b, v129
	v_exp_f32_e32 v129, v129
	s_waitcnt lgkmcnt(14)
	v_mul_f32_e32 v137, s99, v113
	v_mul_f32_e32 v129, v129, v137
	v_cndmask_b32_e32 v129, 0, v129, vcc
	ds_write_b32 v104, v129 offset:9472
	ds_read_b32 v121, v35 offset:46516
	v_readlane_b32 s68, v107, 38
	v_readlane_b32 s100, v30, 38
	v_cmp_gt_i32_e32 vcc, 38, v16
	s_nop 0
	v_sub_f32_e32 v130, s68, v107
	v_mul_f32_e32 v130, 0x3fb8aa3b, v130
	v_exp_f32_e32 v130, v130
	s_waitcnt lgkmcnt(14)
	v_mul_f32_e32 v138, s100, v114
	v_mul_f32_e32 v130, v130, v138
	v_cndmask_b32_e32 v130, 0, v130, vcc
	ds_write_b32 v104, v130 offset:9728
	ds_read_b32 v122, v35 offset:46776
	v_readlane_b32 s69, v107, 39
	v_readlane_b32 s101, v30, 39
	v_cmp_gt_i32_e32 vcc, 39, v16
	s_nop 0
	v_sub_f32_e32 v131, s69, v107
	v_mul_f32_e32 v131, 0x3fb8aa3b, v131
	v_exp_f32_e32 v131, v131
	s_waitcnt lgkmcnt(14)
	v_mul_f32_e32 v139, s101, v115
	v_mul_f32_e32 v131, v131, v139
	v_cndmask_b32_e32 v131, 0, v131, vcc
	ds_write_b32 v104, v131 offset:9984
	ds_read_b32 v123, v35 offset:47036
	v_readlane_b32 s66, v107, 40
	v_readlane_b32 s98, v30, 40
	v_cmp_gt_i32_e32 vcc, 40, v16
	s_nop 0
	v_sub_f32_e32 v124, s66, v107
	v_mul_f32_e32 v124, 0x3fb8aa3b, v124
	v_exp_f32_e32 v124, v124
	s_waitcnt lgkmcnt(14)
	v_mul_f32_e32 v132, s98, v116
	v_mul_f32_e32 v124, v124, v132
	v_cndmask_b32_e32 v124, 0, v124, vcc
	ds_write_b32 v104, v124 offset:10240
	ds_read_b32 v108, v35 offset:47296
	v_readlane_b32 s67, v107, 41
	v_readlane_b32 s99, v30, 41
	v_cmp_gt_i32_e32 vcc, 41, v16
	s_nop 0
	v_sub_f32_e32 v125, s67, v107
	v_mul_f32_e32 v125, 0x3fb8aa3b, v125
	v_exp_f32_e32 v125, v125
	s_waitcnt lgkmcnt(14)
	v_mul_f32_e32 v133, s99, v117
	v_mul_f32_e32 v125, v125, v133
	v_cndmask_b32_e32 v125, 0, v125, vcc
	ds_write_b32 v104, v125 offset:10496
	ds_read_b32 v109, v35 offset:47556
	v_readlane_b32 s68, v107, 42
	v_readlane_b32 s100, v30, 42
	v_cmp_gt_i32_e32 vcc, 42, v16
	s_nop 0
	v_sub_f32_e32 v126, s68, v107
	v_mul_f32_e32 v126, 0x3fb8aa3b, v126
	v_exp_f32_e32 v126, v126
	s_waitcnt lgkmcnt(14)
	v_mul_f32_e32 v134, s100, v118
	v_mul_f32_e32 v126, v126, v134
	v_cndmask_b32_e32 v126, 0, v126, vcc
	ds_write_b32 v104, v126 offset:10752
	ds_read_b32 v110, v35 offset:47816
	v_readlane_b32 s69, v107, 43
	v_readlane_b32 s101, v30, 43
	v_cmp_gt_i32_e32 vcc, 43, v16
	s_nop 0
	v_sub_f32_e32 v127, s69, v107
	v_mul_f32_e32 v127, 0x3fb8aa3b, v127
	v_exp_f32_e32 v127, v127
	s_waitcnt lgkmcnt(14)
	v_mul_f32_e32 v135, s101, v119
	v_mul_f32_e32 v127, v127, v135
	v_cndmask_b32_e32 v127, 0, v127, vcc
	ds_write_b32 v104, v127 offset:11008
	ds_read_b32 v111, v35 offset:48076
	v_readlane_b32 s66, v107, 44
	v_readlane_b32 s98, v30, 44
	v_cmp_gt_i32_e32 vcc, 44, v16
	s_nop 0
	v_sub_f32_e32 v128, s66, v107
	v_mul_f32_e32 v128, 0x3fb8aa3b, v128
	v_exp_f32_e32 v128, v128
	s_waitcnt lgkmcnt(14)
	v_mul_f32_e32 v136, s98, v120
	v_mul_f32_e32 v128, v128, v136
	v_cndmask_b32_e32 v128, 0, v128, vcc
	ds_write_b32 v104, v128 offset:11264
	ds_read_b32 v112, v35 offset:48336
	v_readlane_b32 s67, v107, 45
	v_readlane_b32 s99, v30, 45
	v_cmp_gt_i32_e32 vcc, 45, v16
	s_nop 0
	v_sub_f32_e32 v129, s67, v107
	v_mul_f32_e32 v129, 0x3fb8aa3b, v129
	v_exp_f32_e32 v129, v129
	s_waitcnt lgkmcnt(14)
	v_mul_f32_e32 v137, s99, v121
	v_mul_f32_e32 v129, v129, v137
	v_cndmask_b32_e32 v129, 0, v129, vcc
	ds_write_b32 v104, v129 offset:11520
	ds_read_b32 v113, v35 offset:48596
	v_readlane_b32 s68, v107, 46
	v_readlane_b32 s100, v30, 46
	v_cmp_gt_i32_e32 vcc, 46, v16
	s_nop 0
	v_sub_f32_e32 v130, s68, v107
	v_mul_f32_e32 v130, 0x3fb8aa3b, v130
	v_exp_f32_e32 v130, v130
	s_waitcnt lgkmcnt(14)
	v_mul_f32_e32 v138, s100, v122
	v_mul_f32_e32 v130, v130, v138
	v_cndmask_b32_e32 v130, 0, v130, vcc
	ds_write_b32 v104, v130 offset:11776
	ds_read_b32 v114, v35 offset:48856
	v_readlane_b32 s69, v107, 47
	v_readlane_b32 s101, v30, 47
	v_cmp_gt_i32_e32 vcc, 47, v16
	s_nop 0
	v_sub_f32_e32 v131, s69, v107
	v_mul_f32_e32 v131, 0x3fb8aa3b, v131
	v_exp_f32_e32 v131, v131
	s_waitcnt lgkmcnt(14)
	v_mul_f32_e32 v139, s101, v123
	v_mul_f32_e32 v131, v131, v139
	v_cndmask_b32_e32 v131, 0, v131, vcc
	ds_write_b32 v104, v131 offset:12032
	ds_read_b32 v115, v35 offset:49116
	v_readlane_b32 s66, v107, 48
	v_readlane_b32 s98, v30, 48
	v_cmp_gt_i32_e32 vcc, 48, v16
	s_nop 0
	v_sub_f32_e32 v124, s66, v107
	v_mul_f32_e32 v124, 0x3fb8aa3b, v124
	v_exp_f32_e32 v124, v124
	s_waitcnt lgkmcnt(14)
	v_mul_f32_e32 v132, s98, v108
	v_mul_f32_e32 v124, v124, v132
	v_cndmask_b32_e32 v124, 0, v124, vcc
	ds_write_b32 v104, v124 offset:12288
	ds_read_b32 v116, v35 offset:49376
	v_readlane_b32 s67, v107, 49
	v_readlane_b32 s99, v30, 49
	v_cmp_gt_i32_e32 vcc, 49, v16
	s_nop 0
	v_sub_f32_e32 v125, s67, v107
	v_mul_f32_e32 v125, 0x3fb8aa3b, v125
	v_exp_f32_e32 v125, v125
	s_waitcnt lgkmcnt(14)
	v_mul_f32_e32 v133, s99, v109
	v_mul_f32_e32 v125, v125, v133
	v_cndmask_b32_e32 v125, 0, v125, vcc
	ds_write_b32 v104, v125 offset:12544
	ds_read_b32 v117, v35 offset:49636
	v_readlane_b32 s68, v107, 50
	v_readlane_b32 s100, v30, 50
	v_cmp_gt_i32_e32 vcc, 50, v16
	s_nop 0
	v_sub_f32_e32 v126, s68, v107
	v_mul_f32_e32 v126, 0x3fb8aa3b, v126
	v_exp_f32_e32 v126, v126
	s_waitcnt lgkmcnt(14)
	v_mul_f32_e32 v134, s100, v110
	v_mul_f32_e32 v126, v126, v134
	v_cndmask_b32_e32 v126, 0, v126, vcc
	ds_write_b32 v104, v126 offset:12800
	ds_read_b32 v118, v35 offset:49896
	v_readlane_b32 s69, v107, 51
	v_readlane_b32 s101, v30, 51
	v_cmp_gt_i32_e32 vcc, 51, v16
	s_nop 0
	v_sub_f32_e32 v127, s69, v107
	v_mul_f32_e32 v127, 0x3fb8aa3b, v127
	v_exp_f32_e32 v127, v127
	s_waitcnt lgkmcnt(14)
	v_mul_f32_e32 v135, s101, v111
	v_mul_f32_e32 v127, v127, v135
	v_cndmask_b32_e32 v127, 0, v127, vcc
	ds_write_b32 v104, v127 offset:13056
	ds_read_b32 v119, v35 offset:50156
	v_readlane_b32 s66, v107, 52
	v_readlane_b32 s98, v30, 52
	v_cmp_gt_i32_e32 vcc, 52, v16
	s_nop 0
	v_sub_f32_e32 v128, s66, v107
	v_mul_f32_e32 v128, 0x3fb8aa3b, v128
	v_exp_f32_e32 v128, v128
	s_waitcnt lgkmcnt(14)
	v_mul_f32_e32 v136, s98, v112
	v_mul_f32_e32 v128, v128, v136
	v_cndmask_b32_e32 v128, 0, v128, vcc
	ds_write_b32 v104, v128 offset:13312
	ds_read_b32 v120, v35 offset:50416
	v_readlane_b32 s67, v107, 53
	v_readlane_b32 s99, v30, 53
	v_cmp_gt_i32_e32 vcc, 53, v16
	s_nop 0
	v_sub_f32_e32 v129, s67, v107
	v_mul_f32_e32 v129, 0x3fb8aa3b, v129
	v_exp_f32_e32 v129, v129
	s_waitcnt lgkmcnt(14)
	v_mul_f32_e32 v137, s99, v113
	v_mul_f32_e32 v129, v129, v137
	v_cndmask_b32_e32 v129, 0, v129, vcc
	ds_write_b32 v104, v129 offset:13568
	ds_read_b32 v121, v35 offset:50676
	v_readlane_b32 s68, v107, 54
	v_readlane_b32 s100, v30, 54
	v_cmp_gt_i32_e32 vcc, 54, v16
	s_nop 0
	v_sub_f32_e32 v130, s68, v107
	v_mul_f32_e32 v130, 0x3fb8aa3b, v130
	v_exp_f32_e32 v130, v130
	s_waitcnt lgkmcnt(14)
	v_mul_f32_e32 v138, s100, v114
	v_mul_f32_e32 v130, v130, v138
	v_cndmask_b32_e32 v130, 0, v130, vcc
	ds_write_b32 v104, v130 offset:13824
	ds_read_b32 v122, v35 offset:50936
	v_readlane_b32 s69, v107, 55
	v_readlane_b32 s101, v30, 55
	v_cmp_gt_i32_e32 vcc, 55, v16
	s_nop 0
	v_sub_f32_e32 v131, s69, v107
	v_mul_f32_e32 v131, 0x3fb8aa3b, v131
	v_exp_f32_e32 v131, v131
	s_waitcnt lgkmcnt(14)
	v_mul_f32_e32 v139, s101, v115
	v_mul_f32_e32 v131, v131, v139
	v_cndmask_b32_e32 v131, 0, v131, vcc
	ds_write_b32 v104, v131 offset:14080
	ds_read_b32 v123, v35 offset:51196
	v_readlane_b32 s66, v107, 56
	v_readlane_b32 s98, v30, 56
	v_cmp_gt_i32_e32 vcc, 56, v16
	s_nop 0
	v_sub_f32_e32 v124, s66, v107
	v_mul_f32_e32 v124, 0x3fb8aa3b, v124
	v_exp_f32_e32 v124, v124
	s_waitcnt lgkmcnt(14)
	v_mul_f32_e32 v132, s98, v116
	v_mul_f32_e32 v124, v124, v132
	v_cndmask_b32_e32 v124, 0, v124, vcc
	ds_write_b32 v104, v124 offset:14336
	v_readlane_b32 s67, v107, 57
	v_readlane_b32 s99, v30, 57
	v_cmp_gt_i32_e32 vcc, 57, v16
	s_nop 0
	v_sub_f32_e32 v125, s67, v107
	v_mul_f32_e32 v125, 0x3fb8aa3b, v125
	v_exp_f32_e32 v125, v125
	s_waitcnt lgkmcnt(13)
	v_mul_f32_e32 v133, s99, v117
	v_mul_f32_e32 v125, v125, v133
	v_cndmask_b32_e32 v125, 0, v125, vcc
	ds_write_b32 v104, v125 offset:14592
	v_readlane_b32 s68, v107, 58
	v_readlane_b32 s100, v30, 58
	v_cmp_gt_i32_e32 vcc, 58, v16
	s_nop 0
	v_sub_f32_e32 v126, s68, v107
	v_mul_f32_e32 v126, 0x3fb8aa3b, v126
	v_exp_f32_e32 v126, v126
	s_waitcnt lgkmcnt(12)
	v_mul_f32_e32 v134, s100, v118
	v_mul_f32_e32 v126, v126, v134
	v_cndmask_b32_e32 v126, 0, v126, vcc
	ds_write_b32 v104, v126 offset:14848
	v_readlane_b32 s69, v107, 59
	v_readlane_b32 s101, v30, 59
	v_cmp_gt_i32_e32 vcc, 59, v16
	s_nop 0
	v_sub_f32_e32 v127, s69, v107
	v_mul_f32_e32 v127, 0x3fb8aa3b, v127
	v_exp_f32_e32 v127, v127
	s_waitcnt lgkmcnt(11)
	v_mul_f32_e32 v135, s101, v119
	v_mul_f32_e32 v127, v127, v135
	v_cndmask_b32_e32 v127, 0, v127, vcc
	ds_write_b32 v104, v127 offset:15104
	v_readlane_b32 s66, v107, 60
	v_readlane_b32 s98, v30, 60
	v_cmp_gt_i32_e32 vcc, 60, v16
	s_nop 0
	v_sub_f32_e32 v128, s66, v107
	v_mul_f32_e32 v128, 0x3fb8aa3b, v128
	v_exp_f32_e32 v128, v128
	s_waitcnt lgkmcnt(10)
	v_mul_f32_e32 v136, s98, v120
	v_mul_f32_e32 v128, v128, v136
	v_cndmask_b32_e32 v128, 0, v128, vcc
	ds_write_b32 v104, v128 offset:15360
	v_readlane_b32 s67, v107, 61
	v_readlane_b32 s99, v30, 61
	v_cmp_gt_i32_e32 vcc, 61, v16
	s_nop 0
	v_sub_f32_e32 v129, s67, v107
	v_mul_f32_e32 v129, 0x3fb8aa3b, v129
	v_exp_f32_e32 v129, v129
	s_waitcnt lgkmcnt(9)
	v_mul_f32_e32 v137, s99, v121
	v_mul_f32_e32 v129, v129, v137
	v_cndmask_b32_e32 v129, 0, v129, vcc
	ds_write_b32 v104, v129 offset:15616
	v_readlane_b32 s68, v107, 62
	v_readlane_b32 s100, v30, 62
	v_cmp_gt_i32_e32 vcc, 62, v16
	s_nop 0
	v_sub_f32_e32 v130, s68, v107
	v_mul_f32_e32 v130, 0x3fb8aa3b, v130
	v_exp_f32_e32 v130, v130
	s_waitcnt lgkmcnt(8)
	v_mul_f32_e32 v138, s100, v122
	v_mul_f32_e32 v130, v130, v138
	v_cndmask_b32_e32 v130, 0, v130, vcc
	ds_write_b32 v104, v130 offset:15872
	v_readlane_b32 s69, v107, 63
	v_readlane_b32 s101, v30, 63
	v_cmp_gt_i32_e32 vcc, 63, v16
	s_nop 0
	v_sub_f32_e32 v131, s69, v107
	v_mul_f32_e32 v131, 0x3fb8aa3b, v131
	v_exp_f32_e32 v131, v131
	s_waitcnt lgkmcnt(7)
	v_mul_f32_e32 v139, s101, v123
	v_mul_f32_e32 v131, v131, v139
	v_cndmask_b32_e32 v131, 0, v131, vcc
	ds_write_b32 v104, v131 offset:16128
	s_branch .LBB0_2475
.Lprep_lbuild_rev:
	ds_read_b32 v108, v35 offset:51196
	ds_read_b32 v109, v35 offset:50936
	ds_read_b32 v110, v35 offset:50676
	ds_read_b32 v111, v35 offset:50416
	ds_read_b32 v112, v35 offset:50156
	ds_read_b32 v113, v35 offset:49896
	ds_read_b32 v114, v35 offset:49636
	s_waitcnt vmcnt(0)
	ds_read_b32 v115, v35 offset:49376
	v_readlane_b32 s66, v107, 0
	v_readlane_b32 s98, v30, 0
	v_cmp_gt_i32_e32 vcc, 0, v16
	s_nop 0
	v_sub_f32_e32 v124, s66, v107
	v_mul_f32_e32 v124, 0x3fb8aa3b, v124
	v_exp_f32_e32 v124, v124
	s_waitcnt lgkmcnt(7)
	v_mul_f32_e32 v132, s98, v108
	v_mul_f32_e32 v124, v124, v132
	v_cndmask_b32_e32 v124, 0, v124, vcc
	ds_write_b32 v104, v124 offset:0
	ds_read_b32 v116, v35 offset:49116
	v_readlane_b32 s67, v107, 1
	v_readlane_b32 s99, v30, 1
	v_cmp_gt_i32_e32 vcc, 1, v16
	s_nop 0
	v_sub_f32_e32 v125, s67, v107
	v_mul_f32_e32 v125, 0x3fb8aa3b, v125
	v_exp_f32_e32 v125, v125
	s_waitcnt lgkmcnt(8)
	v_mul_f32_e32 v133, s99, v109
	v_mul_f32_e32 v125, v125, v133
	v_cndmask_b32_e32 v125, 0, v125, vcc
	ds_write_b32 v104, v125 offset:256
	ds_read_b32 v117, v35 offset:48856
	v_readlane_b32 s68, v107, 2
	v_readlane_b32 s100, v30, 2
	v_cmp_gt_i32_e32 vcc, 2, v16
	s_nop 0
	v_sub_f32_e32 v126, s68, v107
	v_mul_f32_e32 v126, 0x3fb8aa3b, v126
	v_exp_f32_e32 v126, v126
	s_waitcnt lgkmcnt(9)
	v_mul_f32_e32 v134, s100, v110
	v_mul_f32_e32 v126, v126, v134
	v_cndmask_b32_e32 v126, 0, v126, vcc
	ds_write_b32 v104, v126 offset:512
	ds_read_b32 v118, v35 offset:48596
	v_readlane_b32 s69, v107, 3
	v_readlane_b32 s101, v30, 3
	v_cmp_gt_i32_e32 vcc, 3, v16
	s_nop 0
	v_sub_f32_e32 v127, s69, v107
	v_mul_f32_e32 v127, 0x3fb8aa3b, v127
	v_exp_f32_e32 v127, v127
	s_waitcnt lgkmcnt(10)
	v_mul_f32_e32 v135, s101, v111
	v_mul_f32_e32 v127, v127, v135
	v_cndmask_b32_e32 v127, 0, v127, vcc
	ds_write_b32 v104, v127 offset:768
	ds_read_b32 v119, v35 offset:48336
	v_readlane_b32 s66, v107, 4
	v_readlane_b32 s98, v30, 4
	v_cmp_gt_i32_e32 vcc, 4, v16
	s_nop 0
	v_sub_f32_e32 v128, s66, v107
	v_mul_f32_e32 v128, 0x3fb8aa3b, v128
	v_exp_f32_e32 v128, v128
	s_waitcnt lgkmcnt(11)
	v_mul_f32_e32 v136, s98, v112
	v_mul_f32_e32 v128, v128, v136
	v_cndmask_b32_e32 v128, 0, v128, vcc
	ds_write_b32 v104, v128 offset:1024
	ds_read_b32 v120, v35 offset:48076
	v_readlane_b32 s67, v107, 5
	v_readlane_b32 s99, v30, 5
	v_cmp_gt_i32_e32 vcc, 5, v16
	s_nop 0
	v_sub_f32_e32 v129, s67, v107
	v_mul_f32_e32 v129, 0x3fb8aa3b, v129
	v_exp_f32_e32 v129, v129
	s_waitcnt lgkmcnt(12)
	v_mul_f32_e32 v137, s99, v113
	v_mul_f32_e32 v129, v129, v137
	v_cndmask_b32_e32 v129, 0, v129, vcc
	ds_write_b32 v104, v129 offset:1280
	ds_read_b32 v121, v35 offset:47816
	v_readlane_b32 s68, v107, 6
	v_readlane_b32 s100, v30, 6
	v_cmp_gt_i32_e32 vcc, 6, v16
	s_nop 0
	v_sub_f32_e32 v130, s68, v107
	v_mul_f32_e32 v130, 0x3fb8aa3b, v130
	v_exp_f32_e32 v130, v130
	s_waitcnt lgkmcnt(13)
	v_mul_f32_e32 v138, s100, v114
	v_mul_f32_e32 v130, v130, v138
	v_cndmask_b32_e32 v130, 0, v130, vcc
	ds_write_b32 v104, v130 offset:1536
	ds_read_b32 v122, v35 offset:47556
	v_readlane_b32 s69, v107, 7
	v_readlane_b32 s101, v30, 7
	v_cmp_gt_i32_e32 vcc, 7, v16
	s_nop 0
	v_sub_f32_e32 v131, s69, v107
	v_mul_f32_e32 v131, 0x3fb8aa3b, v131
	v_exp_f32_e32 v131, v131
	s_waitcnt lgkmcnt(14)
	v_mul_f32_e32 v139, s101, v115
	v_mul_f32_e32 v131, v131, v139
	v_cndmask_b32_e32 v131, 0, v131, vcc
	ds_write_b32 v104, v131 offset:1792
	ds_read_b32 v123, v35 offset:47296
	v_readlane_b32 s66, v107, 8
	v_readlane_b32 s98, v30, 8
	v_cmp_gt_i32_e32 vcc, 8, v16
	s_nop 0
	v_sub_f32_e32 v124, s66, v107
	v_mul_f32_e32 v124, 0x3fb8aa3b, v124
	v_exp_f32_e32 v124, v124
	s_waitcnt lgkmcnt(14)
	v_mul_f32_e32 v132, s98, v116
	v_mul_f32_e32 v124, v124, v132
	v_cndmask_b32_e32 v124, 0, v124, vcc
	ds_write_b32 v104, v124 offset:2048
	ds_read_b32 v108, v35 offset:47036
	v_readlane_b32 s67, v107, 9
	v_readlane_b32 s99, v30, 9
	v_cmp_gt_i32_e32 vcc, 9, v16
	s_nop 0
	v_sub_f32_e32 v125, s67, v107
	v_mul_f32_e32 v125, 0x3fb8aa3b, v125
	v_exp_f32_e32 v125, v125
	s_waitcnt lgkmcnt(14)
	v_mul_f32_e32 v133, s99, v117
	v_mul_f32_e32 v125, v125, v133
	v_cndmask_b32_e32 v125, 0, v125, vcc
	ds_write_b32 v104, v125 offset:2304
	ds_read_b32 v109, v35 offset:46776
	v_readlane_b32 s68, v107, 10
	v_readlane_b32 s100, v30, 10
	v_cmp_gt_i32_e32 vcc, 10, v16
	s_nop 0
	v_sub_f32_e32 v126, s68, v107
	v_mul_f32_e32 v126, 0x3fb8aa3b, v126
	v_exp_f32_e32 v126, v126
	s_waitcnt lgkmcnt(14)
	v_mul_f32_e32 v134, s100, v118
	v_mul_f32_e32 v126, v126, v134
	v_cndmask_b32_e32 v126, 0, v126, vcc
	ds_write_b32 v104, v126 offset:2560
	ds_read_b32 v110, v35 offset:46516
	v_readlane_b32 s69, v107, 11
	v_readlane_b32 s101, v30, 11
	v_cmp_gt_i32_e32 vcc, 11, v16
	s_nop 0
	v_sub_f32_e32 v127, s69, v107
	v_mul_f32_e32 v127, 0x3fb8aa3b, v127
	v_exp_f32_e32 v127, v127
	s_waitcnt lgkmcnt(14)
	v_mul_f32_e32 v135, s101, v119
	v_mul_f32_e32 v127, v127, v135
	v_cndmask_b32_e32 v127, 0, v127, vcc
	ds_write_b32 v104, v127 offset:2816
	ds_read_b32 v111, v35 offset:46256
	v_readlane_b32 s66, v107, 12
	v_readlane_b32 s98, v30, 12
	v_cmp_gt_i32_e32 vcc, 12, v16
	s_nop 0
	v_sub_f32_e32 v128, s66, v107
	v_mul_f32_e32 v128, 0x3fb8aa3b, v128
	v_exp_f32_e32 v128, v128
	s_waitcnt lgkmcnt(14)
	v_mul_f32_e32 v136, s98, v120
	v_mul_f32_e32 v128, v128, v136
	v_cndmask_b32_e32 v128, 0, v128, vcc
	ds_write_b32 v104, v128 offset:3072
	ds_read_b32 v112, v35 offset:45996
	v_readlane_b32 s67, v107, 13
	v_readlane_b32 s99, v30, 13
	v_cmp_gt_i32_e32 vcc, 13, v16
	s_nop 0
	v_sub_f32_e32 v129, s67, v107
	v_mul_f32_e32 v129, 0x3fb8aa3b, v129
	v_exp_f32_e32 v129, v129
	s_waitcnt lgkmcnt(14)
	v_mul_f32_e32 v137, s99, v121
	v_mul_f32_e32 v129, v129, v137
	v_cndmask_b32_e32 v129, 0, v129, vcc
	ds_write_b32 v104, v129 offset:3328
	ds_read_b32 v113, v35 offset:45736
	v_readlane_b32 s68, v107, 14
	v_readlane_b32 s100, v30, 14
	v_cmp_gt_i32_e32 vcc, 14, v16
	s_nop 0
	v_sub_f32_e32 v130, s68, v107
	v_mul_f32_e32 v130, 0x3fb8aa3b, v130
	v_exp_f32_e32 v130, v130
	s_waitcnt lgkmcnt(14)
	v_mul_f32_e32 v138, s100, v122
	v_mul_f32_e32 v130, v130, v138
	v_cndmask_b32_e32 v130, 0, v130, vcc
	ds_write_b32 v104, v130 offset:3584
	ds_read_b32 v114, v35 offset:45476
	v_readlane_b32 s69, v107, 15
	v_readlane_b32 s101, v30, 15
	v_cmp_gt_i32_e32 vcc, 15, v16
	s_nop 0
	v_sub_f32_e32 v131, s69, v107
	v_mul_f32_e32 v131, 0x3fb8aa3b, v131
	v_exp_f32_e32 v131, v131
	s_waitcnt lgkmcnt(14)
	v_mul_f32_e32 v139, s101, v123
	v_mul_f32_e32 v131, v131, v139
	v_cndmask_b32_e32 v131, 0, v131, vcc
	ds_write_b32 v104, v131 offset:3840
	ds_read_b32 v115, v35 offset:45216
	v_readlane_b32 s66, v107, 16
	v_readlane_b32 s98, v30, 16
	v_cmp_gt_i32_e32 vcc, 16, v16
	s_nop 0
	v_sub_f32_e32 v124, s66, v107
	v_mul_f32_e32 v124, 0x3fb8aa3b, v124
	v_exp_f32_e32 v124, v124
	s_waitcnt lgkmcnt(14)
	v_mul_f32_e32 v132, s98, v108
	v_mul_f32_e32 v124, v124, v132
	v_cndmask_b32_e32 v124, 0, v124, vcc
	ds_write_b32 v104, v124 offset:4096
	ds_read_b32 v116, v35 offset:44956
	v_readlane_b32 s67, v107, 17
	v_readlane_b32 s99, v30, 17
	v_cmp_gt_i32_e32 vcc, 17, v16
	s_nop 0
	v_sub_f32_e32 v125, s67, v107
	v_mul_f32_e32 v125, 0x3fb8aa3b, v125
	v_exp_f32_e32 v125, v125
	s_waitcnt lgkmcnt(14)
	v_mul_f32_e32 v133, s99, v109
	v_mul_f32_e32 v125, v125, v133
	v_cndmask_b32_e32 v125, 0, v125, vcc
	ds_write_b32 v104, v125 offset:4352
	ds_read_b32 v117, v35 offset:44696
	v_readlane_b32 s68, v107, 18
	v_readlane_b32 s100, v30, 18
	v_cmp_gt_i32_e32 vcc, 18, v16
	s_nop 0
	v_sub_f32_e32 v126, s68, v107
	v_mul_f32_e32 v126, 0x3fb8aa3b, v126
	v_exp_f32_e32 v126, v126
	s_waitcnt lgkmcnt(14)
	v_mul_f32_e32 v134, s100, v110
	v_mul_f32_e32 v126, v126, v134
	v_cndmask_b32_e32 v126, 0, v126, vcc
	ds_write_b32 v104, v126 offset:4608
	ds_read_b32 v118, v35 offset:44436
	v_readlane_b32 s69, v107, 19
	v_readlane_b32 s101, v30, 19
	v_cmp_gt_i32_e32 vcc, 19, v16
	s_nop 0
	v_sub_f32_e32 v127, s69, v107
	v_mul_f32_e32 v127, 0x3fb8aa3b, v127
	v_exp_f32_e32 v127, v127
	s_waitcnt lgkmcnt(14)
	v_mul_f32_e32 v135, s101, v111
	v_mul_f32_e32 v127, v127, v135
	v_cndmask_b32_e32 v127, 0, v127, vcc
	ds_write_b32 v104, v127 offset:4864
	ds_read_b32 v119, v35 offset:44176
	v_readlane_b32 s66, v107, 20
	v_readlane_b32 s98, v30, 20
	v_cmp_gt_i32_e32 vcc, 20, v16
	s_nop 0
	v_sub_f32_e32 v128, s66, v107
	v_mul_f32_e32 v128, 0x3fb8aa3b, v128
	v_exp_f32_e32 v128, v128
	s_waitcnt lgkmcnt(14)
	v_mul_f32_e32 v136, s98, v112
	v_mul_f32_e32 v128, v128, v136
	v_cndmask_b32_e32 v128, 0, v128, vcc
	ds_write_b32 v104, v128 offset:5120
	ds_read_b32 v120, v35 offset:43916
	v_readlane_b32 s67, v107, 21
	v_readlane_b32 s99, v30, 21
	v_cmp_gt_i32_e32 vcc, 21, v16
	s_nop 0
	v_sub_f32_e32 v129, s67, v107
	v_mul_f32_e32 v129, 0x3fb8aa3b, v129
	v_exp_f32_e32 v129, v129
	s_waitcnt lgkmcnt(14)
	v_mul_f32_e32 v137, s99, v113
	v_mul_f32_e32 v129, v129, v137
	v_cndmask_b32_e32 v129, 0, v129, vcc
	ds_write_b32 v104, v129 offset:5376
	ds_read_b32 v121, v35 offset:43656
	v_readlane_b32 s68, v107, 22
	v_readlane_b32 s100, v30, 22
	v_cmp_gt_i32_e32 vcc, 22, v16
	s_nop 0
	v_sub_f32_e32 v130, s68, v107
	v_mul_f32_e32 v130, 0x3fb8aa3b, v130
	v_exp_f32_e32 v130, v130
	s_waitcnt lgkmcnt(14)
	v_mul_f32_e32 v138, s100, v114
	v_mul_f32_e32 v130, v130, v138
	v_cndmask_b32_e32 v130, 0, v130, vcc
	ds_write_b32 v104, v130 offset:5632
	ds_read_b32 v122, v35 offset:43396
	v_readlane_b32 s69, v107, 23
	v_readlane_b32 s101, v30, 23
	v_cmp_gt_i32_e32 vcc, 23, v16
	s_nop 0
	v_sub_f32_e32 v131, s69, v107
	v_mul_f32_e32 v131, 0x3fb8aa3b, v131
	v_exp_f32_e32 v131, v131
	s_waitcnt lgkmcnt(14)
	v_mul_f32_e32 v139, s101, v115
	v_mul_f32_e32 v131, v131, v139
	v_cndmask_b32_e32 v131, 0, v131, vcc
	ds_write_b32 v104, v131 offset:5888
	ds_read_b32 v123, v35 offset:43136
	v_readlane_b32 s66, v107, 24
	v_readlane_b32 s98, v30, 24
	v_cmp_gt_i32_e32 vcc, 24, v16
	s_nop 0
	v_sub_f32_e32 v124, s66, v107
	v_mul_f32_e32 v124, 0x3fb8aa3b, v124
	v_exp_f32_e32 v124, v124
	s_waitcnt lgkmcnt(14)
	v_mul_f32_e32 v132, s98, v116
	v_mul_f32_e32 v124, v124, v132
	v_cndmask_b32_e32 v124, 0, v124, vcc
	ds_write_b32 v104, v124 offset:6144
	ds_read_b32 v108, v35 offset:42876
	v_readlane_b32 s67, v107, 25
	v_readlane_b32 s99, v30, 25
	v_cmp_gt_i32_e32 vcc, 25, v16
	s_nop 0
	v_sub_f32_e32 v125, s67, v107
	v_mul_f32_e32 v125, 0x3fb8aa3b, v125
	v_exp_f32_e32 v125, v125
	s_waitcnt lgkmcnt(14)
	v_mul_f32_e32 v133, s99, v117
	v_mul_f32_e32 v125, v125, v133
	v_cndmask_b32_e32 v125, 0, v125, vcc
	ds_write_b32 v104, v125 offset:6400
	ds_read_b32 v109, v35 offset:42616
	v_readlane_b32 s68, v107, 26
	v_readlane_b32 s100, v30, 26
	v_cmp_gt_i32_e32 vcc, 26, v16
	s_nop 0
	v_sub_f32_e32 v126, s68, v107
	v_mul_f32_e32 v126, 0x3fb8aa3b, v126
	v_exp_f32_e32 v126, v126
	s_waitcnt lgkmcnt(14)
	v_mul_f32_e32 v134, s100, v118
	v_mul_f32_e32 v126, v126, v134
	v_cndmask_b32_e32 v126, 0, v126, vcc
	ds_write_b32 v104, v126 offset:6656
	ds_read_b32 v110, v35 offset:42356
	v_readlane_b32 s69, v107, 27
	v_readlane_b32 s101, v30, 27
	v_cmp_gt_i32_e32 vcc, 27, v16
	s_nop 0
	v_sub_f32_e32 v127, s69, v107
	v_mul_f32_e32 v127, 0x3fb8aa3b, v127
	v_exp_f32_e32 v127, v127
	s_waitcnt lgkmcnt(14)
	v_mul_f32_e32 v135, s101, v119
	v_mul_f32_e32 v127, v127, v135
	v_cndmask_b32_e32 v127, 0, v127, vcc
	ds_write_b32 v104, v127 offset:6912
	ds_read_b32 v111, v35 offset:42096
	v_readlane_b32 s66, v107, 28
	v_readlane_b32 s98, v30, 28
	v_cmp_gt_i32_e32 vcc, 28, v16
	s_nop 0
	v_sub_f32_e32 v128, s66, v107
	v_mul_f32_e32 v128, 0x3fb8aa3b, v128
	v_exp_f32_e32 v128, v128
	s_waitcnt lgkmcnt(14)
	v_mul_f32_e32 v136, s98, v120
	v_mul_f32_e32 v128, v128, v136
	v_cndmask_b32_e32 v128, 0, v128, vcc
	ds_write_b32 v104, v128 offset:7168
	ds_read_b32 v112, v35 offset:41836
	v_readlane_b32 s67, v107, 29
	v_readlane_b32 s99, v30, 29
	v_cmp_gt_i32_e32 vcc, 29, v16
	s_nop 0
	v_sub_f32_e32 v129, s67, v107
	v_mul_f32_e32 v129, 0x3fb8aa3b, v129
	v_exp_f32_e32 v129, v129
	s_waitcnt lgkmcnt(14)
	v_mul_f32_e32 v137, s99, v121
	v_mul_f32_e32 v129, v129, v137
	v_cndmask_b32_e32 v129, 0, v129, vcc
	ds_write_b32 v104, v129 offset:7424
	ds_read_b32 v113, v35 offset:41576
	v_readlane_b32 s68, v107, 30
	v_readlane_b32 s100, v30, 30
	v_cmp_gt_i32_e32 vcc, 30, v16
	s_nop 0
	v_sub_f32_e32 v130, s68, v107
	v_mul_f32_e32 v130, 0x3fb8aa3b, v130
	v_exp_f32_e32 v130, v130
	s_waitcnt lgkmcnt(14)
	v_mul_f32_e32 v138, s100, v122
	v_mul_f32_e32 v130, v130, v138
	v_cndmask_b32_e32 v130, 0, v130, vcc
	ds_write_b32 v104, v130 offset:7680
	ds_read_b32 v114, v35 offset:41316
	v_readlane_b32 s69, v107, 31
	v_readlane_b32 s101, v30, 31
	v_cmp_gt_i32_e32 vcc, 31, v16
	s_nop 0
	v_sub_f32_e32 v131, s69, v107
	v_mul_f32_e32 v131, 0x3fb8aa3b, v131
	v_exp_f32_e32 v131, v131
	s_waitcnt lgkmcnt(14)
	v_mul_f32_e32 v139, s101, v123
	v_mul_f32_e32 v131, v131, v139
	v_cndmask_b32_e32 v131, 0, v131, vcc
	ds_write_b32 v104, v131 offset:7936
	ds_read_b32 v115, v35 offset:41056
	v_readlane_b32 s66, v107, 32
	v_readlane_b32 s98, v30, 32
	v_cmp_gt_i32_e32 vcc, 32, v16
	s_nop 0
	v_sub_f32_e32 v124, s66, v107
	v_mul_f32_e32 v124, 0x3fb8aa3b, v124
	v_exp_f32_e32 v124, v124
	s_waitcnt lgkmcnt(14)
	v_mul_f32_e32 v132, s98, v108
	v_mul_f32_e32 v124, v124, v132
	v_cndmask_b32_e32 v124, 0, v124, vcc
	ds_write_b32 v104, v124 offset:8192
	ds_read_b32 v116, v35 offset:40796
	v_readlane_b32 s67, v107, 33
	v_readlane_b32 s99, v30, 33
	v_cmp_gt_i32_e32 vcc, 33, v16
	s_nop 0
	v_sub_f32_e32 v125, s67, v107
	v_mul_f32_e32 v125, 0x3fb8aa3b, v125
	v_exp_f32_e32 v125, v125
	s_waitcnt lgkmcnt(14)
	v_mul_f32_e32 v133, s99, v109
	v_mul_f32_e32 v125, v125, v133
	v_cndmask_b32_e32 v125, 0, v125, vcc
	ds_write_b32 v104, v125 offset:8448
	ds_read_b32 v117, v35 offset:40536
	v_readlane_b32 s68, v107, 34
	v_readlane_b32 s100, v30, 34
	v_cmp_gt_i32_e32 vcc, 34, v16
	s_nop 0
	v_sub_f32_e32 v126, s68, v107
	v_mul_f32_e32 v126, 0x3fb8aa3b, v126
	v_exp_f32_e32 v126, v126
	s_waitcnt lgkmcnt(14)
	v_mul_f32_e32 v134, s100, v110
	v_mul_f32_e32 v126, v126, v134
	v_cndmask_b32_e32 v126, 0, v126, vcc
	ds_write_b32 v104, v126 offset:8704
	ds_read_b32 v118, v35 offset:40276
	v_readlane_b32 s69, v107, 35
	v_readlane_b32 s101, v30, 35
	v_cmp_gt_i32_e32 vcc, 35, v16
	s_nop 0
	v_sub_f32_e32 v127, s69, v107
	v_mul_f32_e32 v127, 0x3fb8aa3b, v127
	v_exp_f32_e32 v127, v127
	s_waitcnt lgkmcnt(14)
	v_mul_f32_e32 v135, s101, v111
	v_mul_f32_e32 v127, v127, v135
	v_cndmask_b32_e32 v127, 0, v127, vcc
	ds_write_b32 v104, v127 offset:8960
	ds_read_b32 v119, v35 offset:40016
	v_readlane_b32 s66, v107, 36
	v_readlane_b32 s98, v30, 36
	v_cmp_gt_i32_e32 vcc, 36, v16
	s_nop 0
	v_sub_f32_e32 v128, s66, v107
	v_mul_f32_e32 v128, 0x3fb8aa3b, v128
	v_exp_f32_e32 v128, v128
	s_waitcnt lgkmcnt(14)
	v_mul_f32_e32 v136, s98, v112
	v_mul_f32_e32 v128, v128, v136
	v_cndmask_b32_e32 v128, 0, v128, vcc
	ds_write_b32 v104, v128 offset:9216
	ds_read_b32 v120, v35 offset:39756
	v_readlane_b32 s67, v107, 37
	v_readlane_b32 s99, v30, 37
	v_cmp_gt_i32_e32 vcc, 37, v16
	s_nop 0
	v_sub_f32_e32 v129, s67, v107
	v_mul_f32_e32 v129, 0x3fb8aa3b, v129
	v_exp_f32_e32 v129, v129
	s_waitcnt lgkmcnt(14)
	v_mul_f32_e32 v137, s99, v113
	v_mul_f32_e32 v129, v129, v137
	v_cndmask_b32_e32 v129, 0, v129, vcc
	ds_write_b32 v104, v129 offset:9472
	ds_read_b32 v121, v35 offset:39496
	v_readlane_b32 s68, v107, 38
	v_readlane_b32 s100, v30, 38
	v_cmp_gt_i32_e32 vcc, 38, v16
	s_nop 0
	v_sub_f32_e32 v130, s68, v107
	v_mul_f32_e32 v130, 0x3fb8aa3b, v130
	v_exp_f32_e32 v130, v130
	s_waitcnt lgkmcnt(14)
	v_mul_f32_e32 v138, s100, v114
	v_mul_f32_e32 v130, v130, v138
	v_cndmask_b32_e32 v130, 0, v130, vcc
	ds_write_b32 v104, v130 offset:9728
	ds_read_b32 v122, v35 offset:39236
	v_readlane_b32 s69, v107, 39
	v_readlane_b32 s101, v30, 39
	v_cmp_gt_i32_e32 vcc, 39, v16
	s_nop 0
	v_sub_f32_e32 v131, s69, v107
	v_mul_f32_e32 v131, 0x3fb8aa3b, v131
	v_exp_f32_e32 v131, v131
	s_waitcnt lgkmcnt(14)
	v_mul_f32_e32 v139, s101, v115
	v_mul_f32_e32 v131, v131, v139
	v_cndmask_b32_e32 v131, 0, v131, vcc
	ds_write_b32 v104, v131 offset:9984
	ds_read_b32 v123, v35 offset:38976
	v_readlane_b32 s66, v107, 40
	v_readlane_b32 s98, v30, 40
	v_cmp_gt_i32_e32 vcc, 40, v16
	s_nop 0
	v_sub_f32_e32 v124, s66, v107
	v_mul_f32_e32 v124, 0x3fb8aa3b, v124
	v_exp_f32_e32 v124, v124
	s_waitcnt lgkmcnt(14)
	v_mul_f32_e32 v132, s98, v116
	v_mul_f32_e32 v124, v124, v132
	v_cndmask_b32_e32 v124, 0, v124, vcc
	ds_write_b32 v104, v124 offset:10240
	ds_read_b32 v108, v35 offset:38716
	v_readlane_b32 s67, v107, 41
	v_readlane_b32 s99, v30, 41
	v_cmp_gt_i32_e32 vcc, 41, v16
	s_nop 0
	v_sub_f32_e32 v125, s67, v107
	v_mul_f32_e32 v125, 0x3fb8aa3b, v125
	v_exp_f32_e32 v125, v125
	s_waitcnt lgkmcnt(14)
	v_mul_f32_e32 v133, s99, v117
	v_mul_f32_e32 v125, v125, v133
	v_cndmask_b32_e32 v125, 0, v125, vcc
	ds_write_b32 v104, v125 offset:10496
	ds_read_b32 v109, v35 offset:38456
	v_readlane_b32 s68, v107, 42
	v_readlane_b32 s100, v30, 42
	v_cmp_gt_i32_e32 vcc, 42, v16
	s_nop 0
	v_sub_f32_e32 v126, s68, v107
	v_mul_f32_e32 v126, 0x3fb8aa3b, v126
	v_exp_f32_e32 v126, v126
	s_waitcnt lgkmcnt(14)
	v_mul_f32_e32 v134, s100, v118
	v_mul_f32_e32 v126, v126, v134
	v_cndmask_b32_e32 v126, 0, v126, vcc
	ds_write_b32 v104, v126 offset:10752
	ds_read_b32 v110, v35 offset:38196
	v_readlane_b32 s69, v107, 43
	v_readlane_b32 s101, v30, 43
	v_cmp_gt_i32_e32 vcc, 43, v16
	s_nop 0
	v_sub_f32_e32 v127, s69, v107
	v_mul_f32_e32 v127, 0x3fb8aa3b, v127
	v_exp_f32_e32 v127, v127
	s_waitcnt lgkmcnt(14)
	v_mul_f32_e32 v135, s101, v119
	v_mul_f32_e32 v127, v127, v135
	v_cndmask_b32_e32 v127, 0, v127, vcc
	ds_write_b32 v104, v127 offset:11008
	ds_read_b32 v111, v35 offset:37936
	v_readlane_b32 s66, v107, 44
	v_readlane_b32 s98, v30, 44
	v_cmp_gt_i32_e32 vcc, 44, v16
	s_nop 0
	v_sub_f32_e32 v128, s66, v107
	v_mul_f32_e32 v128, 0x3fb8aa3b, v128
	v_exp_f32_e32 v128, v128
	s_waitcnt lgkmcnt(14)
	v_mul_f32_e32 v136, s98, v120
	v_mul_f32_e32 v128, v128, v136
	v_cndmask_b32_e32 v128, 0, v128, vcc
	ds_write_b32 v104, v128 offset:11264
	ds_read_b32 v112, v35 offset:37676
	v_readlane_b32 s67, v107, 45
	v_readlane_b32 s99, v30, 45
	v_cmp_gt_i32_e32 vcc, 45, v16
	s_nop 0
	v_sub_f32_e32 v129, s67, v107
	v_mul_f32_e32 v129, 0x3fb8aa3b, v129
	v_exp_f32_e32 v129, v129
	s_waitcnt lgkmcnt(14)
	v_mul_f32_e32 v137, s99, v121
	v_mul_f32_e32 v129, v129, v137
	v_cndmask_b32_e32 v129, 0, v129, vcc
	ds_write_b32 v104, v129 offset:11520
	ds_read_b32 v113, v35 offset:37416
	v_readlane_b32 s68, v107, 46
	v_readlane_b32 s100, v30, 46
	v_cmp_gt_i32_e32 vcc, 46, v16
	s_nop 0
	v_sub_f32_e32 v130, s68, v107
	v_mul_f32_e32 v130, 0x3fb8aa3b, v130
	v_exp_f32_e32 v130, v130
	s_waitcnt lgkmcnt(14)
	v_mul_f32_e32 v138, s100, v122
	v_mul_f32_e32 v130, v130, v138
	v_cndmask_b32_e32 v130, 0, v130, vcc
	ds_write_b32 v104, v130 offset:11776
	ds_read_b32 v114, v35 offset:37156
	v_readlane_b32 s69, v107, 47
	v_readlane_b32 s101, v30, 47
	v_cmp_gt_i32_e32 vcc, 47, v16
	s_nop 0
	v_sub_f32_e32 v131, s69, v107
	v_mul_f32_e32 v131, 0x3fb8aa3b, v131
	v_exp_f32_e32 v131, v131
	s_waitcnt lgkmcnt(14)
	v_mul_f32_e32 v139, s101, v123
	v_mul_f32_e32 v131, v131, v139
	v_cndmask_b32_e32 v131, 0, v131, vcc
	ds_write_b32 v104, v131 offset:12032
	ds_read_b32 v115, v35 offset:36896
	v_readlane_b32 s66, v107, 48
	v_readlane_b32 s98, v30, 48
	v_cmp_gt_i32_e32 vcc, 48, v16
	s_nop 0
	v_sub_f32_e32 v124, s66, v107
	v_mul_f32_e32 v124, 0x3fb8aa3b, v124
	v_exp_f32_e32 v124, v124
	s_waitcnt lgkmcnt(14)
	v_mul_f32_e32 v132, s98, v108
	v_mul_f32_e32 v124, v124, v132
	v_cndmask_b32_e32 v124, 0, v124, vcc
	ds_write_b32 v104, v124 offset:12288
	ds_read_b32 v116, v35 offset:36636
	v_readlane_b32 s67, v107, 49
	v_readlane_b32 s99, v30, 49
	v_cmp_gt_i32_e32 vcc, 49, v16
	s_nop 0
	v_sub_f32_e32 v125, s67, v107
	v_mul_f32_e32 v125, 0x3fb8aa3b, v125
	v_exp_f32_e32 v125, v125
	s_waitcnt lgkmcnt(14)
	v_mul_f32_e32 v133, s99, v109
	v_mul_f32_e32 v125, v125, v133
	v_cndmask_b32_e32 v125, 0, v125, vcc
	ds_write_b32 v104, v125 offset:12544
	ds_read_b32 v117, v35 offset:36376
	v_readlane_b32 s68, v107, 50
	v_readlane_b32 s100, v30, 50
	v_cmp_gt_i32_e32 vcc, 50, v16
	s_nop 0
	v_sub_f32_e32 v126, s68, v107
	v_mul_f32_e32 v126, 0x3fb8aa3b, v126
	v_exp_f32_e32 v126, v126
	s_waitcnt lgkmcnt(14)
	v_mul_f32_e32 v134, s100, v110
	v_mul_f32_e32 v126, v126, v134
	v_cndmask_b32_e32 v126, 0, v126, vcc
	ds_write_b32 v104, v126 offset:12800
	ds_read_b32 v118, v35 offset:36116
	v_readlane_b32 s69, v107, 51
	v_readlane_b32 s101, v30, 51
	v_cmp_gt_i32_e32 vcc, 51, v16
	s_nop 0
	v_sub_f32_e32 v127, s69, v107
	v_mul_f32_e32 v127, 0x3fb8aa3b, v127
	v_exp_f32_e32 v127, v127
	s_waitcnt lgkmcnt(14)
	v_mul_f32_e32 v135, s101, v111
	v_mul_f32_e32 v127, v127, v135
	v_cndmask_b32_e32 v127, 0, v127, vcc
	ds_write_b32 v104, v127 offset:13056
	ds_read_b32 v119, v35 offset:35856
	v_readlane_b32 s66, v107, 52
	v_readlane_b32 s98, v30, 52
	v_cmp_gt_i32_e32 vcc, 52, v16
	s_nop 0
	v_sub_f32_e32 v128, s66, v107
	v_mul_f32_e32 v128, 0x3fb8aa3b, v128
	v_exp_f32_e32 v128, v128
	s_waitcnt lgkmcnt(14)
	v_mul_f32_e32 v136, s98, v112
	v_mul_f32_e32 v128, v128, v136
	v_cndmask_b32_e32 v128, 0, v128, vcc
	ds_write_b32 v104, v128 offset:13312
	ds_read_b32 v120, v35 offset:35596
	v_readlane_b32 s67, v107, 53
	v_readlane_b32 s99, v30, 53
	v_cmp_gt_i32_e32 vcc, 53, v16
	s_nop 0
	v_sub_f32_e32 v129, s67, v107
	v_mul_f32_e32 v129, 0x3fb8aa3b, v129
	v_exp_f32_e32 v129, v129
	s_waitcnt lgkmcnt(14)
	v_mul_f32_e32 v137, s99, v113
	v_mul_f32_e32 v129, v129, v137
	v_cndmask_b32_e32 v129, 0, v129, vcc
	ds_write_b32 v104, v129 offset:13568
	ds_read_b32 v121, v35 offset:35336
	v_readlane_b32 s68, v107, 54
	v_readlane_b32 s100, v30, 54
	v_cmp_gt_i32_e32 vcc, 54, v16
	s_nop 0
	v_sub_f32_e32 v130, s68, v107
	v_mul_f32_e32 v130, 0x3fb8aa3b, v130
	v_exp_f32_e32 v130, v130
	s_waitcnt lgkmcnt(14)
	v_mul_f32_e32 v138, s100, v114
	v_mul_f32_e32 v130, v130, v138
	v_cndmask_b32_e32 v130, 0, v130, vcc
	ds_write_b32 v104, v130 offset:13824
	ds_read_b32 v122, v35 offset:35076
	v_readlane_b32 s69, v107, 55
	v_readlane_b32 s101, v30, 55
	v_cmp_gt_i32_e32 vcc, 55, v16
	s_nop 0
	v_sub_f32_e32 v131, s69, v107
	v_mul_f32_e32 v131, 0x3fb8aa3b, v131
	v_exp_f32_e32 v131, v131
	s_waitcnt lgkmcnt(14)
	v_mul_f32_e32 v139, s101, v115
	v_mul_f32_e32 v131, v131, v139
	v_cndmask_b32_e32 v131, 0, v131, vcc
	ds_write_b32 v104, v131 offset:14080
	ds_read_b32 v123, v35 offset:34816
	v_readlane_b32 s66, v107, 56
	v_readlane_b32 s98, v30, 56
	v_cmp_gt_i32_e32 vcc, 56, v16
	s_nop 0
	v_sub_f32_e32 v124, s66, v107
	v_mul_f32_e32 v124, 0x3fb8aa3b, v124
	v_exp_f32_e32 v124, v124
	s_waitcnt lgkmcnt(14)
	v_mul_f32_e32 v132, s98, v116
	v_mul_f32_e32 v124, v124, v132
	v_cndmask_b32_e32 v124, 0, v124, vcc
	ds_write_b32 v104, v124 offset:14336
	v_readlane_b32 s67, v107, 57
	v_readlane_b32 s99, v30, 57
	v_cmp_gt_i32_e32 vcc, 57, v16
	s_nop 0
	v_sub_f32_e32 v125, s67, v107
	v_mul_f32_e32 v125, 0x3fb8aa3b, v125
	v_exp_f32_e32 v125, v125
	s_waitcnt lgkmcnt(13)
	v_mul_f32_e32 v133, s99, v117
	v_mul_f32_e32 v125, v125, v133
	v_cndmask_b32_e32 v125, 0, v125, vcc
	ds_write_b32 v104, v125 offset:14592
	v_readlane_b32 s68, v107, 58
	v_readlane_b32 s100, v30, 58
	v_cmp_gt_i32_e32 vcc, 58, v16
	s_nop 0
	v_sub_f32_e32 v126, s68, v107
	v_mul_f32_e32 v126, 0x3fb8aa3b, v126
	v_exp_f32_e32 v126, v126
	s_waitcnt lgkmcnt(12)
	v_mul_f32_e32 v134, s100, v118
	v_mul_f32_e32 v126, v126, v134
	v_cndmask_b32_e32 v126, 0, v126, vcc
	ds_write_b32 v104, v126 offset:14848
	v_readlane_b32 s69, v107, 59
	v_readlane_b32 s101, v30, 59
	v_cmp_gt_i32_e32 vcc, 59, v16
	s_nop 0
	v_sub_f32_e32 v127, s69, v107
	v_mul_f32_e32 v127, 0x3fb8aa3b, v127
	v_exp_f32_e32 v127, v127
	s_waitcnt lgkmcnt(11)
	v_mul_f32_e32 v135, s101, v119
	v_mul_f32_e32 v127, v127, v135
	v_cndmask_b32_e32 v127, 0, v127, vcc
	ds_write_b32 v104, v127 offset:15104
	v_readlane_b32 s66, v107, 60
	v_readlane_b32 s98, v30, 60
	v_cmp_gt_i32_e32 vcc, 60, v16
	s_nop 0
	v_sub_f32_e32 v128, s66, v107
	v_mul_f32_e32 v128, 0x3fb8aa3b, v128
	v_exp_f32_e32 v128, v128
	s_waitcnt lgkmcnt(10)
	v_mul_f32_e32 v136, s98, v120
	v_mul_f32_e32 v128, v128, v136
	v_cndmask_b32_e32 v128, 0, v128, vcc
	ds_write_b32 v104, v128 offset:15360
	v_readlane_b32 s67, v107, 61
	v_readlane_b32 s99, v30, 61
	v_cmp_gt_i32_e32 vcc, 61, v16
	s_nop 0
	v_sub_f32_e32 v129, s67, v107
	v_mul_f32_e32 v129, 0x3fb8aa3b, v129
	v_exp_f32_e32 v129, v129
	s_waitcnt lgkmcnt(9)
	v_mul_f32_e32 v137, s99, v121
	v_mul_f32_e32 v129, v129, v137
	v_cndmask_b32_e32 v129, 0, v129, vcc
	ds_write_b32 v104, v129 offset:15616
	v_readlane_b32 s68, v107, 62
	v_readlane_b32 s100, v30, 62
	v_cmp_gt_i32_e32 vcc, 62, v16
	s_nop 0
	v_sub_f32_e32 v130, s68, v107
	v_mul_f32_e32 v130, 0x3fb8aa3b, v130
	v_exp_f32_e32 v130, v130
	s_waitcnt lgkmcnt(8)
	v_mul_f32_e32 v138, s100, v122
	v_mul_f32_e32 v130, v130, v138
	v_cndmask_b32_e32 v130, 0, v130, vcc
	ds_write_b32 v104, v130 offset:15872
	v_readlane_b32 s69, v107, 63
	v_readlane_b32 s101, v30, 63
	v_cmp_gt_i32_e32 vcc, 63, v16
	s_nop 0
	v_sub_f32_e32 v131, s69, v107
	v_mul_f32_e32 v131, 0x3fb8aa3b, v131
	v_exp_f32_e32 v131, v131
	s_waitcnt lgkmcnt(7)
	v_mul_f32_e32 v139, s101, v123
	v_mul_f32_e32 v131, v131, v139
	v_cndmask_b32_e32 v131, 0, v131, vcc
	ds_write_b32 v104, v131 offset:16128

.LBB0_3055:
	s_mov_b64 s[10:11], exec
	v_readlane_b32 s2, v239, 2
	s_lshl_b32 s2, s2, 8
	v_mbcnt_lo_u32_b32 v1, s10, 0
	s_add_u32 s8, s96, s2
	v_mbcnt_hi_u32_b32 v1, s11, v1
	s_addc_u32 s9, s97, 0
	v_cmp_eq_u32_e32 vcc, 0, v1
	s_and_saveexec_b64 s[12:13], vcc
	s_cbranch_execz .LBB0_3057
	s_bcnt1_i32_b64 s2, s[10:11]
	v_mov_b32_e32 v3, 0x1000
	v_mov_b32_e32 v4, s2
	buffer_inv sc1
	global_atomic_add v3, v3, v4, s[8:9] offset:1024 sc0

.LBB0_3088:
	s_or_b64 exec, exec, s[10:11]
	s_mov_b64 s[10:11], exec
	v_mbcnt_lo_u32_b32 v0, s10, 0
	v_mbcnt_hi_u32_b32 v0, s11, v0
	v_cmp_eq_u32_e32 vcc, 0, v0
	s_waitcnt vmcnt(0)
	s_and_saveexec_b64 s[12:13], vcc
	s_cbranch_execz .LBB0_3090
	s_bcnt1_i32_b64 s2, s[10:11]
	v_mov_b32_e32 v0, 0x2000
	v_mov_b32_e32 v1, s2
	global_atomic_add v0, v1, s[8:9] offset:1024

.LBB0_3140:
	s_mov_b64 s[10:11], exec
	v_readlane_b32 s0, v239, 2
	s_lshl_b32 s0, s0, 8
	v_mbcnt_lo_u32_b32 v1, s10, 0
	s_add_u32 s8, s96, s0
	v_mbcnt_hi_u32_b32 v1, s11, v1
	s_addc_u32 s9, s97, 0
	v_cmp_eq_u32_e32 vcc, 0, v1
	s_and_saveexec_b64 s[12:13], vcc
	s_cbranch_execz .LBB0_3142
	s_bcnt1_i32_b64 s0, s[10:11]
	v_mov_b32_e32 v3, 0x1000
	v_mov_b32_e32 v4, s0
	buffer_inv sc1
	global_atomic_add v3, v3, v4, s[8:9] offset:1024 sc0

.LBB0_3173:
	s_or_b64 exec, exec, s[10:11]
	s_mov_b64 s[10:11], exec
	v_mbcnt_lo_u32_b32 v0, s10, 0
	v_mbcnt_hi_u32_b32 v0, s11, v0
	v_cmp_eq_u32_e32 vcc, 0, v0
	s_waitcnt vmcnt(0)
	s_and_saveexec_b64 s[12:13], vcc
	s_cbranch_execz .LBB0_3175
	s_bcnt1_i32_b64 s0, s[10:11]
	v_mov_b32_e32 v0, 0x2000
	v_mov_b32_e32 v1, s0
	global_atomic_add v0, v1, s[8:9] offset:1024

.LBB0_3400:
	s_mov_b64 s[8:9], exec
	v_readlane_b32 s0, v239, 2
	s_lshl_b32 s0, s0, 8
	v_mbcnt_lo_u32_b32 v1, s8, 0
	s_add_u32 s6, s96, s0
	v_mbcnt_hi_u32_b32 v1, s9, v1
	s_addc_u32 s7, s97, 0
	v_cmp_eq_u32_e32 vcc, 0, v1
	s_and_saveexec_b64 s[10:11], vcc
	s_cbranch_execz .LBB0_3402
	s_bcnt1_i32_b64 s0, s[8:9]
	v_mov_b32_e32 v3, 0x1000
	v_mov_b32_e32 v4, s0
	buffer_inv sc1
	global_atomic_add v3, v3, v4, s[6:7] offset:1024 sc0

.LBB0_3433:
	s_or_b64 exec, exec, s[8:9]
	s_mov_b64 s[8:9], exec
	v_mbcnt_lo_u32_b32 v0, s8, 0
	v_mbcnt_hi_u32_b32 v0, s9, v0
	v_cmp_eq_u32_e32 vcc, 0, v0
	s_waitcnt vmcnt(0)
	s_and_saveexec_b64 s[10:11], vcc
	s_cbranch_execz .LBB0_3435
	s_bcnt1_i32_b64 s0, s[8:9]
	v_mov_b32_e32 v0, 0x2000
	v_mov_b32_e32 v1, s0
	global_atomic_add v0, v1, s[6:7] offset:1024

.LBB0_3563:
	s_mov_b64 s[4:5], exec
	v_readlane_b32 s2, v239, 2
	s_lshl_b32 s2, s2, 8
	v_mbcnt_lo_u32_b32 v1, s4, 0
	s_add_u32 s2, s96, s2
	v_mbcnt_hi_u32_b32 v1, s5, v1
	s_addc_u32 s3, s97, 0
	v_cmp_eq_u32_e32 vcc, 0, v1
	s_and_saveexec_b64 s[6:7], vcc
	s_cbranch_execz .LBB0_3565
	s_bcnt1_i32_b64 s4, s[4:5]
	v_mov_b32_e32 v3, 0x1000
	v_mov_b32_e32 v4, s4
	buffer_inv sc1
	global_atomic_add v3, v3, v4, s[2:3] offset:1024 sc0

.LBB0_3578:
	s_or_b64 exec, exec, s[6:7]
	s_waitcnt vmcnt(0)
	s_waitcnt vmcnt(0)

.LBB0_3596:
	s_or_b64 exec, exec, s[4:5]
	s_mov_b64 s[4:5], exec
	v_mbcnt_lo_u32_b32 v0, s4, 0
	v_mbcnt_hi_u32_b32 v0, s5, v0
	v_cmp_eq_u32_e32 vcc, 0, v0
	s_waitcnt vmcnt(0)
	s_and_saveexec_b64 s[6:7], vcc
	s_cbranch_execz .LBB0_3598
	s_bcnt1_i32_b64 s4, s[4:5]
	v_mov_b32_e32 v0, 0x2000
	v_mov_b32_e32 v1, s4
	global_atomic_add v0, v1, s[2:3] offset:1024

	.amdhsa_kernel _ZN12_GLOBAL__N_13fwdENS_6ParamsE
		.amdhsa_group_segment_fixed_size 0
		.amdhsa_private_segment_fixed_size 0
		.amdhsa_kernarg_size 768
		.amdhsa_user_sgpr_count 2
		.amdhsa_user_sgpr_dispatch_ptr 0
		.amdhsa_user_sgpr_queue_ptr 0
		.amdhsa_user_sgpr_kernarg_segment_ptr 1
		.amdhsa_user_sgpr_dispatch_id 0
		.amdhsa_user_sgpr_kernarg_preload_length 0
		.amdhsa_user_sgpr_kernarg_preload_offset 0
		.amdhsa_user_sgpr_private_segment_size 0
		.amdhsa_uses_dynamic_stack 0
		.amdhsa_enable_private_segment 0
		.amdhsa_system_sgpr_workgroup_id_x 1
		.amdhsa_system_sgpr_workgroup_id_y 0
		.amdhsa_system_sgpr_workgroup_id_z 0
		.amdhsa_system_sgpr_workgroup_info 0
		.amdhsa_system_vgpr_workitem_id 0
		.amdhsa_next_free_vgpr 241
		.amdhsa_next_free_sgpr 102
		.amdhsa_accum_offset 244
		.amdhsa_reserve_vcc 1
		.amdhsa_float_round_mode_32 0
		.amdhsa_float_round_mode_16_64 0
		.amdhsa_float_denorm_mode_32 3
		.amdhsa_float_denorm_mode_16_64 3
		.amdhsa_dx10_clamp 1
		.amdhsa_ieee_mode 1
		.amdhsa_fp16_overflow 0
		.amdhsa_tg_split 0
		.amdhsa_exception_fp_ieee_invalid_op 0
		.amdhsa_exception_fp_denorm_src 0
		.amdhsa_exception_fp_ieee_div_zero 0
		.amdhsa_exception_fp_ieee_overflow 0
		.amdhsa_exception_fp_ieee_underflow 0
		.amdhsa_exception_fp_ieee_inexact 0
		.amdhsa_exception_int_div_zero 0
	.end_amdhsa_kernel

amdhsa.kernels:
  - .agpr_count:     0
    .args:
      - .offset:         0
        .size:           512
        .value_kind:     by_value
      - .offset:         512
        .size:           4
        .value_kind:     hidden_block_count_x
      - .offset:         516
        .size:           4
        .value_kind:     hidden_block_count_y
      - .offset:         520
        .size:           4
        .value_kind:     hidden_block_count_z
      - .offset:         524
        .size:           2
        .value_kind:     hidden_group_size_x
      - .offset:         526
        .size:           2
        .value_kind:     hidden_group_size_y
      - .offset:         528
        .size:           2
        .value_kind:     hidden_group_size_z
      - .offset:         530
        .size:           2
        .value_kind:     hidden_remainder_x
      - .offset:         532
        .size:           2
        .value_kind:     hidden_remainder_y
      - .offset:         534
        .size:           2
        .value_kind:     hidden_remainder_z
      - .offset:         552
        .size:           8
        .value_kind:     hidden_global_offset_x
      - .offset:         560
        .size:           8
        .value_kind:     hidden_global_offset_y
      - .offset:         568
        .size:           8
        .value_kind:     hidden_global_offset_z
      - .offset:         576
        .size:           2
        .value_kind:     hidden_grid_dims
      - .offset:         632
        .size:           4
        .value_kind:     hidden_dynamic_lds_size
    .group_segment_fixed_size: 0
    .kernarg_segment_align: 8
    .kernarg_segment_size: 768
    .language:       OpenCL C
    .language_version:
      - 2
      - 0
    .max_flat_workgroup_size: 512
    .name:           _ZN12_GLOBAL__N_13fwdENS_6ParamsE
    .private_segment_fixed_size: 0
    .sgpr_count:     108
    .sgpr_spill_count: 178
    .symbol:         _ZN12_GLOBAL__N_13fwdENS_6ParamsE.kd
    .uniform_work_group_size: 1
    .uses_dynamic_stack: false
    .vgpr_count:     241
    .vgpr_spill_count: 0
    .wavefront_size: 64
